# scan inner loop: output dot of previous step software-pipelined into the next step's reduction (rest as v26)
# baseline (speedup 1.0000x reference)
.LBB0_985:
	s_and_saveexec_b64 s[24:25], s[16:17]
	s_cbranch_execz .LBB0_988
	ds_read_b128 v[30:33], v161 offset:8192
	ds_read_b128 v[34:37], v161 offset:16384
	ds_read_b128 v[46:49], v161 offset:24576
	ds_read_b64 v[80:81], v82 offset:40960
	ds_read_b128 v[38:41], v161
	ds_read_b128 v[42:45], v161 offset:32768
	s_waitcnt lgkmcnt(0)
	v_pk_mul_f32 v[106:107], v[72:73], v[30:31]
	v_pk_mul_f32 v[108:109], v[76:77], v[30:31]
	v_pk_fma_f32 v[106:107], v[74:75], v[32:33], v[106:107]
	v_pk_fma_f32 v[108:109], v[78:79], v[32:33], v[108:109]
	v_add_f32_e32 v110, v106, v107
	v_add_f32_e32 v112, v108, v109
	s_nop 0
	v_add_f32_dpp v110, v110, v110 quad_perm:[1,0,3,2] row_mask:0xf bank_mask:0xf bound_ctrl:1
	v_add_f32_dpp v112, v112, v112 quad_perm:[1,0,3,2] row_mask:0xf bank_mask:0xf bound_ctrl:1
	ds_read_b128 v[84:87], v161 offset:8448
	ds_read_b128 v[88:91], v161 offset:16640
	v_add_f32_dpp v110, v110, v110 quad_perm:[2,3,0,1] row_mask:0xf bank_mask:0xf bound_ctrl:1
	v_add_f32_dpp v112, v112, v112 quad_perm:[2,3,0,1] row_mask:0xf bank_mask:0xf bound_ctrl:1
	ds_read_b128 v[100:103], v161 offset:24832
	ds_read_b64 v[104:105], v82 offset:41216
	v_add_f32_dpp v110, v110, v110 row_half_mirror row_mask:0xf bank_mask:0xf bound_ctrl:1
	v_add_f32_dpp v112, v112, v112 row_half_mirror row_mask:0xf bank_mask:0xf bound_ctrl:1
	ds_read_b128 v[92:95], v161 offset:256
	v_add_f32_dpp v110, v110, v110 row_ror:8 row_mask:0xf bank_mask:0xf bound_ctrl:1
	v_add_f32_dpp v112, v112, v112 row_ror:8 row_mask:0xf bank_mask:0xf bound_ctrl:1
	ds_read_b128 v[96:99], v161 offset:33024
	v_pk_mul_f32 v[114:115], v[34:35], v[110:111] op_sel_hi:[1,0]
	v_pk_mul_f32 v[116:117], v[34:35], v[112:113] op_sel_hi:[1,0]
	v_pk_mul_f32 v[118:119], v[36:37], v[110:111] op_sel_hi:[1,0]
	v_pk_mul_f32 v[120:121], v[36:37], v[112:113] op_sel_hi:[1,0]
	v_pk_fma_f32 v[114:115], v[46:47], v[80:81], v[114:115] op_sel_hi:[1,0,1]
	v_pk_fma_f32 v[116:117], v[46:47], v[80:81], v[116:117] op_sel:[0,1,0]
	v_pk_fma_f32 v[118:119], v[48:49], v[80:81], v[118:119] op_sel_hi:[1,0,1]
	v_pk_fma_f32 v[120:121], v[48:49], v[80:81], v[120:121] op_sel:[0,1,0]
	v_pk_fma_f32 v[72:73], v[72:73], v[38:39], v[114:115]
	v_pk_fma_f32 v[76:77], v[76:77], v[38:39], v[116:117]
	v_pk_fma_f32 v[74:75], v[74:75], v[40:41], v[118:119]
	v_pk_fma_f32 v[78:79], v[78:79], v[40:41], v[120:121]
	s_waitcnt lgkmcnt(0)
	v_pk_mul_f32 v[106:107], v[72:73], v[84:85]
	v_pk_mul_f32 v[108:109], v[76:77], v[84:85]
	v_pk_mul_f32 v[122:123], v[72:73], v[42:43]
	v_pk_mul_f32 v[124:125], v[76:77], v[42:43]
	v_pk_fma_f32 v[106:107], v[74:75], v[86:87], v[106:107]
	v_pk_fma_f32 v[108:109], v[78:79], v[86:87], v[108:109]
	v_pk_fma_f32 v[122:123], v[74:75], v[44:45], v[122:123]
	v_pk_fma_f32 v[124:125], v[78:79], v[44:45], v[124:125]
	v_add_f32_e32 v110, v106, v107
	v_add_f32_e32 v112, v108, v109
	v_add_f32_e32 v126, v122, v123
	v_add_f32_e32 v127, v124, v125
	v_add_f32_dpp v110, v110, v110 quad_perm:[1,0,3,2] row_mask:0xf bank_mask:0xf bound_ctrl:1
	v_add_f32_dpp v112, v112, v112 quad_perm:[1,0,3,2] row_mask:0xf bank_mask:0xf bound_ctrl:1
	ds_write_b64 v187, v[126:127]
	ds_read_b128 v[30:33], v161 offset:8704
	v_add_f32_dpp v110, v110, v110 quad_perm:[2,3,0,1] row_mask:0xf bank_mask:0xf bound_ctrl:1
	v_add_f32_dpp v112, v112, v112 quad_perm:[2,3,0,1] row_mask:0xf bank_mask:0xf bound_ctrl:1
	ds_read_b128 v[34:37], v161 offset:16896
	ds_read_b128 v[46:49], v161 offset:25088
	v_add_f32_dpp v110, v110, v110 row_half_mirror row_mask:0xf bank_mask:0xf bound_ctrl:1
	v_add_f32_dpp v112, v112, v112 row_half_mirror row_mask:0xf bank_mask:0xf bound_ctrl:1
	ds_read_b64 v[80:81], v82 offset:41472
	ds_read_b128 v[38:41], v161 offset:512
	v_add_f32_dpp v110, v110, v110 row_ror:8 row_mask:0xf bank_mask:0xf bound_ctrl:1
	v_add_f32_dpp v112, v112, v112 row_ror:8 row_mask:0xf bank_mask:0xf bound_ctrl:1
	ds_read_b128 v[42:45], v161 offset:33280
	v_pk_mul_f32 v[114:115], v[88:89], v[110:111] op_sel_hi:[1,0]
	v_pk_mul_f32 v[116:117], v[88:89], v[112:113] op_sel_hi:[1,0]
	v_pk_mul_f32 v[118:119], v[90:91], v[110:111] op_sel_hi:[1,0]
	v_pk_mul_f32 v[120:121], v[90:91], v[112:113] op_sel_hi:[1,0]
	v_pk_fma_f32 v[114:115], v[100:101], v[104:105], v[114:115] op_sel_hi:[1,0,1]
	v_pk_fma_f32 v[116:117], v[100:101], v[104:105], v[116:117] op_sel:[0,1,0]
	v_pk_fma_f32 v[118:119], v[102:103], v[104:105], v[118:119] op_sel_hi:[1,0,1]
	v_pk_fma_f32 v[120:121], v[102:103], v[104:105], v[120:121] op_sel:[0,1,0]
	v_pk_fma_f32 v[72:73], v[72:73], v[92:93], v[114:115]
	v_pk_fma_f32 v[76:77], v[76:77], v[92:93], v[116:117]
	v_pk_fma_f32 v[74:75], v[74:75], v[94:95], v[118:119]
	v_pk_fma_f32 v[78:79], v[78:79], v[94:95], v[120:121]
	s_waitcnt lgkmcnt(0)
	v_pk_mul_f32 v[106:107], v[72:73], v[30:31]
	v_pk_mul_f32 v[108:109], v[76:77], v[30:31]
	v_pk_mul_f32 v[122:123], v[72:73], v[96:97]
	v_pk_mul_f32 v[124:125], v[76:77], v[96:97]
	v_pk_fma_f32 v[106:107], v[74:75], v[32:33], v[106:107]
	v_pk_fma_f32 v[108:109], v[78:79], v[32:33], v[108:109]
	v_pk_fma_f32 v[122:123], v[74:75], v[98:99], v[122:123]
	v_pk_fma_f32 v[124:125], v[78:79], v[98:99], v[124:125]
	v_add_f32_e32 v110, v106, v107
	v_add_f32_e32 v112, v108, v109
	v_add_f32_e32 v126, v122, v123
	v_add_f32_e32 v127, v124, v125
	v_add_f32_dpp v110, v110, v110 quad_perm:[1,0,3,2] row_mask:0xf bank_mask:0xf bound_ctrl:1
	v_add_f32_dpp v112, v112, v112 quad_perm:[1,0,3,2] row_mask:0xf bank_mask:0xf bound_ctrl:1
	ds_write_b64 v187, v[126:127] offset:2048
	ds_read_b128 v[84:87], v161 offset:8960
	v_add_f32_dpp v110, v110, v110 quad_perm:[2,3,0,1] row_mask:0xf bank_mask:0xf bound_ctrl:1
	v_add_f32_dpp v112, v112, v112 quad_perm:[2,3,0,1] row_mask:0xf bank_mask:0xf bound_ctrl:1
	ds_read_b128 v[88:91], v161 offset:17152
	ds_read_b128 v[100:103], v161 offset:25344
	v_add_f32_dpp v110, v110, v110 row_half_mirror row_mask:0xf bank_mask:0xf bound_ctrl:1
	v_add_f32_dpp v112, v112, v112 row_half_mirror row_mask:0xf bank_mask:0xf bound_ctrl:1
	ds_read_b64 v[104:105], v82 offset:41728
	ds_read_b128 v[92:95], v161 offset:768
	v_add_f32_dpp v110, v110, v110 row_ror:8 row_mask:0xf bank_mask:0xf bound_ctrl:1
	v_add_f32_dpp v112, v112, v112 row_ror:8 row_mask:0xf bank_mask:0xf bound_ctrl:1
	ds_read_b128 v[96:99], v161 offset:33536
	v_pk_mul_f32 v[114:115], v[34:35], v[110:111] op_sel_hi:[1,0]
	v_pk_mul_f32 v[116:117], v[34:35], v[112:113] op_sel_hi:[1,0]
	v_pk_mul_f32 v[118:119], v[36:37], v[110:111] op_sel_hi:[1,0]
	v_pk_mul_f32 v[120:121], v[36:37], v[112:113] op_sel_hi:[1,0]
	v_pk_fma_f32 v[114:115], v[46:47], v[80:81], v[114:115] op_sel_hi:[1,0,1]
	v_pk_fma_f32 v[116:117], v[46:47], v[80:81], v[116:117] op_sel:[0,1,0]
	v_pk_fma_f32 v[118:119], v[48:49], v[80:81], v[118:119] op_sel_hi:[1,0,1]
	v_pk_fma_f32 v[120:121], v[48:49], v[80:81], v[120:121] op_sel:[0,1,0]
	v_pk_fma_f32 v[72:73], v[72:73], v[38:39], v[114:115]
	v_pk_fma_f32 v[76:77], v[76:77], v[38:39], v[116:117]
	v_pk_fma_f32 v[74:75], v[74:75], v[40:41], v[118:119]
	v_pk_fma_f32 v[78:79], v[78:79], v[40:41], v[120:121]
	s_waitcnt lgkmcnt(0)
	v_pk_mul_f32 v[106:107], v[72:73], v[84:85]
	v_pk_mul_f32 v[108:109], v[76:77], v[84:85]
	v_pk_mul_f32 v[122:123], v[72:73], v[42:43]
	v_pk_mul_f32 v[124:125], v[76:77], v[42:43]
	v_pk_fma_f32 v[106:107], v[74:75], v[86:87], v[106:107]
	v_pk_fma_f32 v[108:109], v[78:79], v[86:87], v[108:109]
	v_pk_fma_f32 v[122:123], v[74:75], v[44:45], v[122:123]
	v_pk_fma_f32 v[124:125], v[78:79], v[44:45], v[124:125]
	v_add_f32_e32 v110, v106, v107
	v_add_f32_e32 v112, v108, v109
	v_add_f32_e32 v126, v122, v123
	v_add_f32_e32 v127, v124, v125
	v_add_f32_dpp v110, v110, v110 quad_perm:[1,0,3,2] row_mask:0xf bank_mask:0xf bound_ctrl:1
	v_add_f32_dpp v112, v112, v112 quad_perm:[1,0,3,2] row_mask:0xf bank_mask:0xf bound_ctrl:1
	ds_write_b64 v187, v[126:127] offset:4096
	ds_read_b128 v[30:33], v161 offset:9216
	v_add_f32_dpp v110, v110, v110 quad_perm:[2,3,0,1] row_mask:0xf bank_mask:0xf bound_ctrl:1
	v_add_f32_dpp v112, v112, v112 quad_perm:[2,3,0,1] row_mask:0xf bank_mask:0xf bound_ctrl:1
	ds_read_b128 v[34:37], v161 offset:17408
	ds_read_b128 v[46:49], v161 offset:25600
	v_add_f32_dpp v110, v110, v110 row_half_mirror row_mask:0xf bank_mask:0xf bound_ctrl:1
	v_add_f32_dpp v112, v112, v112 row_half_mirror row_mask:0xf bank_mask:0xf bound_ctrl:1
	ds_read_b64 v[80:81], v82 offset:41984
	ds_read_b128 v[38:41], v161 offset:1024
	v_add_f32_dpp v110, v110, v110 row_ror:8 row_mask:0xf bank_mask:0xf bound_ctrl:1
	v_add_f32_dpp v112, v112, v112 row_ror:8 row_mask:0xf bank_mask:0xf bound_ctrl:1
	ds_read_b128 v[42:45], v161 offset:33792
	v_pk_mul_f32 v[114:115], v[88:89], v[110:111] op_sel_hi:[1,0]
	v_pk_mul_f32 v[116:117], v[88:89], v[112:113] op_sel_hi:[1,0]
	v_pk_mul_f32 v[118:119], v[90:91], v[110:111] op_sel_hi:[1,0]
	v_pk_mul_f32 v[120:121], v[90:91], v[112:113] op_sel_hi:[1,0]
	v_pk_fma_f32 v[114:115], v[100:101], v[104:105], v[114:115] op_sel_hi:[1,0,1]
	v_pk_fma_f32 v[116:117], v[100:101], v[104:105], v[116:117] op_sel:[0,1,0]
	v_pk_fma_f32 v[118:119], v[102:103], v[104:105], v[118:119] op_sel_hi:[1,0,1]
	v_pk_fma_f32 v[120:121], v[102:103], v[104:105], v[120:121] op_sel:[0,1,0]
	v_pk_fma_f32 v[72:73], v[72:73], v[92:93], v[114:115]
	v_pk_fma_f32 v[76:77], v[76:77], v[92:93], v[116:117]
	v_pk_fma_f32 v[74:75], v[74:75], v[94:95], v[118:119]
	v_pk_fma_f32 v[78:79], v[78:79], v[94:95], v[120:121]
	s_waitcnt lgkmcnt(0)
	v_pk_mul_f32 v[106:107], v[72:73], v[30:31]
	v_pk_mul_f32 v[108:109], v[76:77], v[30:31]
	v_pk_mul_f32 v[122:123], v[72:73], v[96:97]
	v_pk_mul_f32 v[124:125], v[76:77], v[96:97]
	v_pk_fma_f32 v[106:107], v[74:75], v[32:33], v[106:107]
	v_pk_fma_f32 v[108:109], v[78:79], v[32:33], v[108:109]
	v_pk_fma_f32 v[122:123], v[74:75], v[98:99], v[122:123]
	v_pk_fma_f32 v[124:125], v[78:79], v[98:99], v[124:125]
	v_add_f32_e32 v110, v106, v107
	v_add_f32_e32 v112, v108, v109
	v_add_f32_e32 v126, v122, v123
	v_add_f32_e32 v127, v124, v125
	v_add_f32_dpp v110, v110, v110 quad_perm:[1,0,3,2] row_mask:0xf bank_mask:0xf bound_ctrl:1
	v_add_f32_dpp v112, v112, v112 quad_perm:[1,0,3,2] row_mask:0xf bank_mask:0xf bound_ctrl:1
	ds_write_b64 v187, v[126:127] offset:6144
	ds_read_b128 v[84:87], v161 offset:9472
	v_add_f32_dpp v110, v110, v110 quad_perm:[2,3,0,1] row_mask:0xf bank_mask:0xf bound_ctrl:1
	v_add_f32_dpp v112, v112, v112 quad_perm:[2,3,0,1] row_mask:0xf bank_mask:0xf bound_ctrl:1
	ds_read_b128 v[88:91], v161 offset:17664
	ds_read_b128 v[100:103], v161 offset:25856
	v_add_f32_dpp v110, v110, v110 row_half_mirror row_mask:0xf bank_mask:0xf bound_ctrl:1
	v_add_f32_dpp v112, v112, v112 row_half_mirror row_mask:0xf bank_mask:0xf bound_ctrl:1
	ds_read_b64 v[104:105], v82 offset:42240
	ds_read_b128 v[92:95], v161 offset:1280
	v_add_f32_dpp v110, v110, v110 row_ror:8 row_mask:0xf bank_mask:0xf bound_ctrl:1
	v_add_f32_dpp v112, v112, v112 row_ror:8 row_mask:0xf bank_mask:0xf bound_ctrl:1
	ds_read_b128 v[96:99], v161 offset:34048
	v_pk_mul_f32 v[114:115], v[34:35], v[110:111] op_sel_hi:[1,0]
	v_pk_mul_f32 v[116:117], v[34:35], v[112:113] op_sel_hi:[1,0]
	v_pk_mul_f32 v[118:119], v[36:37], v[110:111] op_sel_hi:[1,0]
	v_pk_mul_f32 v[120:121], v[36:37], v[112:113] op_sel_hi:[1,0]
	v_pk_fma_f32 v[114:115], v[46:47], v[80:81], v[114:115] op_sel_hi:[1,0,1]
	v_pk_fma_f32 v[116:117], v[46:47], v[80:81], v[116:117] op_sel:[0,1,0]
	v_pk_fma_f32 v[118:119], v[48:49], v[80:81], v[118:119] op_sel_hi:[1,0,1]
	v_pk_fma_f32 v[120:121], v[48:49], v[80:81], v[120:121] op_sel:[0,1,0]
	v_pk_fma_f32 v[72:73], v[72:73], v[38:39], v[114:115]
	v_pk_fma_f32 v[76:77], v[76:77], v[38:39], v[116:117]
	v_pk_fma_f32 v[74:75], v[74:75], v[40:41], v[118:119]
	v_pk_fma_f32 v[78:79], v[78:79], v[40:41], v[120:121]
	s_waitcnt lgkmcnt(0)
	v_pk_mul_f32 v[106:107], v[72:73], v[84:85]
	v_pk_mul_f32 v[108:109], v[76:77], v[84:85]
	v_pk_mul_f32 v[122:123], v[72:73], v[42:43]
	v_pk_mul_f32 v[124:125], v[76:77], v[42:43]
	v_pk_fma_f32 v[106:107], v[74:75], v[86:87], v[106:107]
	v_pk_fma_f32 v[108:109], v[78:79], v[86:87], v[108:109]
	v_pk_fma_f32 v[122:123], v[74:75], v[44:45], v[122:123]
	v_pk_fma_f32 v[124:125], v[78:79], v[44:45], v[124:125]
	v_add_f32_e32 v110, v106, v107
	v_add_f32_e32 v112, v108, v109
	v_add_f32_e32 v126, v122, v123
	v_add_f32_e32 v127, v124, v125
	v_add_f32_dpp v110, v110, v110 quad_perm:[1,0,3,2] row_mask:0xf bank_mask:0xf bound_ctrl:1
	v_add_f32_dpp v112, v112, v112 quad_perm:[1,0,3,2] row_mask:0xf bank_mask:0xf bound_ctrl:1
	ds_write_b64 v187, v[126:127] offset:8192
	ds_read_b128 v[30:33], v161 offset:9728
	v_add_f32_dpp v110, v110, v110 quad_perm:[2,3,0,1] row_mask:0xf bank_mask:0xf bound_ctrl:1
	v_add_f32_dpp v112, v112, v112 quad_perm:[2,3,0,1] row_mask:0xf bank_mask:0xf bound_ctrl:1
	ds_read_b128 v[34:37], v161 offset:17920
	ds_read_b128 v[46:49], v161 offset:26112
	v_add_f32_dpp v110, v110, v110 row_half_mirror row_mask:0xf bank_mask:0xf bound_ctrl:1
	v_add_f32_dpp v112, v112, v112 row_half_mirror row_mask:0xf bank_mask:0xf bound_ctrl:1
	ds_read_b64 v[80:81], v82 offset:42496
	ds_read_b128 v[38:41], v161 offset:1536
	v_add_f32_dpp v110, v110, v110 row_ror:8 row_mask:0xf bank_mask:0xf bound_ctrl:1
	v_add_f32_dpp v112, v112, v112 row_ror:8 row_mask:0xf bank_mask:0xf bound_ctrl:1
	ds_read_b128 v[42:45], v161 offset:34304
	v_pk_mul_f32 v[114:115], v[88:89], v[110:111] op_sel_hi:[1,0]
	v_pk_mul_f32 v[116:117], v[88:89], v[112:113] op_sel_hi:[1,0]
	v_pk_mul_f32 v[118:119], v[90:91], v[110:111] op_sel_hi:[1,0]
	v_pk_mul_f32 v[120:121], v[90:91], v[112:113] op_sel_hi:[1,0]
	v_pk_fma_f32 v[114:115], v[100:101], v[104:105], v[114:115] op_sel_hi:[1,0,1]
	v_pk_fma_f32 v[116:117], v[100:101], v[104:105], v[116:117] op_sel:[0,1,0]
	v_pk_fma_f32 v[118:119], v[102:103], v[104:105], v[118:119] op_sel_hi:[1,0,1]
	v_pk_fma_f32 v[120:121], v[102:103], v[104:105], v[120:121] op_sel:[0,1,0]
	v_pk_fma_f32 v[72:73], v[72:73], v[92:93], v[114:115]
	v_pk_fma_f32 v[76:77], v[76:77], v[92:93], v[116:117]
	v_pk_fma_f32 v[74:75], v[74:75], v[94:95], v[118:119]
	v_pk_fma_f32 v[78:79], v[78:79], v[94:95], v[120:121]
	s_waitcnt lgkmcnt(0)
	v_pk_mul_f32 v[106:107], v[72:73], v[30:31]
	v_pk_mul_f32 v[108:109], v[76:77], v[30:31]
	v_pk_mul_f32 v[122:123], v[72:73], v[96:97]
	v_pk_mul_f32 v[124:125], v[76:77], v[96:97]
	v_pk_fma_f32 v[106:107], v[74:75], v[32:33], v[106:107]
	v_pk_fma_f32 v[108:109], v[78:79], v[32:33], v[108:109]
	v_pk_fma_f32 v[122:123], v[74:75], v[98:99], v[122:123]
	v_pk_fma_f32 v[124:125], v[78:79], v[98:99], v[124:125]
	v_add_f32_e32 v110, v106, v107
	v_add_f32_e32 v112, v108, v109
	v_add_f32_e32 v126, v122, v123
	v_add_f32_e32 v127, v124, v125
	v_add_f32_dpp v110, v110, v110 quad_perm:[1,0,3,2] row_mask:0xf bank_mask:0xf bound_ctrl:1
	v_add_f32_dpp v112, v112, v112 quad_perm:[1,0,3,2] row_mask:0xf bank_mask:0xf bound_ctrl:1
	ds_write_b64 v187, v[126:127] offset:10240
	ds_read_b128 v[84:87], v161 offset:9984
	v_add_f32_dpp v110, v110, v110 quad_perm:[2,3,0,1] row_mask:0xf bank_mask:0xf bound_ctrl:1
	v_add_f32_dpp v112, v112, v112 quad_perm:[2,3,0,1] row_mask:0xf bank_mask:0xf bound_ctrl:1
	ds_read_b128 v[88:91], v161 offset:18176
	ds_read_b128 v[100:103], v161 offset:26368
	v_add_f32_dpp v110, v110, v110 row_half_mirror row_mask:0xf bank_mask:0xf bound_ctrl:1
	v_add_f32_dpp v112, v112, v112 row_half_mirror row_mask:0xf bank_mask:0xf bound_ctrl:1
	ds_read_b64 v[104:105], v82 offset:42752
	ds_read_b128 v[92:95], v161 offset:1792
	v_add_f32_dpp v110, v110, v110 row_ror:8 row_mask:0xf bank_mask:0xf bound_ctrl:1
	v_add_f32_dpp v112, v112, v112 row_ror:8 row_mask:0xf bank_mask:0xf bound_ctrl:1
	ds_read_b128 v[96:99], v161 offset:34560
	v_pk_mul_f32 v[114:115], v[34:35], v[110:111] op_sel_hi:[1,0]
	v_pk_mul_f32 v[116:117], v[34:35], v[112:113] op_sel_hi:[1,0]
	v_pk_mul_f32 v[118:119], v[36:37], v[110:111] op_sel_hi:[1,0]
	v_pk_mul_f32 v[120:121], v[36:37], v[112:113] op_sel_hi:[1,0]
	v_pk_fma_f32 v[114:115], v[46:47], v[80:81], v[114:115] op_sel_hi:[1,0,1]
	v_pk_fma_f32 v[116:117], v[46:47], v[80:81], v[116:117] op_sel:[0,1,0]
	v_pk_fma_f32 v[118:119], v[48:49], v[80:81], v[118:119] op_sel_hi:[1,0,1]
	v_pk_fma_f32 v[120:121], v[48:49], v[80:81], v[120:121] op_sel:[0,1,0]
	v_pk_fma_f32 v[72:73], v[72:73], v[38:39], v[114:115]
	v_pk_fma_f32 v[76:77], v[76:77], v[38:39], v[116:117]
	v_pk_fma_f32 v[74:75], v[74:75], v[40:41], v[118:119]
	v_pk_fma_f32 v[78:79], v[78:79], v[40:41], v[120:121]
	s_waitcnt lgkmcnt(0)
	v_pk_mul_f32 v[106:107], v[72:73], v[84:85]
	v_pk_mul_f32 v[108:109], v[76:77], v[84:85]
	v_pk_mul_f32 v[122:123], v[72:73], v[42:43]
	v_pk_mul_f32 v[124:125], v[76:77], v[42:43]
	v_pk_fma_f32 v[106:107], v[74:75], v[86:87], v[106:107]
	v_pk_fma_f32 v[108:109], v[78:79], v[86:87], v[108:109]
	v_pk_fma_f32 v[122:123], v[74:75], v[44:45], v[122:123]
	v_pk_fma_f32 v[124:125], v[78:79], v[44:45], v[124:125]
	v_add_f32_e32 v110, v106, v107
	v_add_f32_e32 v112, v108, v109
	v_add_f32_e32 v126, v122, v123
	v_add_f32_e32 v127, v124, v125
	v_add_f32_dpp v110, v110, v110 quad_perm:[1,0,3,2] row_mask:0xf bank_mask:0xf bound_ctrl:1
	v_add_f32_dpp v112, v112, v112 quad_perm:[1,0,3,2] row_mask:0xf bank_mask:0xf bound_ctrl:1
	ds_write_b64 v187, v[126:127] offset:12288
	ds_read_b128 v[30:33], v161 offset:10240
	v_add_f32_dpp v110, v110, v110 quad_perm:[2,3,0,1] row_mask:0xf bank_mask:0xf bound_ctrl:1
	v_add_f32_dpp v112, v112, v112 quad_perm:[2,3,0,1] row_mask:0xf bank_mask:0xf bound_ctrl:1
	ds_read_b128 v[34:37], v161 offset:18432
	ds_read_b128 v[46:49], v161 offset:26624
	v_add_f32_dpp v110, v110, v110 row_half_mirror row_mask:0xf bank_mask:0xf bound_ctrl:1
	v_add_f32_dpp v112, v112, v112 row_half_mirror row_mask:0xf bank_mask:0xf bound_ctrl:1
	ds_read_b64 v[80:81], v82 offset:43008
	ds_read_b128 v[38:41], v161 offset:2048
	v_add_f32_dpp v110, v110, v110 row_ror:8 row_mask:0xf bank_mask:0xf bound_ctrl:1
	v_add_f32_dpp v112, v112, v112 row_ror:8 row_mask:0xf bank_mask:0xf bound_ctrl:1
	ds_read_b128 v[42:45], v161 offset:34816
	v_pk_mul_f32 v[114:115], v[88:89], v[110:111] op_sel_hi:[1,0]
	v_pk_mul_f32 v[116:117], v[88:89], v[112:113] op_sel_hi:[1,0]
	v_pk_mul_f32 v[118:119], v[90:91], v[110:111] op_sel_hi:[1,0]
	v_pk_mul_f32 v[120:121], v[90:91], v[112:113] op_sel_hi:[1,0]
	v_pk_fma_f32 v[114:115], v[100:101], v[104:105], v[114:115] op_sel_hi:[1,0,1]
	v_pk_fma_f32 v[116:117], v[100:101], v[104:105], v[116:117] op_sel:[0,1,0]
	v_pk_fma_f32 v[118:119], v[102:103], v[104:105], v[118:119] op_sel_hi:[1,0,1]
	v_pk_fma_f32 v[120:121], v[102:103], v[104:105], v[120:121] op_sel:[0,1,0]
	v_pk_fma_f32 v[72:73], v[72:73], v[92:93], v[114:115]
	v_pk_fma_f32 v[76:77], v[76:77], v[92:93], v[116:117]
	v_pk_fma_f32 v[74:75], v[74:75], v[94:95], v[118:119]
	v_pk_fma_f32 v[78:79], v[78:79], v[94:95], v[120:121]
	s_waitcnt lgkmcnt(0)
	v_pk_mul_f32 v[106:107], v[72:73], v[30:31]
	v_pk_mul_f32 v[108:109], v[76:77], v[30:31]
	v_pk_mul_f32 v[122:123], v[72:73], v[96:97]
	v_pk_mul_f32 v[124:125], v[76:77], v[96:97]
	v_pk_fma_f32 v[106:107], v[74:75], v[32:33], v[106:107]
	v_pk_fma_f32 v[108:109], v[78:79], v[32:33], v[108:109]
	v_pk_fma_f32 v[122:123], v[74:75], v[98:99], v[122:123]
	v_pk_fma_f32 v[124:125], v[78:79], v[98:99], v[124:125]
	v_add_f32_e32 v110, v106, v107
	v_add_f32_e32 v112, v108, v109
	v_add_f32_e32 v126, v122, v123
	v_add_f32_e32 v127, v124, v125
	v_add_f32_dpp v110, v110, v110 quad_perm:[1,0,3,2] row_mask:0xf bank_mask:0xf bound_ctrl:1
	v_add_f32_dpp v112, v112, v112 quad_perm:[1,0,3,2] row_mask:0xf bank_mask:0xf bound_ctrl:1
	ds_write_b64 v187, v[126:127] offset:14336
	ds_read_b128 v[84:87], v161 offset:10496
	v_add_f32_dpp v110, v110, v110 quad_perm:[2,3,0,1] row_mask:0xf bank_mask:0xf bound_ctrl:1
	v_add_f32_dpp v112, v112, v112 quad_perm:[2,3,0,1] row_mask:0xf bank_mask:0xf bound_ctrl:1
	ds_read_b128 v[88:91], v161 offset:18688
	ds_read_b128 v[100:103], v161 offset:26880
	v_add_f32_dpp v110, v110, v110 row_half_mirror row_mask:0xf bank_mask:0xf bound_ctrl:1
	v_add_f32_dpp v112, v112, v112 row_half_mirror row_mask:0xf bank_mask:0xf bound_ctrl:1
	ds_read_b64 v[104:105], v82 offset:43264
	ds_read_b128 v[92:95], v161 offset:2304
	v_add_f32_dpp v110, v110, v110 row_ror:8 row_mask:0xf bank_mask:0xf bound_ctrl:1
	v_add_f32_dpp v112, v112, v112 row_ror:8 row_mask:0xf bank_mask:0xf bound_ctrl:1
	ds_read_b128 v[96:99], v161 offset:35072
	v_pk_mul_f32 v[114:115], v[34:35], v[110:111] op_sel_hi:[1,0]
	v_pk_mul_f32 v[116:117], v[34:35], v[112:113] op_sel_hi:[1,0]
	v_pk_mul_f32 v[118:119], v[36:37], v[110:111] op_sel_hi:[1,0]
	v_pk_mul_f32 v[120:121], v[36:37], v[112:113] op_sel_hi:[1,0]
	v_pk_fma_f32 v[114:115], v[46:47], v[80:81], v[114:115] op_sel_hi:[1,0,1]
	v_pk_fma_f32 v[116:117], v[46:47], v[80:81], v[116:117] op_sel:[0,1,0]
	v_pk_fma_f32 v[118:119], v[48:49], v[80:81], v[118:119] op_sel_hi:[1,0,1]
	v_pk_fma_f32 v[120:121], v[48:49], v[80:81], v[120:121] op_sel:[0,1,0]
	v_pk_fma_f32 v[72:73], v[72:73], v[38:39], v[114:115]
	v_pk_fma_f32 v[76:77], v[76:77], v[38:39], v[116:117]
	v_pk_fma_f32 v[74:75], v[74:75], v[40:41], v[118:119]
	v_pk_fma_f32 v[78:79], v[78:79], v[40:41], v[120:121]
	s_waitcnt lgkmcnt(0)
	v_pk_mul_f32 v[106:107], v[72:73], v[84:85]
	v_pk_mul_f32 v[108:109], v[76:77], v[84:85]
	v_pk_mul_f32 v[122:123], v[72:73], v[42:43]
	v_pk_mul_f32 v[124:125], v[76:77], v[42:43]
	v_pk_fma_f32 v[106:107], v[74:75], v[86:87], v[106:107]
	v_pk_fma_f32 v[108:109], v[78:79], v[86:87], v[108:109]
	v_pk_fma_f32 v[122:123], v[74:75], v[44:45], v[122:123]
	v_pk_fma_f32 v[124:125], v[78:79], v[44:45], v[124:125]
	v_add_f32_e32 v110, v106, v107
	v_add_f32_e32 v112, v108, v109
	v_add_f32_e32 v126, v122, v123
	v_add_f32_e32 v127, v124, v125
	v_add_f32_dpp v110, v110, v110 quad_perm:[1,0,3,2] row_mask:0xf bank_mask:0xf bound_ctrl:1
	v_add_f32_dpp v112, v112, v112 quad_perm:[1,0,3,2] row_mask:0xf bank_mask:0xf bound_ctrl:1
	ds_write_b64 v187, v[126:127] offset:16384
	ds_read_b128 v[30:33], v161 offset:10752
	v_add_f32_dpp v110, v110, v110 quad_perm:[2,3,0,1] row_mask:0xf bank_mask:0xf bound_ctrl:1
	v_add_f32_dpp v112, v112, v112 quad_perm:[2,3,0,1] row_mask:0xf bank_mask:0xf bound_ctrl:1
	ds_read_b128 v[34:37], v161 offset:18944
	ds_read_b128 v[46:49], v161 offset:27136
	v_add_f32_dpp v110, v110, v110 row_half_mirror row_mask:0xf bank_mask:0xf bound_ctrl:1
	v_add_f32_dpp v112, v112, v112 row_half_mirror row_mask:0xf bank_mask:0xf bound_ctrl:1
	ds_read_b64 v[80:81], v82 offset:43520
	ds_read_b128 v[38:41], v161 offset:2560
	v_add_f32_dpp v110, v110, v110 row_ror:8 row_mask:0xf bank_mask:0xf bound_ctrl:1
	v_add_f32_dpp v112, v112, v112 row_ror:8 row_mask:0xf bank_mask:0xf bound_ctrl:1
	ds_read_b128 v[42:45], v161 offset:35328
	v_pk_mul_f32 v[114:115], v[88:89], v[110:111] op_sel_hi:[1,0]
	v_pk_mul_f32 v[116:117], v[88:89], v[112:113] op_sel_hi:[1,0]
	v_pk_mul_f32 v[118:119], v[90:91], v[110:111] op_sel_hi:[1,0]
	v_pk_mul_f32 v[120:121], v[90:91], v[112:113] op_sel_hi:[1,0]
	v_pk_fma_f32 v[114:115], v[100:101], v[104:105], v[114:115] op_sel_hi:[1,0,1]
	v_pk_fma_f32 v[116:117], v[100:101], v[104:105], v[116:117] op_sel:[0,1,0]
	v_pk_fma_f32 v[118:119], v[102:103], v[104:105], v[118:119] op_sel_hi:[1,0,1]
	v_pk_fma_f32 v[120:121], v[102:103], v[104:105], v[120:121] op_sel:[0,1,0]
	v_pk_fma_f32 v[72:73], v[72:73], v[92:93], v[114:115]
	v_pk_fma_f32 v[76:77], v[76:77], v[92:93], v[116:117]
	v_pk_fma_f32 v[74:75], v[74:75], v[94:95], v[118:119]
	v_pk_fma_f32 v[78:79], v[78:79], v[94:95], v[120:121]
	s_waitcnt lgkmcnt(0)
	v_pk_mul_f32 v[106:107], v[72:73], v[30:31]
	v_pk_mul_f32 v[108:109], v[76:77], v[30:31]
	v_pk_mul_f32 v[122:123], v[72:73], v[96:97]
	v_pk_mul_f32 v[124:125], v[76:77], v[96:97]
	v_pk_fma_f32 v[106:107], v[74:75], v[32:33], v[106:107]
	v_pk_fma_f32 v[108:109], v[78:79], v[32:33], v[108:109]
	v_pk_fma_f32 v[122:123], v[74:75], v[98:99], v[122:123]
	v_pk_fma_f32 v[124:125], v[78:79], v[98:99], v[124:125]
	v_add_f32_e32 v110, v106, v107
	v_add_f32_e32 v112, v108, v109
	v_add_f32_e32 v126, v122, v123
	v_add_f32_e32 v127, v124, v125
	v_add_f32_dpp v110, v110, v110 quad_perm:[1,0,3,2] row_mask:0xf bank_mask:0xf bound_ctrl:1
	v_add_f32_dpp v112, v112, v112 quad_perm:[1,0,3,2] row_mask:0xf bank_mask:0xf bound_ctrl:1
	ds_write_b64 v187, v[126:127] offset:18432
	ds_read_b128 v[84:87], v161 offset:11008
	v_add_f32_dpp v110, v110, v110 quad_perm:[2,3,0,1] row_mask:0xf bank_mask:0xf bound_ctrl:1
	v_add_f32_dpp v112, v112, v112 quad_perm:[2,3,0,1] row_mask:0xf bank_mask:0xf bound_ctrl:1
	ds_read_b128 v[88:91], v161 offset:19200
	ds_read_b128 v[100:103], v161 offset:27392
	v_add_f32_dpp v110, v110, v110 row_half_mirror row_mask:0xf bank_mask:0xf bound_ctrl:1
	v_add_f32_dpp v112, v112, v112 row_half_mirror row_mask:0xf bank_mask:0xf bound_ctrl:1
	ds_read_b64 v[104:105], v82 offset:43776
	ds_read_b128 v[92:95], v161 offset:2816
	v_add_f32_dpp v110, v110, v110 row_ror:8 row_mask:0xf bank_mask:0xf bound_ctrl:1
	v_add_f32_dpp v112, v112, v112 row_ror:8 row_mask:0xf bank_mask:0xf bound_ctrl:1
	ds_read_b128 v[96:99], v161 offset:35584
	v_pk_mul_f32 v[114:115], v[34:35], v[110:111] op_sel_hi:[1,0]
	v_pk_mul_f32 v[116:117], v[34:35], v[112:113] op_sel_hi:[1,0]
	v_pk_mul_f32 v[118:119], v[36:37], v[110:111] op_sel_hi:[1,0]
	v_pk_mul_f32 v[120:121], v[36:37], v[112:113] op_sel_hi:[1,0]
	v_pk_fma_f32 v[114:115], v[46:47], v[80:81], v[114:115] op_sel_hi:[1,0,1]
	v_pk_fma_f32 v[116:117], v[46:47], v[80:81], v[116:117] op_sel:[0,1,0]
	v_pk_fma_f32 v[118:119], v[48:49], v[80:81], v[118:119] op_sel_hi:[1,0,1]
	v_pk_fma_f32 v[120:121], v[48:49], v[80:81], v[120:121] op_sel:[0,1,0]
	v_pk_fma_f32 v[72:73], v[72:73], v[38:39], v[114:115]
	v_pk_fma_f32 v[76:77], v[76:77], v[38:39], v[116:117]
	v_pk_fma_f32 v[74:75], v[74:75], v[40:41], v[118:119]
	v_pk_fma_f32 v[78:79], v[78:79], v[40:41], v[120:121]
	s_waitcnt lgkmcnt(0)
	v_pk_mul_f32 v[106:107], v[72:73], v[84:85]
	v_pk_mul_f32 v[108:109], v[76:77], v[84:85]
	v_pk_mul_f32 v[122:123], v[72:73], v[42:43]
	v_pk_mul_f32 v[124:125], v[76:77], v[42:43]
	v_pk_fma_f32 v[106:107], v[74:75], v[86:87], v[106:107]
	v_pk_fma_f32 v[108:109], v[78:79], v[86:87], v[108:109]
	v_pk_fma_f32 v[122:123], v[74:75], v[44:45], v[122:123]
	v_pk_fma_f32 v[124:125], v[78:79], v[44:45], v[124:125]
	v_add_f32_e32 v110, v106, v107
	v_add_f32_e32 v112, v108, v109
	v_add_f32_e32 v126, v122, v123
	v_add_f32_e32 v127, v124, v125
	v_add_f32_dpp v110, v110, v110 quad_perm:[1,0,3,2] row_mask:0xf bank_mask:0xf bound_ctrl:1
	v_add_f32_dpp v112, v112, v112 quad_perm:[1,0,3,2] row_mask:0xf bank_mask:0xf bound_ctrl:1
	ds_write_b64 v187, v[126:127] offset:20480
	ds_read_b128 v[30:33], v161 offset:11264
	v_add_f32_dpp v110, v110, v110 quad_perm:[2,3,0,1] row_mask:0xf bank_mask:0xf bound_ctrl:1
	v_add_f32_dpp v112, v112, v112 quad_perm:[2,3,0,1] row_mask:0xf bank_mask:0xf bound_ctrl:1
	ds_read_b128 v[34:37], v161 offset:19456
	ds_read_b128 v[46:49], v161 offset:27648
	v_add_f32_dpp v110, v110, v110 row_half_mirror row_mask:0xf bank_mask:0xf bound_ctrl:1
	v_add_f32_dpp v112, v112, v112 row_half_mirror row_mask:0xf bank_mask:0xf bound_ctrl:1
	ds_read_b64 v[80:81], v82 offset:44032
	ds_read_b128 v[38:41], v161 offset:3072
	v_add_f32_dpp v110, v110, v110 row_ror:8 row_mask:0xf bank_mask:0xf bound_ctrl:1
	v_add_f32_dpp v112, v112, v112 row_ror:8 row_mask:0xf bank_mask:0xf bound_ctrl:1
	ds_read_b128 v[42:45], v161 offset:35840
	v_pk_mul_f32 v[114:115], v[88:89], v[110:111] op_sel_hi:[1,0]
	v_pk_mul_f32 v[116:117], v[88:89], v[112:113] op_sel_hi:[1,0]
	v_pk_mul_f32 v[118:119], v[90:91], v[110:111] op_sel_hi:[1,0]
	v_pk_mul_f32 v[120:121], v[90:91], v[112:113] op_sel_hi:[1,0]
	v_pk_fma_f32 v[114:115], v[100:101], v[104:105], v[114:115] op_sel_hi:[1,0,1]
	v_pk_fma_f32 v[116:117], v[100:101], v[104:105], v[116:117] op_sel:[0,1,0]
	v_pk_fma_f32 v[118:119], v[102:103], v[104:105], v[118:119] op_sel_hi:[1,0,1]
	v_pk_fma_f32 v[120:121], v[102:103], v[104:105], v[120:121] op_sel:[0,1,0]
	v_pk_fma_f32 v[72:73], v[72:73], v[92:93], v[114:115]
	v_pk_fma_f32 v[76:77], v[76:77], v[92:93], v[116:117]
	v_pk_fma_f32 v[74:75], v[74:75], v[94:95], v[118:119]
	v_pk_fma_f32 v[78:79], v[78:79], v[94:95], v[120:121]
	s_waitcnt lgkmcnt(0)
	v_pk_mul_f32 v[106:107], v[72:73], v[30:31]
	v_pk_mul_f32 v[108:109], v[76:77], v[30:31]
	v_pk_mul_f32 v[122:123], v[72:73], v[96:97]
	v_pk_mul_f32 v[124:125], v[76:77], v[96:97]
	v_pk_fma_f32 v[106:107], v[74:75], v[32:33], v[106:107]
	v_pk_fma_f32 v[108:109], v[78:79], v[32:33], v[108:109]
	v_pk_fma_f32 v[122:123], v[74:75], v[98:99], v[122:123]
	v_pk_fma_f32 v[124:125], v[78:79], v[98:99], v[124:125]
	v_add_f32_e32 v110, v106, v107
	v_add_f32_e32 v112, v108, v109
	v_add_f32_e32 v126, v122, v123
	v_add_f32_e32 v127, v124, v125
	v_add_f32_dpp v110, v110, v110 quad_perm:[1,0,3,2] row_mask:0xf bank_mask:0xf bound_ctrl:1
	v_add_f32_dpp v112, v112, v112 quad_perm:[1,0,3,2] row_mask:0xf bank_mask:0xf bound_ctrl:1
	ds_write_b64 v187, v[126:127] offset:22528
	ds_read_b128 v[84:87], v161 offset:11520
	v_add_f32_dpp v110, v110, v110 quad_perm:[2,3,0,1] row_mask:0xf bank_mask:0xf bound_ctrl:1
	v_add_f32_dpp v112, v112, v112 quad_perm:[2,3,0,1] row_mask:0xf bank_mask:0xf bound_ctrl:1
	ds_read_b128 v[88:91], v161 offset:19712
	ds_read_b128 v[100:103], v161 offset:27904
	v_add_f32_dpp v110, v110, v110 row_half_mirror row_mask:0xf bank_mask:0xf bound_ctrl:1
	v_add_f32_dpp v112, v112, v112 row_half_mirror row_mask:0xf bank_mask:0xf bound_ctrl:1
	ds_read_b64 v[104:105], v82 offset:44288
	ds_read_b128 v[92:95], v161 offset:3328
	v_add_f32_dpp v110, v110, v110 row_ror:8 row_mask:0xf bank_mask:0xf bound_ctrl:1
	v_add_f32_dpp v112, v112, v112 row_ror:8 row_mask:0xf bank_mask:0xf bound_ctrl:1
	ds_read_b128 v[96:99], v161 offset:36096
	v_pk_mul_f32 v[114:115], v[34:35], v[110:111] op_sel_hi:[1,0]
	v_pk_mul_f32 v[116:117], v[34:35], v[112:113] op_sel_hi:[1,0]
	v_pk_mul_f32 v[118:119], v[36:37], v[110:111] op_sel_hi:[1,0]
	v_pk_mul_f32 v[120:121], v[36:37], v[112:113] op_sel_hi:[1,0]
	v_pk_fma_f32 v[114:115], v[46:47], v[80:81], v[114:115] op_sel_hi:[1,0,1]
	v_pk_fma_f32 v[116:117], v[46:47], v[80:81], v[116:117] op_sel:[0,1,0]
	v_pk_fma_f32 v[118:119], v[48:49], v[80:81], v[118:119] op_sel_hi:[1,0,1]
	v_pk_fma_f32 v[120:121], v[48:49], v[80:81], v[120:121] op_sel:[0,1,0]
	v_pk_fma_f32 v[72:73], v[72:73], v[38:39], v[114:115]
	v_pk_fma_f32 v[76:77], v[76:77], v[38:39], v[116:117]
	v_pk_fma_f32 v[74:75], v[74:75], v[40:41], v[118:119]
	v_pk_fma_f32 v[78:79], v[78:79], v[40:41], v[120:121]
	s_waitcnt lgkmcnt(0)
	v_pk_mul_f32 v[106:107], v[72:73], v[84:85]
	v_pk_mul_f32 v[108:109], v[76:77], v[84:85]
	v_pk_mul_f32 v[122:123], v[72:73], v[42:43]
	v_pk_mul_f32 v[124:125], v[76:77], v[42:43]
	v_pk_fma_f32 v[106:107], v[74:75], v[86:87], v[106:107]
	v_pk_fma_f32 v[108:109], v[78:79], v[86:87], v[108:109]
	v_pk_fma_f32 v[122:123], v[74:75], v[44:45], v[122:123]
	v_pk_fma_f32 v[124:125], v[78:79], v[44:45], v[124:125]
	v_add_f32_e32 v110, v106, v107
	v_add_f32_e32 v112, v108, v109
	v_add_f32_e32 v126, v122, v123
	v_add_f32_e32 v127, v124, v125
	v_add_f32_dpp v110, v110, v110 quad_perm:[1,0,3,2] row_mask:0xf bank_mask:0xf bound_ctrl:1
	v_add_f32_dpp v112, v112, v112 quad_perm:[1,0,3,2] row_mask:0xf bank_mask:0xf bound_ctrl:1
	ds_write_b64 v187, v[126:127] offset:24576
	ds_read_b128 v[30:33], v161 offset:11776
	v_add_f32_dpp v110, v110, v110 quad_perm:[2,3,0,1] row_mask:0xf bank_mask:0xf bound_ctrl:1
	v_add_f32_dpp v112, v112, v112 quad_perm:[2,3,0,1] row_mask:0xf bank_mask:0xf bound_ctrl:1
	ds_read_b128 v[34:37], v161 offset:19968
	ds_read_b128 v[46:49], v161 offset:28160
	v_add_f32_dpp v110, v110, v110 row_half_mirror row_mask:0xf bank_mask:0xf bound_ctrl:1
	v_add_f32_dpp v112, v112, v112 row_half_mirror row_mask:0xf bank_mask:0xf bound_ctrl:1
	ds_read_b64 v[80:81], v82 offset:44544
	ds_read_b128 v[38:41], v161 offset:3584
	v_add_f32_dpp v110, v110, v110 row_ror:8 row_mask:0xf bank_mask:0xf bound_ctrl:1
	v_add_f32_dpp v112, v112, v112 row_ror:8 row_mask:0xf bank_mask:0xf bound_ctrl:1
	ds_read_b128 v[42:45], v161 offset:36352
	v_pk_mul_f32 v[114:115], v[88:89], v[110:111] op_sel_hi:[1,0]
	v_pk_mul_f32 v[116:117], v[88:89], v[112:113] op_sel_hi:[1,0]
	v_pk_mul_f32 v[118:119], v[90:91], v[110:111] op_sel_hi:[1,0]
	v_pk_mul_f32 v[120:121], v[90:91], v[112:113] op_sel_hi:[1,0]
	v_pk_fma_f32 v[114:115], v[100:101], v[104:105], v[114:115] op_sel_hi:[1,0,1]
	v_pk_fma_f32 v[116:117], v[100:101], v[104:105], v[116:117] op_sel:[0,1,0]
	v_pk_fma_f32 v[118:119], v[102:103], v[104:105], v[118:119] op_sel_hi:[1,0,1]
	v_pk_fma_f32 v[120:121], v[102:103], v[104:105], v[120:121] op_sel:[0,1,0]
	v_pk_fma_f32 v[72:73], v[72:73], v[92:93], v[114:115]
	v_pk_fma_f32 v[76:77], v[76:77], v[92:93], v[116:117]
	v_pk_fma_f32 v[74:75], v[74:75], v[94:95], v[118:119]
	v_pk_fma_f32 v[78:79], v[78:79], v[94:95], v[120:121]
	s_waitcnt lgkmcnt(0)
	v_pk_mul_f32 v[106:107], v[72:73], v[30:31]
	v_pk_mul_f32 v[108:109], v[76:77], v[30:31]
	v_pk_mul_f32 v[122:123], v[72:73], v[96:97]
	v_pk_mul_f32 v[124:125], v[76:77], v[96:97]
	v_pk_fma_f32 v[106:107], v[74:75], v[32:33], v[106:107]
	v_pk_fma_f32 v[108:109], v[78:79], v[32:33], v[108:109]
	v_pk_fma_f32 v[122:123], v[74:75], v[98:99], v[122:123]
	v_pk_fma_f32 v[124:125], v[78:79], v[98:99], v[124:125]
	v_add_f32_e32 v110, v106, v107
	v_add_f32_e32 v112, v108, v109
	v_add_f32_e32 v126, v122, v123
	v_add_f32_e32 v127, v124, v125
	v_add_f32_dpp v110, v110, v110 quad_perm:[1,0,3,2] row_mask:0xf bank_mask:0xf bound_ctrl:1
	v_add_f32_dpp v112, v112, v112 quad_perm:[1,0,3,2] row_mask:0xf bank_mask:0xf bound_ctrl:1
	ds_write_b64 v187, v[126:127] offset:26624
	ds_read_b128 v[84:87], v161 offset:12032
	v_add_f32_dpp v110, v110, v110 quad_perm:[2,3,0,1] row_mask:0xf bank_mask:0xf bound_ctrl:1
	v_add_f32_dpp v112, v112, v112 quad_perm:[2,3,0,1] row_mask:0xf bank_mask:0xf bound_ctrl:1
	ds_read_b128 v[88:91], v161 offset:20224
	ds_read_b128 v[100:103], v161 offset:28416
	v_add_f32_dpp v110, v110, v110 row_half_mirror row_mask:0xf bank_mask:0xf bound_ctrl:1
	v_add_f32_dpp v112, v112, v112 row_half_mirror row_mask:0xf bank_mask:0xf bound_ctrl:1
	ds_read_b64 v[104:105], v82 offset:44800
	ds_read_b128 v[92:95], v161 offset:3840
	v_add_f32_dpp v110, v110, v110 row_ror:8 row_mask:0xf bank_mask:0xf bound_ctrl:1
	v_add_f32_dpp v112, v112, v112 row_ror:8 row_mask:0xf bank_mask:0xf bound_ctrl:1
	ds_read_b128 v[96:99], v161 offset:36608
	v_pk_mul_f32 v[114:115], v[34:35], v[110:111] op_sel_hi:[1,0]
	v_pk_mul_f32 v[116:117], v[34:35], v[112:113] op_sel_hi:[1,0]
	v_pk_mul_f32 v[118:119], v[36:37], v[110:111] op_sel_hi:[1,0]
	v_pk_mul_f32 v[120:121], v[36:37], v[112:113] op_sel_hi:[1,0]
	v_pk_fma_f32 v[114:115], v[46:47], v[80:81], v[114:115] op_sel_hi:[1,0,1]
	v_pk_fma_f32 v[116:117], v[46:47], v[80:81], v[116:117] op_sel:[0,1,0]
	v_pk_fma_f32 v[118:119], v[48:49], v[80:81], v[118:119] op_sel_hi:[1,0,1]
	v_pk_fma_f32 v[120:121], v[48:49], v[80:81], v[120:121] op_sel:[0,1,0]
	v_pk_fma_f32 v[72:73], v[72:73], v[38:39], v[114:115]
	v_pk_fma_f32 v[76:77], v[76:77], v[38:39], v[116:117]
	v_pk_fma_f32 v[74:75], v[74:75], v[40:41], v[118:119]
	v_pk_fma_f32 v[78:79], v[78:79], v[40:41], v[120:121]
	s_waitcnt lgkmcnt(0)
	v_pk_mul_f32 v[106:107], v[72:73], v[84:85]
	v_pk_mul_f32 v[108:109], v[76:77], v[84:85]
	v_pk_mul_f32 v[122:123], v[72:73], v[42:43]
	v_pk_mul_f32 v[124:125], v[76:77], v[42:43]
	v_pk_fma_f32 v[106:107], v[74:75], v[86:87], v[106:107]
	v_pk_fma_f32 v[108:109], v[78:79], v[86:87], v[108:109]
	v_pk_fma_f32 v[122:123], v[74:75], v[44:45], v[122:123]
	v_pk_fma_f32 v[124:125], v[78:79], v[44:45], v[124:125]
	v_add_f32_e32 v110, v106, v107
	v_add_f32_e32 v112, v108, v109
	v_add_f32_e32 v126, v122, v123
	v_add_f32_e32 v127, v124, v125
	v_add_f32_dpp v110, v110, v110 quad_perm:[1,0,3,2] row_mask:0xf bank_mask:0xf bound_ctrl:1
	v_add_f32_dpp v112, v112, v112 quad_perm:[1,0,3,2] row_mask:0xf bank_mask:0xf bound_ctrl:1
	ds_write_b64 v187, v[126:127] offset:28672
	ds_read_b128 v[30:33], v161 offset:12288
	v_add_f32_dpp v110, v110, v110 quad_perm:[2,3,0,1] row_mask:0xf bank_mask:0xf bound_ctrl:1
	v_add_f32_dpp v112, v112, v112 quad_perm:[2,3,0,1] row_mask:0xf bank_mask:0xf bound_ctrl:1
	ds_read_b128 v[34:37], v161 offset:20480
	ds_read_b128 v[46:49], v161 offset:28672
	v_add_f32_dpp v110, v110, v110 row_half_mirror row_mask:0xf bank_mask:0xf bound_ctrl:1
	v_add_f32_dpp v112, v112, v112 row_half_mirror row_mask:0xf bank_mask:0xf bound_ctrl:1
	ds_read_b64 v[80:81], v82 offset:45056
	ds_read_b128 v[38:41], v161 offset:4096
	v_add_f32_dpp v110, v110, v110 row_ror:8 row_mask:0xf bank_mask:0xf bound_ctrl:1
	v_add_f32_dpp v112, v112, v112 row_ror:8 row_mask:0xf bank_mask:0xf bound_ctrl:1
	ds_read_b128 v[42:45], v161 offset:36864
	v_pk_mul_f32 v[114:115], v[88:89], v[110:111] op_sel_hi:[1,0]
	v_pk_mul_f32 v[116:117], v[88:89], v[112:113] op_sel_hi:[1,0]
	v_pk_mul_f32 v[118:119], v[90:91], v[110:111] op_sel_hi:[1,0]
	v_pk_mul_f32 v[120:121], v[90:91], v[112:113] op_sel_hi:[1,0]
	v_pk_fma_f32 v[114:115], v[100:101], v[104:105], v[114:115] op_sel_hi:[1,0,1]
	v_pk_fma_f32 v[116:117], v[100:101], v[104:105], v[116:117] op_sel:[0,1,0]
	v_pk_fma_f32 v[118:119], v[102:103], v[104:105], v[118:119] op_sel_hi:[1,0,1]
	v_pk_fma_f32 v[120:121], v[102:103], v[104:105], v[120:121] op_sel:[0,1,0]
	v_pk_fma_f32 v[72:73], v[72:73], v[92:93], v[114:115]
	v_pk_fma_f32 v[76:77], v[76:77], v[92:93], v[116:117]
	v_pk_fma_f32 v[74:75], v[74:75], v[94:95], v[118:119]
	v_pk_fma_f32 v[78:79], v[78:79], v[94:95], v[120:121]
	s_waitcnt lgkmcnt(0)
	v_pk_mul_f32 v[106:107], v[72:73], v[30:31]
	v_pk_mul_f32 v[108:109], v[76:77], v[30:31]
	v_pk_mul_f32 v[122:123], v[72:73], v[96:97]
	v_pk_mul_f32 v[124:125], v[76:77], v[96:97]
	v_pk_fma_f32 v[106:107], v[74:75], v[32:33], v[106:107]
	v_pk_fma_f32 v[108:109], v[78:79], v[32:33], v[108:109]
	v_pk_fma_f32 v[122:123], v[74:75], v[98:99], v[122:123]
	v_pk_fma_f32 v[124:125], v[78:79], v[98:99], v[124:125]
	v_add_f32_e32 v110, v106, v107
	v_add_f32_e32 v112, v108, v109
	v_add_f32_e32 v126, v122, v123
	v_add_f32_e32 v127, v124, v125
	v_add_f32_dpp v110, v110, v110 quad_perm:[1,0,3,2] row_mask:0xf bank_mask:0xf bound_ctrl:1
	v_add_f32_dpp v112, v112, v112 quad_perm:[1,0,3,2] row_mask:0xf bank_mask:0xf bound_ctrl:1
	ds_write_b64 v187, v[126:127] offset:30720
	ds_read_b128 v[84:87], v161 offset:12544
	v_add_f32_dpp v110, v110, v110 quad_perm:[2,3,0,1] row_mask:0xf bank_mask:0xf bound_ctrl:1
	v_add_f32_dpp v112, v112, v112 quad_perm:[2,3,0,1] row_mask:0xf bank_mask:0xf bound_ctrl:1
	ds_read_b128 v[88:91], v161 offset:20736
	ds_read_b128 v[100:103], v161 offset:28928
	v_add_f32_dpp v110, v110, v110 row_half_mirror row_mask:0xf bank_mask:0xf bound_ctrl:1
	v_add_f32_dpp v112, v112, v112 row_half_mirror row_mask:0xf bank_mask:0xf bound_ctrl:1
	ds_read_b64 v[104:105], v82 offset:45312
	ds_read_b128 v[92:95], v161 offset:4352
	v_add_f32_dpp v110, v110, v110 row_ror:8 row_mask:0xf bank_mask:0xf bound_ctrl:1
	v_add_f32_dpp v112, v112, v112 row_ror:8 row_mask:0xf bank_mask:0xf bound_ctrl:1
	ds_read_b128 v[96:99], v161 offset:37120
	v_pk_mul_f32 v[114:115], v[34:35], v[110:111] op_sel_hi:[1,0]
	v_pk_mul_f32 v[116:117], v[34:35], v[112:113] op_sel_hi:[1,0]
	v_pk_mul_f32 v[118:119], v[36:37], v[110:111] op_sel_hi:[1,0]
	v_pk_mul_f32 v[120:121], v[36:37], v[112:113] op_sel_hi:[1,0]
	v_pk_fma_f32 v[114:115], v[46:47], v[80:81], v[114:115] op_sel_hi:[1,0,1]
	v_pk_fma_f32 v[116:117], v[46:47], v[80:81], v[116:117] op_sel:[0,1,0]
	v_pk_fma_f32 v[118:119], v[48:49], v[80:81], v[118:119] op_sel_hi:[1,0,1]
	v_pk_fma_f32 v[120:121], v[48:49], v[80:81], v[120:121] op_sel:[0,1,0]
	v_pk_fma_f32 v[72:73], v[72:73], v[38:39], v[114:115]
	v_pk_fma_f32 v[76:77], v[76:77], v[38:39], v[116:117]
	v_pk_fma_f32 v[74:75], v[74:75], v[40:41], v[118:119]
	v_pk_fma_f32 v[78:79], v[78:79], v[40:41], v[120:121]
	s_waitcnt lgkmcnt(0)
	v_pk_mul_f32 v[106:107], v[72:73], v[84:85]
	v_pk_mul_f32 v[108:109], v[76:77], v[84:85]
	v_pk_mul_f32 v[122:123], v[72:73], v[42:43]
	v_pk_mul_f32 v[124:125], v[76:77], v[42:43]
	v_pk_fma_f32 v[106:107], v[74:75], v[86:87], v[106:107]
	v_pk_fma_f32 v[108:109], v[78:79], v[86:87], v[108:109]
	v_pk_fma_f32 v[122:123], v[74:75], v[44:45], v[122:123]
	v_pk_fma_f32 v[124:125], v[78:79], v[44:45], v[124:125]
	v_add_f32_e32 v110, v106, v107
	v_add_f32_e32 v112, v108, v109
	v_add_f32_e32 v126, v122, v123
	v_add_f32_e32 v127, v124, v125
	v_add_f32_dpp v110, v110, v110 quad_perm:[1,0,3,2] row_mask:0xf bank_mask:0xf bound_ctrl:1
	v_add_f32_dpp v112, v112, v112 quad_perm:[1,0,3,2] row_mask:0xf bank_mask:0xf bound_ctrl:1
	ds_write_b64 v187, v[126:127] offset:32768
	ds_read_b128 v[30:33], v161 offset:12800
	v_add_f32_dpp v110, v110, v110 quad_perm:[2,3,0,1] row_mask:0xf bank_mask:0xf bound_ctrl:1
	v_add_f32_dpp v112, v112, v112 quad_perm:[2,3,0,1] row_mask:0xf bank_mask:0xf bound_ctrl:1
	ds_read_b128 v[34:37], v161 offset:20992
	ds_read_b128 v[46:49], v161 offset:29184
	v_add_f32_dpp v110, v110, v110 row_half_mirror row_mask:0xf bank_mask:0xf bound_ctrl:1
	v_add_f32_dpp v112, v112, v112 row_half_mirror row_mask:0xf bank_mask:0xf bound_ctrl:1
	ds_read_b64 v[80:81], v82 offset:45568
	ds_read_b128 v[38:41], v161 offset:4608
	v_add_f32_dpp v110, v110, v110 row_ror:8 row_mask:0xf bank_mask:0xf bound_ctrl:1
	v_add_f32_dpp v112, v112, v112 row_ror:8 row_mask:0xf bank_mask:0xf bound_ctrl:1
	ds_read_b128 v[42:45], v161 offset:37376
	v_pk_mul_f32 v[114:115], v[88:89], v[110:111] op_sel_hi:[1,0]
	v_pk_mul_f32 v[116:117], v[88:89], v[112:113] op_sel_hi:[1,0]
	v_pk_mul_f32 v[118:119], v[90:91], v[110:111] op_sel_hi:[1,0]
	v_pk_mul_f32 v[120:121], v[90:91], v[112:113] op_sel_hi:[1,0]
	v_pk_fma_f32 v[114:115], v[100:101], v[104:105], v[114:115] op_sel_hi:[1,0,1]
	v_pk_fma_f32 v[116:117], v[100:101], v[104:105], v[116:117] op_sel:[0,1,0]
	v_pk_fma_f32 v[118:119], v[102:103], v[104:105], v[118:119] op_sel_hi:[1,0,1]
	v_pk_fma_f32 v[120:121], v[102:103], v[104:105], v[120:121] op_sel:[0,1,0]
	v_pk_fma_f32 v[72:73], v[72:73], v[92:93], v[114:115]
	v_pk_fma_f32 v[76:77], v[76:77], v[92:93], v[116:117]
	v_pk_fma_f32 v[74:75], v[74:75], v[94:95], v[118:119]
	v_pk_fma_f32 v[78:79], v[78:79], v[94:95], v[120:121]
	s_waitcnt lgkmcnt(0)
	v_pk_mul_f32 v[106:107], v[72:73], v[30:31]
	v_pk_mul_f32 v[108:109], v[76:77], v[30:31]
	v_pk_mul_f32 v[122:123], v[72:73], v[96:97]
	v_pk_mul_f32 v[124:125], v[76:77], v[96:97]
	v_pk_fma_f32 v[106:107], v[74:75], v[32:33], v[106:107]
	v_pk_fma_f32 v[108:109], v[78:79], v[32:33], v[108:109]
	v_pk_fma_f32 v[122:123], v[74:75], v[98:99], v[122:123]
	v_pk_fma_f32 v[124:125], v[78:79], v[98:99], v[124:125]
	v_add_f32_e32 v110, v106, v107
	v_add_f32_e32 v112, v108, v109
	v_add_f32_e32 v126, v122, v123
	v_add_f32_e32 v127, v124, v125
	v_add_f32_dpp v110, v110, v110 quad_perm:[1,0,3,2] row_mask:0xf bank_mask:0xf bound_ctrl:1
	v_add_f32_dpp v112, v112, v112 quad_perm:[1,0,3,2] row_mask:0xf bank_mask:0xf bound_ctrl:1
	ds_write_b64 v187, v[126:127] offset:34816
	ds_read_b128 v[84:87], v161 offset:13056
	v_add_f32_dpp v110, v110, v110 quad_perm:[2,3,0,1] row_mask:0xf bank_mask:0xf bound_ctrl:1
	v_add_f32_dpp v112, v112, v112 quad_perm:[2,3,0,1] row_mask:0xf bank_mask:0xf bound_ctrl:1
	ds_read_b128 v[88:91], v161 offset:21248
	ds_read_b128 v[100:103], v161 offset:29440
	v_add_f32_dpp v110, v110, v110 row_half_mirror row_mask:0xf bank_mask:0xf bound_ctrl:1
	v_add_f32_dpp v112, v112, v112 row_half_mirror row_mask:0xf bank_mask:0xf bound_ctrl:1
	ds_read_b64 v[104:105], v82 offset:45824
	ds_read_b128 v[92:95], v161 offset:4864
	v_add_f32_dpp v110, v110, v110 row_ror:8 row_mask:0xf bank_mask:0xf bound_ctrl:1
	v_add_f32_dpp v112, v112, v112 row_ror:8 row_mask:0xf bank_mask:0xf bound_ctrl:1
	ds_read_b128 v[96:99], v161 offset:37632
	v_pk_mul_f32 v[114:115], v[34:35], v[110:111] op_sel_hi:[1,0]
	v_pk_mul_f32 v[116:117], v[34:35], v[112:113] op_sel_hi:[1,0]
	v_pk_mul_f32 v[118:119], v[36:37], v[110:111] op_sel_hi:[1,0]
	v_pk_mul_f32 v[120:121], v[36:37], v[112:113] op_sel_hi:[1,0]
	v_pk_fma_f32 v[114:115], v[46:47], v[80:81], v[114:115] op_sel_hi:[1,0,1]
	v_pk_fma_f32 v[116:117], v[46:47], v[80:81], v[116:117] op_sel:[0,1,0]
	v_pk_fma_f32 v[118:119], v[48:49], v[80:81], v[118:119] op_sel_hi:[1,0,1]
	v_pk_fma_f32 v[120:121], v[48:49], v[80:81], v[120:121] op_sel:[0,1,0]
	v_pk_fma_f32 v[72:73], v[72:73], v[38:39], v[114:115]
	v_pk_fma_f32 v[76:77], v[76:77], v[38:39], v[116:117]
	v_pk_fma_f32 v[74:75], v[74:75], v[40:41], v[118:119]
	v_pk_fma_f32 v[78:79], v[78:79], v[40:41], v[120:121]
	s_waitcnt lgkmcnt(0)
	v_pk_mul_f32 v[106:107], v[72:73], v[84:85]
	v_pk_mul_f32 v[108:109], v[76:77], v[84:85]
	v_pk_mul_f32 v[122:123], v[72:73], v[42:43]
	v_pk_mul_f32 v[124:125], v[76:77], v[42:43]
	v_pk_fma_f32 v[106:107], v[74:75], v[86:87], v[106:107]
	v_pk_fma_f32 v[108:109], v[78:79], v[86:87], v[108:109]
	v_pk_fma_f32 v[122:123], v[74:75], v[44:45], v[122:123]
	v_pk_fma_f32 v[124:125], v[78:79], v[44:45], v[124:125]
	v_add_f32_e32 v110, v106, v107
	v_add_f32_e32 v112, v108, v109
	v_add_f32_e32 v126, v122, v123
	v_add_f32_e32 v127, v124, v125
	v_add_f32_dpp v110, v110, v110 quad_perm:[1,0,3,2] row_mask:0xf bank_mask:0xf bound_ctrl:1
	v_add_f32_dpp v112, v112, v112 quad_perm:[1,0,3,2] row_mask:0xf bank_mask:0xf bound_ctrl:1
	ds_write_b64 v187, v[126:127] offset:36864
	ds_read_b128 v[30:33], v161 offset:13312
	v_add_f32_dpp v110, v110, v110 quad_perm:[2,3,0,1] row_mask:0xf bank_mask:0xf bound_ctrl:1
	v_add_f32_dpp v112, v112, v112 quad_perm:[2,3,0,1] row_mask:0xf bank_mask:0xf bound_ctrl:1
	ds_read_b128 v[34:37], v161 offset:21504
	ds_read_b128 v[46:49], v161 offset:29696
	v_add_f32_dpp v110, v110, v110 row_half_mirror row_mask:0xf bank_mask:0xf bound_ctrl:1
	v_add_f32_dpp v112, v112, v112 row_half_mirror row_mask:0xf bank_mask:0xf bound_ctrl:1
	ds_read_b64 v[80:81], v82 offset:46080
	ds_read_b128 v[38:41], v161 offset:5120
	v_add_f32_dpp v110, v110, v110 row_ror:8 row_mask:0xf bank_mask:0xf bound_ctrl:1
	v_add_f32_dpp v112, v112, v112 row_ror:8 row_mask:0xf bank_mask:0xf bound_ctrl:1
	ds_read_b128 v[42:45], v161 offset:37888
	v_pk_mul_f32 v[114:115], v[88:89], v[110:111] op_sel_hi:[1,0]
	v_pk_mul_f32 v[116:117], v[88:89], v[112:113] op_sel_hi:[1,0]
	v_pk_mul_f32 v[118:119], v[90:91], v[110:111] op_sel_hi:[1,0]
	v_pk_mul_f32 v[120:121], v[90:91], v[112:113] op_sel_hi:[1,0]
	v_pk_fma_f32 v[114:115], v[100:101], v[104:105], v[114:115] op_sel_hi:[1,0,1]
	v_pk_fma_f32 v[116:117], v[100:101], v[104:105], v[116:117] op_sel:[0,1,0]
	v_pk_fma_f32 v[118:119], v[102:103], v[104:105], v[118:119] op_sel_hi:[1,0,1]
	v_pk_fma_f32 v[120:121], v[102:103], v[104:105], v[120:121] op_sel:[0,1,0]
	v_pk_fma_f32 v[72:73], v[72:73], v[92:93], v[114:115]
	v_pk_fma_f32 v[76:77], v[76:77], v[92:93], v[116:117]
	v_pk_fma_f32 v[74:75], v[74:75], v[94:95], v[118:119]
	v_pk_fma_f32 v[78:79], v[78:79], v[94:95], v[120:121]
	s_waitcnt lgkmcnt(0)
	v_pk_mul_f32 v[106:107], v[72:73], v[30:31]
	v_pk_mul_f32 v[108:109], v[76:77], v[30:31]
	v_pk_mul_f32 v[122:123], v[72:73], v[96:97]
	v_pk_mul_f32 v[124:125], v[76:77], v[96:97]
	v_pk_fma_f32 v[106:107], v[74:75], v[32:33], v[106:107]
	v_pk_fma_f32 v[108:109], v[78:79], v[32:33], v[108:109]
	v_pk_fma_f32 v[122:123], v[74:75], v[98:99], v[122:123]
	v_pk_fma_f32 v[124:125], v[78:79], v[98:99], v[124:125]
	v_add_f32_e32 v110, v106, v107
	v_add_f32_e32 v112, v108, v109
	v_add_f32_e32 v126, v122, v123
	v_add_f32_e32 v127, v124, v125
	v_add_f32_dpp v110, v110, v110 quad_perm:[1,0,3,2] row_mask:0xf bank_mask:0xf bound_ctrl:1
	v_add_f32_dpp v112, v112, v112 quad_perm:[1,0,3,2] row_mask:0xf bank_mask:0xf bound_ctrl:1
	ds_write_b64 v187, v[126:127] offset:38912
	ds_read_b128 v[84:87], v161 offset:13568
	v_add_f32_dpp v110, v110, v110 quad_perm:[2,3,0,1] row_mask:0xf bank_mask:0xf bound_ctrl:1
	v_add_f32_dpp v112, v112, v112 quad_perm:[2,3,0,1] row_mask:0xf bank_mask:0xf bound_ctrl:1
	ds_read_b128 v[88:91], v161 offset:21760
	ds_read_b128 v[100:103], v161 offset:29952
	v_add_f32_dpp v110, v110, v110 row_half_mirror row_mask:0xf bank_mask:0xf bound_ctrl:1
	v_add_f32_dpp v112, v112, v112 row_half_mirror row_mask:0xf bank_mask:0xf bound_ctrl:1
	ds_read_b64 v[104:105], v82 offset:46336
	ds_read_b128 v[92:95], v161 offset:5376
	v_add_f32_dpp v110, v110, v110 row_ror:8 row_mask:0xf bank_mask:0xf bound_ctrl:1
	v_add_f32_dpp v112, v112, v112 row_ror:8 row_mask:0xf bank_mask:0xf bound_ctrl:1
	ds_read_b128 v[96:99], v161 offset:38144
	v_pk_mul_f32 v[114:115], v[34:35], v[110:111] op_sel_hi:[1,0]
	v_pk_mul_f32 v[116:117], v[34:35], v[112:113] op_sel_hi:[1,0]
	v_pk_mul_f32 v[118:119], v[36:37], v[110:111] op_sel_hi:[1,0]
	v_pk_mul_f32 v[120:121], v[36:37], v[112:113] op_sel_hi:[1,0]
	v_pk_fma_f32 v[114:115], v[46:47], v[80:81], v[114:115] op_sel_hi:[1,0,1]
	v_pk_fma_f32 v[116:117], v[46:47], v[80:81], v[116:117] op_sel:[0,1,0]
	v_pk_fma_f32 v[118:119], v[48:49], v[80:81], v[118:119] op_sel_hi:[1,0,1]
	v_pk_fma_f32 v[120:121], v[48:49], v[80:81], v[120:121] op_sel:[0,1,0]
	v_pk_fma_f32 v[72:73], v[72:73], v[38:39], v[114:115]
	v_pk_fma_f32 v[76:77], v[76:77], v[38:39], v[116:117]
	v_pk_fma_f32 v[74:75], v[74:75], v[40:41], v[118:119]
	v_pk_fma_f32 v[78:79], v[78:79], v[40:41], v[120:121]
	s_waitcnt lgkmcnt(0)
	v_pk_mul_f32 v[106:107], v[72:73], v[84:85]
	v_pk_mul_f32 v[108:109], v[76:77], v[84:85]
	v_pk_mul_f32 v[122:123], v[72:73], v[42:43]
	v_pk_mul_f32 v[124:125], v[76:77], v[42:43]
	v_pk_fma_f32 v[106:107], v[74:75], v[86:87], v[106:107]
	v_pk_fma_f32 v[108:109], v[78:79], v[86:87], v[108:109]
	v_pk_fma_f32 v[122:123], v[74:75], v[44:45], v[122:123]
	v_pk_fma_f32 v[124:125], v[78:79], v[44:45], v[124:125]
	v_add_f32_e32 v110, v106, v107
	v_add_f32_e32 v112, v108, v109
	v_add_f32_e32 v126, v122, v123
	v_add_f32_e32 v127, v124, v125
	v_add_f32_dpp v110, v110, v110 quad_perm:[1,0,3,2] row_mask:0xf bank_mask:0xf bound_ctrl:1
	v_add_f32_dpp v112, v112, v112 quad_perm:[1,0,3,2] row_mask:0xf bank_mask:0xf bound_ctrl:1
	ds_write_b64 v187, v[126:127] offset:40960
	ds_read_b128 v[30:33], v161 offset:13824
	v_add_f32_dpp v110, v110, v110 quad_perm:[2,3,0,1] row_mask:0xf bank_mask:0xf bound_ctrl:1
	v_add_f32_dpp v112, v112, v112 quad_perm:[2,3,0,1] row_mask:0xf bank_mask:0xf bound_ctrl:1
	ds_read_b128 v[34:37], v161 offset:22016
	ds_read_b128 v[46:49], v161 offset:30208
	v_add_f32_dpp v110, v110, v110 row_half_mirror row_mask:0xf bank_mask:0xf bound_ctrl:1
	v_add_f32_dpp v112, v112, v112 row_half_mirror row_mask:0xf bank_mask:0xf bound_ctrl:1
	ds_read_b64 v[80:81], v82 offset:46592
	ds_read_b128 v[38:41], v161 offset:5632
	v_add_f32_dpp v110, v110, v110 row_ror:8 row_mask:0xf bank_mask:0xf bound_ctrl:1
	v_add_f32_dpp v112, v112, v112 row_ror:8 row_mask:0xf bank_mask:0xf bound_ctrl:1
	ds_read_b128 v[42:45], v161 offset:38400
	v_pk_mul_f32 v[114:115], v[88:89], v[110:111] op_sel_hi:[1,0]
	v_pk_mul_f32 v[116:117], v[88:89], v[112:113] op_sel_hi:[1,0]
	v_pk_mul_f32 v[118:119], v[90:91], v[110:111] op_sel_hi:[1,0]
	v_pk_mul_f32 v[120:121], v[90:91], v[112:113] op_sel_hi:[1,0]
	v_pk_fma_f32 v[114:115], v[100:101], v[104:105], v[114:115] op_sel_hi:[1,0,1]
	v_pk_fma_f32 v[116:117], v[100:101], v[104:105], v[116:117] op_sel:[0,1,0]
	v_pk_fma_f32 v[118:119], v[102:103], v[104:105], v[118:119] op_sel_hi:[1,0,1]
	v_pk_fma_f32 v[120:121], v[102:103], v[104:105], v[120:121] op_sel:[0,1,0]
	v_pk_fma_f32 v[72:73], v[72:73], v[92:93], v[114:115]
	v_pk_fma_f32 v[76:77], v[76:77], v[92:93], v[116:117]
	v_pk_fma_f32 v[74:75], v[74:75], v[94:95], v[118:119]
	v_pk_fma_f32 v[78:79], v[78:79], v[94:95], v[120:121]
	s_waitcnt lgkmcnt(0)
	v_pk_mul_f32 v[106:107], v[72:73], v[30:31]
	v_pk_mul_f32 v[108:109], v[76:77], v[30:31]
	v_pk_mul_f32 v[122:123], v[72:73], v[96:97]
	v_pk_mul_f32 v[124:125], v[76:77], v[96:97]
	v_pk_fma_f32 v[106:107], v[74:75], v[32:33], v[106:107]
	v_pk_fma_f32 v[108:109], v[78:79], v[32:33], v[108:109]
	v_pk_fma_f32 v[122:123], v[74:75], v[98:99], v[122:123]
	v_pk_fma_f32 v[124:125], v[78:79], v[98:99], v[124:125]
	v_add_f32_e32 v110, v106, v107
	v_add_f32_e32 v112, v108, v109
	v_add_f32_e32 v126, v122, v123
	v_add_f32_e32 v127, v124, v125
	v_add_f32_dpp v110, v110, v110 quad_perm:[1,0,3,2] row_mask:0xf bank_mask:0xf bound_ctrl:1
	v_add_f32_dpp v112, v112, v112 quad_perm:[1,0,3,2] row_mask:0xf bank_mask:0xf bound_ctrl:1
	ds_write_b64 v187, v[126:127] offset:43008
	ds_read_b128 v[84:87], v161 offset:14080
	v_add_f32_dpp v110, v110, v110 quad_perm:[2,3,0,1] row_mask:0xf bank_mask:0xf bound_ctrl:1
	v_add_f32_dpp v112, v112, v112 quad_perm:[2,3,0,1] row_mask:0xf bank_mask:0xf bound_ctrl:1
	ds_read_b128 v[88:91], v161 offset:22272
	ds_read_b128 v[100:103], v161 offset:30464
	v_add_f32_dpp v110, v110, v110 row_half_mirror row_mask:0xf bank_mask:0xf bound_ctrl:1
	v_add_f32_dpp v112, v112, v112 row_half_mirror row_mask:0xf bank_mask:0xf bound_ctrl:1
	ds_read_b64 v[104:105], v82 offset:46848
	ds_read_b128 v[92:95], v161 offset:5888
	v_add_f32_dpp v110, v110, v110 row_ror:8 row_mask:0xf bank_mask:0xf bound_ctrl:1
	v_add_f32_dpp v112, v112, v112 row_ror:8 row_mask:0xf bank_mask:0xf bound_ctrl:1
	ds_read_b128 v[96:99], v161 offset:38656
	v_pk_mul_f32 v[114:115], v[34:35], v[110:111] op_sel_hi:[1,0]
	v_pk_mul_f32 v[116:117], v[34:35], v[112:113] op_sel_hi:[1,0]
	v_pk_mul_f32 v[118:119], v[36:37], v[110:111] op_sel_hi:[1,0]
	v_pk_mul_f32 v[120:121], v[36:37], v[112:113] op_sel_hi:[1,0]
	v_pk_fma_f32 v[114:115], v[46:47], v[80:81], v[114:115] op_sel_hi:[1,0,1]
	v_pk_fma_f32 v[116:117], v[46:47], v[80:81], v[116:117] op_sel:[0,1,0]
	v_pk_fma_f32 v[118:119], v[48:49], v[80:81], v[118:119] op_sel_hi:[1,0,1]
	v_pk_fma_f32 v[120:121], v[48:49], v[80:81], v[120:121] op_sel:[0,1,0]
	v_pk_fma_f32 v[72:73], v[72:73], v[38:39], v[114:115]
	v_pk_fma_f32 v[76:77], v[76:77], v[38:39], v[116:117]
	v_pk_fma_f32 v[74:75], v[74:75], v[40:41], v[118:119]
	v_pk_fma_f32 v[78:79], v[78:79], v[40:41], v[120:121]
	s_waitcnt lgkmcnt(0)
	v_pk_mul_f32 v[106:107], v[72:73], v[84:85]
	v_pk_mul_f32 v[108:109], v[76:77], v[84:85]
	v_pk_mul_f32 v[122:123], v[72:73], v[42:43]
	v_pk_mul_f32 v[124:125], v[76:77], v[42:43]
	v_pk_fma_f32 v[106:107], v[74:75], v[86:87], v[106:107]
	v_pk_fma_f32 v[108:109], v[78:79], v[86:87], v[108:109]
	v_pk_fma_f32 v[122:123], v[74:75], v[44:45], v[122:123]
	v_pk_fma_f32 v[124:125], v[78:79], v[44:45], v[124:125]
	v_add_f32_e32 v110, v106, v107
	v_add_f32_e32 v112, v108, v109
	v_add_f32_e32 v126, v122, v123
	v_add_f32_e32 v127, v124, v125
	v_add_f32_dpp v110, v110, v110 quad_perm:[1,0,3,2] row_mask:0xf bank_mask:0xf bound_ctrl:1
	v_add_f32_dpp v112, v112, v112 quad_perm:[1,0,3,2] row_mask:0xf bank_mask:0xf bound_ctrl:1
	ds_write_b64 v187, v[126:127] offset:45056
	ds_read_b128 v[30:33], v161 offset:14336
	v_add_f32_dpp v110, v110, v110 quad_perm:[2,3,0,1] row_mask:0xf bank_mask:0xf bound_ctrl:1
	v_add_f32_dpp v112, v112, v112 quad_perm:[2,3,0,1] row_mask:0xf bank_mask:0xf bound_ctrl:1
	ds_read_b128 v[34:37], v161 offset:22528
	ds_read_b128 v[46:49], v161 offset:30720
	v_add_f32_dpp v110, v110, v110 row_half_mirror row_mask:0xf bank_mask:0xf bound_ctrl:1
	v_add_f32_dpp v112, v112, v112 row_half_mirror row_mask:0xf bank_mask:0xf bound_ctrl:1
	ds_read_b64 v[80:81], v82 offset:47104
	ds_read_b128 v[38:41], v161 offset:6144
	v_add_f32_dpp v110, v110, v110 row_ror:8 row_mask:0xf bank_mask:0xf bound_ctrl:1
	v_add_f32_dpp v112, v112, v112 row_ror:8 row_mask:0xf bank_mask:0xf bound_ctrl:1
	ds_read_b128 v[42:45], v161 offset:38912
	v_pk_mul_f32 v[114:115], v[88:89], v[110:111] op_sel_hi:[1,0]
	v_pk_mul_f32 v[116:117], v[88:89], v[112:113] op_sel_hi:[1,0]
	v_pk_mul_f32 v[118:119], v[90:91], v[110:111] op_sel_hi:[1,0]
	v_pk_mul_f32 v[120:121], v[90:91], v[112:113] op_sel_hi:[1,0]
	v_pk_fma_f32 v[114:115], v[100:101], v[104:105], v[114:115] op_sel_hi:[1,0,1]
	v_pk_fma_f32 v[116:117], v[100:101], v[104:105], v[116:117] op_sel:[0,1,0]
	v_pk_fma_f32 v[118:119], v[102:103], v[104:105], v[118:119] op_sel_hi:[1,0,1]
	v_pk_fma_f32 v[120:121], v[102:103], v[104:105], v[120:121] op_sel:[0,1,0]
	v_pk_fma_f32 v[72:73], v[72:73], v[92:93], v[114:115]
	v_pk_fma_f32 v[76:77], v[76:77], v[92:93], v[116:117]
	v_pk_fma_f32 v[74:75], v[74:75], v[94:95], v[118:119]
	v_pk_fma_f32 v[78:79], v[78:79], v[94:95], v[120:121]
	s_waitcnt lgkmcnt(0)
	v_pk_mul_f32 v[106:107], v[72:73], v[30:31]
	v_pk_mul_f32 v[108:109], v[76:77], v[30:31]
	v_pk_mul_f32 v[122:123], v[72:73], v[96:97]
	v_pk_mul_f32 v[124:125], v[76:77], v[96:97]
	v_pk_fma_f32 v[106:107], v[74:75], v[32:33], v[106:107]
	v_pk_fma_f32 v[108:109], v[78:79], v[32:33], v[108:109]
	v_pk_fma_f32 v[122:123], v[74:75], v[98:99], v[122:123]
	v_pk_fma_f32 v[124:125], v[78:79], v[98:99], v[124:125]
	v_add_f32_e32 v110, v106, v107
	v_add_f32_e32 v112, v108, v109
	v_add_f32_e32 v126, v122, v123
	v_add_f32_e32 v127, v124, v125
	v_add_f32_dpp v110, v110, v110 quad_perm:[1,0,3,2] row_mask:0xf bank_mask:0xf bound_ctrl:1
	v_add_f32_dpp v112, v112, v112 quad_perm:[1,0,3,2] row_mask:0xf bank_mask:0xf bound_ctrl:1
	ds_write_b64 v187, v[126:127] offset:47104
	ds_read_b128 v[84:87], v161 offset:14592
	v_add_f32_dpp v110, v110, v110 quad_perm:[2,3,0,1] row_mask:0xf bank_mask:0xf bound_ctrl:1
	v_add_f32_dpp v112, v112, v112 quad_perm:[2,3,0,1] row_mask:0xf bank_mask:0xf bound_ctrl:1
	ds_read_b128 v[88:91], v161 offset:22784
	ds_read_b128 v[100:103], v161 offset:30976
	v_add_f32_dpp v110, v110, v110 row_half_mirror row_mask:0xf bank_mask:0xf bound_ctrl:1
	v_add_f32_dpp v112, v112, v112 row_half_mirror row_mask:0xf bank_mask:0xf bound_ctrl:1
	ds_read_b64 v[104:105], v82 offset:47360
	ds_read_b128 v[92:95], v161 offset:6400
	v_add_f32_dpp v110, v110, v110 row_ror:8 row_mask:0xf bank_mask:0xf bound_ctrl:1
	v_add_f32_dpp v112, v112, v112 row_ror:8 row_mask:0xf bank_mask:0xf bound_ctrl:1
	ds_read_b128 v[96:99], v161 offset:39168
	v_pk_mul_f32 v[114:115], v[34:35], v[110:111] op_sel_hi:[1,0]
	v_pk_mul_f32 v[116:117], v[34:35], v[112:113] op_sel_hi:[1,0]
	v_pk_mul_f32 v[118:119], v[36:37], v[110:111] op_sel_hi:[1,0]
	v_pk_mul_f32 v[120:121], v[36:37], v[112:113] op_sel_hi:[1,0]
	v_pk_fma_f32 v[114:115], v[46:47], v[80:81], v[114:115] op_sel_hi:[1,0,1]
	v_pk_fma_f32 v[116:117], v[46:47], v[80:81], v[116:117] op_sel:[0,1,0]
	v_pk_fma_f32 v[118:119], v[48:49], v[80:81], v[118:119] op_sel_hi:[1,0,1]
	v_pk_fma_f32 v[120:121], v[48:49], v[80:81], v[120:121] op_sel:[0,1,0]
	v_pk_fma_f32 v[72:73], v[72:73], v[38:39], v[114:115]
	v_pk_fma_f32 v[76:77], v[76:77], v[38:39], v[116:117]
	v_pk_fma_f32 v[74:75], v[74:75], v[40:41], v[118:119]
	v_pk_fma_f32 v[78:79], v[78:79], v[40:41], v[120:121]
	s_waitcnt lgkmcnt(0)
	v_pk_mul_f32 v[106:107], v[72:73], v[84:85]
	v_pk_mul_f32 v[108:109], v[76:77], v[84:85]
	v_pk_mul_f32 v[122:123], v[72:73], v[42:43]
	v_pk_mul_f32 v[124:125], v[76:77], v[42:43]
	v_pk_fma_f32 v[106:107], v[74:75], v[86:87], v[106:107]
	v_pk_fma_f32 v[108:109], v[78:79], v[86:87], v[108:109]
	v_pk_fma_f32 v[122:123], v[74:75], v[44:45], v[122:123]
	v_pk_fma_f32 v[124:125], v[78:79], v[44:45], v[124:125]
	v_add_f32_e32 v110, v106, v107
	v_add_f32_e32 v112, v108, v109
	v_add_f32_e32 v126, v122, v123
	v_add_f32_e32 v127, v124, v125
	v_add_f32_dpp v110, v110, v110 quad_perm:[1,0,3,2] row_mask:0xf bank_mask:0xf bound_ctrl:1
	v_add_f32_dpp v112, v112, v112 quad_perm:[1,0,3,2] row_mask:0xf bank_mask:0xf bound_ctrl:1
	ds_write_b64 v187, v[126:127] offset:49152
	ds_read_b128 v[30:33], v161 offset:14848
	v_add_f32_dpp v110, v110, v110 quad_perm:[2,3,0,1] row_mask:0xf bank_mask:0xf bound_ctrl:1
	v_add_f32_dpp v112, v112, v112 quad_perm:[2,3,0,1] row_mask:0xf bank_mask:0xf bound_ctrl:1
	ds_read_b128 v[34:37], v161 offset:23040
	ds_read_b128 v[46:49], v161 offset:31232
	v_add_f32_dpp v110, v110, v110 row_half_mirror row_mask:0xf bank_mask:0xf bound_ctrl:1
	v_add_f32_dpp v112, v112, v112 row_half_mirror row_mask:0xf bank_mask:0xf bound_ctrl:1
	ds_read_b64 v[80:81], v82 offset:47616
	ds_read_b128 v[38:41], v161 offset:6656
	v_add_f32_dpp v110, v110, v110 row_ror:8 row_mask:0xf bank_mask:0xf bound_ctrl:1
	v_add_f32_dpp v112, v112, v112 row_ror:8 row_mask:0xf bank_mask:0xf bound_ctrl:1
	ds_read_b128 v[42:45], v161 offset:39424
	v_pk_mul_f32 v[114:115], v[88:89], v[110:111] op_sel_hi:[1,0]
	v_pk_mul_f32 v[116:117], v[88:89], v[112:113] op_sel_hi:[1,0]
	v_pk_mul_f32 v[118:119], v[90:91], v[110:111] op_sel_hi:[1,0]
	v_pk_mul_f32 v[120:121], v[90:91], v[112:113] op_sel_hi:[1,0]
	v_pk_fma_f32 v[114:115], v[100:101], v[104:105], v[114:115] op_sel_hi:[1,0,1]
	v_pk_fma_f32 v[116:117], v[100:101], v[104:105], v[116:117] op_sel:[0,1,0]
	v_pk_fma_f32 v[118:119], v[102:103], v[104:105], v[118:119] op_sel_hi:[1,0,1]
	v_pk_fma_f32 v[120:121], v[102:103], v[104:105], v[120:121] op_sel:[0,1,0]
	v_pk_fma_f32 v[72:73], v[72:73], v[92:93], v[114:115]
	v_pk_fma_f32 v[76:77], v[76:77], v[92:93], v[116:117]
	v_pk_fma_f32 v[74:75], v[74:75], v[94:95], v[118:119]
	v_pk_fma_f32 v[78:79], v[78:79], v[94:95], v[120:121]
	s_waitcnt lgkmcnt(0)
	v_pk_mul_f32 v[106:107], v[72:73], v[30:31]
	v_pk_mul_f32 v[108:109], v[76:77], v[30:31]
	v_pk_mul_f32 v[122:123], v[72:73], v[96:97]
	v_pk_mul_f32 v[124:125], v[76:77], v[96:97]
	v_pk_fma_f32 v[106:107], v[74:75], v[32:33], v[106:107]
	v_pk_fma_f32 v[108:109], v[78:79], v[32:33], v[108:109]
	v_pk_fma_f32 v[122:123], v[74:75], v[98:99], v[122:123]
	v_pk_fma_f32 v[124:125], v[78:79], v[98:99], v[124:125]
	v_add_f32_e32 v110, v106, v107
	v_add_f32_e32 v112, v108, v109
	v_add_f32_e32 v126, v122, v123
	v_add_f32_e32 v127, v124, v125
	v_add_f32_dpp v110, v110, v110 quad_perm:[1,0,3,2] row_mask:0xf bank_mask:0xf bound_ctrl:1
	v_add_f32_dpp v112, v112, v112 quad_perm:[1,0,3,2] row_mask:0xf bank_mask:0xf bound_ctrl:1
	ds_write_b64 v187, v[126:127] offset:51200
	ds_read_b128 v[84:87], v161 offset:15104
	v_add_f32_dpp v110, v110, v110 quad_perm:[2,3,0,1] row_mask:0xf bank_mask:0xf bound_ctrl:1
	v_add_f32_dpp v112, v112, v112 quad_perm:[2,3,0,1] row_mask:0xf bank_mask:0xf bound_ctrl:1
	ds_read_b128 v[88:91], v161 offset:23296
	ds_read_b128 v[100:103], v161 offset:31488
	v_add_f32_dpp v110, v110, v110 row_half_mirror row_mask:0xf bank_mask:0xf bound_ctrl:1
	v_add_f32_dpp v112, v112, v112 row_half_mirror row_mask:0xf bank_mask:0xf bound_ctrl:1
	ds_read_b64 v[104:105], v82 offset:47872
	ds_read_b128 v[92:95], v161 offset:6912
	v_add_f32_dpp v110, v110, v110 row_ror:8 row_mask:0xf bank_mask:0xf bound_ctrl:1
	v_add_f32_dpp v112, v112, v112 row_ror:8 row_mask:0xf bank_mask:0xf bound_ctrl:1
	ds_read_b128 v[96:99], v161 offset:39680
	v_pk_mul_f32 v[114:115], v[34:35], v[110:111] op_sel_hi:[1,0]
	v_pk_mul_f32 v[116:117], v[34:35], v[112:113] op_sel_hi:[1,0]
	v_pk_mul_f32 v[118:119], v[36:37], v[110:111] op_sel_hi:[1,0]
	v_pk_mul_f32 v[120:121], v[36:37], v[112:113] op_sel_hi:[1,0]
	v_pk_fma_f32 v[114:115], v[46:47], v[80:81], v[114:115] op_sel_hi:[1,0,1]
	v_pk_fma_f32 v[116:117], v[46:47], v[80:81], v[116:117] op_sel:[0,1,0]
	v_pk_fma_f32 v[118:119], v[48:49], v[80:81], v[118:119] op_sel_hi:[1,0,1]
	v_pk_fma_f32 v[120:121], v[48:49], v[80:81], v[120:121] op_sel:[0,1,0]
	v_pk_fma_f32 v[72:73], v[72:73], v[38:39], v[114:115]
	v_pk_fma_f32 v[76:77], v[76:77], v[38:39], v[116:117]
	v_pk_fma_f32 v[74:75], v[74:75], v[40:41], v[118:119]
	v_pk_fma_f32 v[78:79], v[78:79], v[40:41], v[120:121]
	s_waitcnt lgkmcnt(0)
	v_pk_mul_f32 v[106:107], v[72:73], v[84:85]
	v_pk_mul_f32 v[108:109], v[76:77], v[84:85]
	v_pk_mul_f32 v[122:123], v[72:73], v[42:43]
	v_pk_mul_f32 v[124:125], v[76:77], v[42:43]
	v_pk_fma_f32 v[106:107], v[74:75], v[86:87], v[106:107]
	v_pk_fma_f32 v[108:109], v[78:79], v[86:87], v[108:109]
	v_pk_fma_f32 v[122:123], v[74:75], v[44:45], v[122:123]
	v_pk_fma_f32 v[124:125], v[78:79], v[44:45], v[124:125]
	v_add_f32_e32 v110, v106, v107
	v_add_f32_e32 v112, v108, v109
	v_add_f32_e32 v126, v122, v123
	v_add_f32_e32 v127, v124, v125
	v_add_f32_dpp v110, v110, v110 quad_perm:[1,0,3,2] row_mask:0xf bank_mask:0xf bound_ctrl:1
	v_add_f32_dpp v112, v112, v112 quad_perm:[1,0,3,2] row_mask:0xf bank_mask:0xf bound_ctrl:1
	ds_write_b64 v187, v[126:127] offset:53248
	ds_read_b128 v[30:33], v161 offset:15360
	v_add_f32_dpp v110, v110, v110 quad_perm:[2,3,0,1] row_mask:0xf bank_mask:0xf bound_ctrl:1
	v_add_f32_dpp v112, v112, v112 quad_perm:[2,3,0,1] row_mask:0xf bank_mask:0xf bound_ctrl:1
	ds_read_b128 v[34:37], v161 offset:23552
	ds_read_b128 v[46:49], v161 offset:31744
	v_add_f32_dpp v110, v110, v110 row_half_mirror row_mask:0xf bank_mask:0xf bound_ctrl:1
	v_add_f32_dpp v112, v112, v112 row_half_mirror row_mask:0xf bank_mask:0xf bound_ctrl:1
	ds_read_b64 v[80:81], v82 offset:48128
	ds_read_b128 v[38:41], v161 offset:7168
	v_add_f32_dpp v110, v110, v110 row_ror:8 row_mask:0xf bank_mask:0xf bound_ctrl:1
	v_add_f32_dpp v112, v112, v112 row_ror:8 row_mask:0xf bank_mask:0xf bound_ctrl:1
	ds_read_b128 v[42:45], v161 offset:39936
	v_pk_mul_f32 v[114:115], v[88:89], v[110:111] op_sel_hi:[1,0]
	v_pk_mul_f32 v[116:117], v[88:89], v[112:113] op_sel_hi:[1,0]
	v_pk_mul_f32 v[118:119], v[90:91], v[110:111] op_sel_hi:[1,0]
	v_pk_mul_f32 v[120:121], v[90:91], v[112:113] op_sel_hi:[1,0]
	v_pk_fma_f32 v[114:115], v[100:101], v[104:105], v[114:115] op_sel_hi:[1,0,1]
	v_pk_fma_f32 v[116:117], v[100:101], v[104:105], v[116:117] op_sel:[0,1,0]
	v_pk_fma_f32 v[118:119], v[102:103], v[104:105], v[118:119] op_sel_hi:[1,0,1]
	v_pk_fma_f32 v[120:121], v[102:103], v[104:105], v[120:121] op_sel:[0,1,0]
	v_pk_fma_f32 v[72:73], v[72:73], v[92:93], v[114:115]
	v_pk_fma_f32 v[76:77], v[76:77], v[92:93], v[116:117]
	v_pk_fma_f32 v[74:75], v[74:75], v[94:95], v[118:119]
	v_pk_fma_f32 v[78:79], v[78:79], v[94:95], v[120:121]
	s_waitcnt lgkmcnt(0)
	v_pk_mul_f32 v[106:107], v[72:73], v[30:31]
	v_pk_mul_f32 v[108:109], v[76:77], v[30:31]
	v_pk_mul_f32 v[122:123], v[72:73], v[96:97]
	v_pk_mul_f32 v[124:125], v[76:77], v[96:97]
	v_pk_fma_f32 v[106:107], v[74:75], v[32:33], v[106:107]
	v_pk_fma_f32 v[108:109], v[78:79], v[32:33], v[108:109]
	v_pk_fma_f32 v[122:123], v[74:75], v[98:99], v[122:123]
	v_pk_fma_f32 v[124:125], v[78:79], v[98:99], v[124:125]
	v_add_f32_e32 v110, v106, v107
	v_add_f32_e32 v112, v108, v109
	v_add_f32_e32 v126, v122, v123
	v_add_f32_e32 v127, v124, v125
	v_add_f32_dpp v110, v110, v110 quad_perm:[1,0,3,2] row_mask:0xf bank_mask:0xf bound_ctrl:1
	v_add_f32_dpp v112, v112, v112 quad_perm:[1,0,3,2] row_mask:0xf bank_mask:0xf bound_ctrl:1
	ds_write_b64 v187, v[126:127] offset:55296
	ds_read_b128 v[84:87], v161 offset:15616
	v_add_f32_dpp v110, v110, v110 quad_perm:[2,3,0,1] row_mask:0xf bank_mask:0xf bound_ctrl:1
	v_add_f32_dpp v112, v112, v112 quad_perm:[2,3,0,1] row_mask:0xf bank_mask:0xf bound_ctrl:1
	ds_read_b128 v[88:91], v161 offset:23808
	ds_read_b128 v[100:103], v161 offset:32000
	v_add_f32_dpp v110, v110, v110 row_half_mirror row_mask:0xf bank_mask:0xf bound_ctrl:1
	v_add_f32_dpp v112, v112, v112 row_half_mirror row_mask:0xf bank_mask:0xf bound_ctrl:1
	ds_read_b64 v[104:105], v82 offset:48384
	ds_read_b128 v[92:95], v161 offset:7424
	v_add_f32_dpp v110, v110, v110 row_ror:8 row_mask:0xf bank_mask:0xf bound_ctrl:1
	v_add_f32_dpp v112, v112, v112 row_ror:8 row_mask:0xf bank_mask:0xf bound_ctrl:1
	ds_read_b128 v[96:99], v161 offset:40192
	v_pk_mul_f32 v[114:115], v[34:35], v[110:111] op_sel_hi:[1,0]
	v_pk_mul_f32 v[116:117], v[34:35], v[112:113] op_sel_hi:[1,0]
	v_pk_mul_f32 v[118:119], v[36:37], v[110:111] op_sel_hi:[1,0]
	v_pk_mul_f32 v[120:121], v[36:37], v[112:113] op_sel_hi:[1,0]
	v_pk_fma_f32 v[114:115], v[46:47], v[80:81], v[114:115] op_sel_hi:[1,0,1]
	v_pk_fma_f32 v[116:117], v[46:47], v[80:81], v[116:117] op_sel:[0,1,0]
	v_pk_fma_f32 v[118:119], v[48:49], v[80:81], v[118:119] op_sel_hi:[1,0,1]
	v_pk_fma_f32 v[120:121], v[48:49], v[80:81], v[120:121] op_sel:[0,1,0]
	v_pk_fma_f32 v[72:73], v[72:73], v[38:39], v[114:115]
	v_pk_fma_f32 v[76:77], v[76:77], v[38:39], v[116:117]
	v_pk_fma_f32 v[74:75], v[74:75], v[40:41], v[118:119]
	v_pk_fma_f32 v[78:79], v[78:79], v[40:41], v[120:121]
	s_waitcnt lgkmcnt(0)
	v_pk_mul_f32 v[106:107], v[72:73], v[84:85]
	v_pk_mul_f32 v[108:109], v[76:77], v[84:85]
	v_pk_mul_f32 v[122:123], v[72:73], v[42:43]
	v_pk_mul_f32 v[124:125], v[76:77], v[42:43]
	v_pk_fma_f32 v[106:107], v[74:75], v[86:87], v[106:107]
	v_pk_fma_f32 v[108:109], v[78:79], v[86:87], v[108:109]
	v_pk_fma_f32 v[122:123], v[74:75], v[44:45], v[122:123]
	v_pk_fma_f32 v[124:125], v[78:79], v[44:45], v[124:125]
	v_add_f32_e32 v110, v106, v107
	v_add_f32_e32 v112, v108, v109
	v_add_f32_e32 v126, v122, v123
	v_add_f32_e32 v127, v124, v125
	v_add_f32_dpp v110, v110, v110 quad_perm:[1,0,3,2] row_mask:0xf bank_mask:0xf bound_ctrl:1
	v_add_f32_dpp v112, v112, v112 quad_perm:[1,0,3,2] row_mask:0xf bank_mask:0xf bound_ctrl:1
	ds_write_b64 v187, v[126:127] offset:57344
	ds_read_b128 v[30:33], v161 offset:15872
	v_add_f32_dpp v110, v110, v110 quad_perm:[2,3,0,1] row_mask:0xf bank_mask:0xf bound_ctrl:1
	v_add_f32_dpp v112, v112, v112 quad_perm:[2,3,0,1] row_mask:0xf bank_mask:0xf bound_ctrl:1
	ds_read_b128 v[34:37], v161 offset:24064
	ds_read_b128 v[46:49], v161 offset:32256
	v_add_f32_dpp v110, v110, v110 row_half_mirror row_mask:0xf bank_mask:0xf bound_ctrl:1
	v_add_f32_dpp v112, v112, v112 row_half_mirror row_mask:0xf bank_mask:0xf bound_ctrl:1
	ds_read_b64 v[80:81], v82 offset:48640
	ds_read_b128 v[38:41], v161 offset:7680
	v_add_f32_dpp v110, v110, v110 row_ror:8 row_mask:0xf bank_mask:0xf bound_ctrl:1
	v_add_f32_dpp v112, v112, v112 row_ror:8 row_mask:0xf bank_mask:0xf bound_ctrl:1
	ds_read_b128 v[42:45], v161 offset:40448
	v_pk_mul_f32 v[114:115], v[88:89], v[110:111] op_sel_hi:[1,0]
	v_pk_mul_f32 v[116:117], v[88:89], v[112:113] op_sel_hi:[1,0]
	v_pk_mul_f32 v[118:119], v[90:91], v[110:111] op_sel_hi:[1,0]
	v_pk_mul_f32 v[120:121], v[90:91], v[112:113] op_sel_hi:[1,0]
	v_pk_fma_f32 v[114:115], v[100:101], v[104:105], v[114:115] op_sel_hi:[1,0,1]
	v_pk_fma_f32 v[116:117], v[100:101], v[104:105], v[116:117] op_sel:[0,1,0]
	v_pk_fma_f32 v[118:119], v[102:103], v[104:105], v[118:119] op_sel_hi:[1,0,1]
	v_pk_fma_f32 v[120:121], v[102:103], v[104:105], v[120:121] op_sel:[0,1,0]
	v_pk_fma_f32 v[72:73], v[72:73], v[92:93], v[114:115]
	v_pk_fma_f32 v[76:77], v[76:77], v[92:93], v[116:117]
	v_pk_fma_f32 v[74:75], v[74:75], v[94:95], v[118:119]
	v_pk_fma_f32 v[78:79], v[78:79], v[94:95], v[120:121]
	s_waitcnt lgkmcnt(0)
	v_pk_mul_f32 v[106:107], v[72:73], v[30:31]
	v_pk_mul_f32 v[108:109], v[76:77], v[30:31]
	v_pk_mul_f32 v[122:123], v[72:73], v[96:97]
	v_pk_mul_f32 v[124:125], v[76:77], v[96:97]
	v_pk_fma_f32 v[106:107], v[74:75], v[32:33], v[106:107]
	v_pk_fma_f32 v[108:109], v[78:79], v[32:33], v[108:109]
	v_pk_fma_f32 v[122:123], v[74:75], v[98:99], v[122:123]
	v_pk_fma_f32 v[124:125], v[78:79], v[98:99], v[124:125]
	v_add_f32_e32 v110, v106, v107
	v_add_f32_e32 v112, v108, v109
	v_add_f32_e32 v126, v122, v123
	v_add_f32_e32 v127, v124, v125
	v_add_f32_dpp v110, v110, v110 quad_perm:[1,0,3,2] row_mask:0xf bank_mask:0xf bound_ctrl:1
	v_add_f32_dpp v112, v112, v112 quad_perm:[1,0,3,2] row_mask:0xf bank_mask:0xf bound_ctrl:1
	ds_write_b64 v187, v[126:127] offset:59392
	ds_read_b128 v[84:87], v161 offset:16128
	v_add_f32_dpp v110, v110, v110 quad_perm:[2,3,0,1] row_mask:0xf bank_mask:0xf bound_ctrl:1
	v_add_f32_dpp v112, v112, v112 quad_perm:[2,3,0,1] row_mask:0xf bank_mask:0xf bound_ctrl:1
	ds_read_b128 v[88:91], v161 offset:24320
	ds_read_b128 v[100:103], v161 offset:32512
	v_add_f32_dpp v110, v110, v110 row_half_mirror row_mask:0xf bank_mask:0xf bound_ctrl:1
	v_add_f32_dpp v112, v112, v112 row_half_mirror row_mask:0xf bank_mask:0xf bound_ctrl:1
	ds_read_b64 v[104:105], v82 offset:48896
	ds_read_b128 v[92:95], v161 offset:7936
	v_add_f32_dpp v110, v110, v110 row_ror:8 row_mask:0xf bank_mask:0xf bound_ctrl:1
	v_add_f32_dpp v112, v112, v112 row_ror:8 row_mask:0xf bank_mask:0xf bound_ctrl:1
	ds_read_b128 v[96:99], v161 offset:40704
	v_pk_mul_f32 v[114:115], v[34:35], v[110:111] op_sel_hi:[1,0]
	v_pk_mul_f32 v[116:117], v[34:35], v[112:113] op_sel_hi:[1,0]
	v_pk_mul_f32 v[118:119], v[36:37], v[110:111] op_sel_hi:[1,0]
	v_pk_mul_f32 v[120:121], v[36:37], v[112:113] op_sel_hi:[1,0]
	v_pk_fma_f32 v[114:115], v[46:47], v[80:81], v[114:115] op_sel_hi:[1,0,1]
	v_pk_fma_f32 v[116:117], v[46:47], v[80:81], v[116:117] op_sel:[0,1,0]
	v_pk_fma_f32 v[118:119], v[48:49], v[80:81], v[118:119] op_sel_hi:[1,0,1]
	v_pk_fma_f32 v[120:121], v[48:49], v[80:81], v[120:121] op_sel:[0,1,0]
	v_pk_fma_f32 v[72:73], v[72:73], v[38:39], v[114:115]
	v_pk_fma_f32 v[76:77], v[76:77], v[38:39], v[116:117]
	v_pk_fma_f32 v[74:75], v[74:75], v[40:41], v[118:119]
	v_pk_fma_f32 v[78:79], v[78:79], v[40:41], v[120:121]
	s_waitcnt lgkmcnt(0)
	v_pk_mul_f32 v[106:107], v[72:73], v[84:85]
	v_pk_mul_f32 v[108:109], v[76:77], v[84:85]
	v_pk_mul_f32 v[122:123], v[72:73], v[42:43]
	v_pk_mul_f32 v[124:125], v[76:77], v[42:43]
	v_pk_fma_f32 v[106:107], v[74:75], v[86:87], v[106:107]
	v_pk_fma_f32 v[108:109], v[78:79], v[86:87], v[108:109]
	v_pk_fma_f32 v[122:123], v[74:75], v[44:45], v[122:123]
	v_pk_fma_f32 v[124:125], v[78:79], v[44:45], v[124:125]
	v_add_f32_e32 v110, v106, v107
	v_add_f32_e32 v112, v108, v109
	v_add_f32_e32 v126, v122, v123
	v_add_f32_e32 v127, v124, v125
	v_add_f32_dpp v110, v110, v110 quad_perm:[1,0,3,2] row_mask:0xf bank_mask:0xf bound_ctrl:1
	v_add_f32_dpp v112, v112, v112 quad_perm:[1,0,3,2] row_mask:0xf bank_mask:0xf bound_ctrl:1
	ds_write_b64 v187, v[126:127] offset:61440
	v_add_f32_dpp v110, v110, v110 quad_perm:[2,3,0,1] row_mask:0xf bank_mask:0xf bound_ctrl:1
	v_add_f32_dpp v112, v112, v112 quad_perm:[2,3,0,1] row_mask:0xf bank_mask:0xf bound_ctrl:1
	s_nop 0
	v_add_f32_dpp v110, v110, v110 row_half_mirror row_mask:0xf bank_mask:0xf bound_ctrl:1
	v_add_f32_dpp v112, v112, v112 row_half_mirror row_mask:0xf bank_mask:0xf bound_ctrl:1
	s_nop 0
	v_add_f32_dpp v110, v110, v110 row_ror:8 row_mask:0xf bank_mask:0xf bound_ctrl:1
	v_add_f32_dpp v112, v112, v112 row_ror:8 row_mask:0xf bank_mask:0xf bound_ctrl:1
	v_pk_mul_f32 v[114:115], v[88:89], v[110:111] op_sel_hi:[1,0]
	v_pk_mul_f32 v[116:117], v[88:89], v[112:113] op_sel_hi:[1,0]
	v_pk_mul_f32 v[118:119], v[90:91], v[110:111] op_sel_hi:[1,0]
	v_pk_mul_f32 v[120:121], v[90:91], v[112:113] op_sel_hi:[1,0]
	v_pk_fma_f32 v[114:115], v[100:101], v[104:105], v[114:115] op_sel_hi:[1,0,1]
	v_pk_fma_f32 v[116:117], v[100:101], v[104:105], v[116:117] op_sel:[0,1,0]
	v_pk_fma_f32 v[118:119], v[102:103], v[104:105], v[118:119] op_sel_hi:[1,0,1]
	v_pk_fma_f32 v[120:121], v[102:103], v[104:105], v[120:121] op_sel:[0,1,0]
	v_pk_fma_f32 v[72:73], v[72:73], v[92:93], v[114:115]
	v_pk_fma_f32 v[76:77], v[76:77], v[92:93], v[116:117]
	v_pk_fma_f32 v[74:75], v[74:75], v[94:95], v[118:119]
	v_pk_fma_f32 v[78:79], v[78:79], v[94:95], v[120:121]
	v_pk_mul_f32 v[122:123], v[72:73], v[96:97]
	v_pk_mul_f32 v[124:125], v[76:77], v[96:97]
	v_pk_fma_f32 v[122:123], v[74:75], v[98:99], v[122:123]
	v_pk_fma_f32 v[124:125], v[78:79], v[98:99], v[124:125]
	v_add_f32_e32 v126, v122, v123
	v_add_f32_e32 v127, v124, v125
	ds_write_b64 v187, v[126:127] offset:63488

.LBB0_3086:
	s_and_saveexec_b64 s[30:31], s[22:23]
	s_cbranch_execz .LBB0_3089
	ds_read_b128 v[30:33], v161 offset:8192
	ds_read_b128 v[34:37], v161 offset:16384
	ds_read_b128 v[46:49], v161 offset:24576
	ds_read_b64 v[80:81], v82 offset:40960
	ds_read_b128 v[38:41], v161
	ds_read_b128 v[42:45], v161 offset:32768
	s_waitcnt lgkmcnt(0)
	v_pk_mul_f32 v[106:107], v[72:73], v[30:31]
	v_pk_mul_f32 v[108:109], v[76:77], v[30:31]
	v_pk_fma_f32 v[106:107], v[74:75], v[32:33], v[106:107]
	v_pk_fma_f32 v[108:109], v[78:79], v[32:33], v[108:109]
	v_add_f32_e32 v110, v106, v107
	v_add_f32_e32 v112, v108, v109
	s_nop 0
	v_add_f32_dpp v110, v110, v110 quad_perm:[1,0,3,2] row_mask:0xf bank_mask:0xf bound_ctrl:1
	v_add_f32_dpp v112, v112, v112 quad_perm:[1,0,3,2] row_mask:0xf bank_mask:0xf bound_ctrl:1
	ds_read_b128 v[84:87], v161 offset:8448
	ds_read_b128 v[88:91], v161 offset:16640
	v_add_f32_dpp v110, v110, v110 quad_perm:[2,3,0,1] row_mask:0xf bank_mask:0xf bound_ctrl:1
	v_add_f32_dpp v112, v112, v112 quad_perm:[2,3,0,1] row_mask:0xf bank_mask:0xf bound_ctrl:1
	ds_read_b128 v[100:103], v161 offset:24832
	ds_read_b64 v[104:105], v82 offset:41216
	v_add_f32_dpp v110, v110, v110 row_half_mirror row_mask:0xf bank_mask:0xf bound_ctrl:1
	v_add_f32_dpp v112, v112, v112 row_half_mirror row_mask:0xf bank_mask:0xf bound_ctrl:1
	ds_read_b128 v[92:95], v161 offset:256
	v_add_f32_dpp v110, v110, v110 row_ror:8 row_mask:0xf bank_mask:0xf bound_ctrl:1
	v_add_f32_dpp v112, v112, v112 row_ror:8 row_mask:0xf bank_mask:0xf bound_ctrl:1
	ds_read_b128 v[96:99], v161 offset:33024
	v_pk_mul_f32 v[114:115], v[34:35], v[110:111] op_sel_hi:[1,0]
	v_pk_mul_f32 v[116:117], v[34:35], v[112:113] op_sel_hi:[1,0]
	v_pk_mul_f32 v[118:119], v[36:37], v[110:111] op_sel_hi:[1,0]
	v_pk_mul_f32 v[120:121], v[36:37], v[112:113] op_sel_hi:[1,0]
	v_pk_fma_f32 v[114:115], v[46:47], v[80:81], v[114:115] op_sel_hi:[1,0,1]
	v_pk_fma_f32 v[116:117], v[46:47], v[80:81], v[116:117] op_sel:[0,1,0]
	v_pk_fma_f32 v[118:119], v[48:49], v[80:81], v[118:119] op_sel_hi:[1,0,1]
	v_pk_fma_f32 v[120:121], v[48:49], v[80:81], v[120:121] op_sel:[0,1,0]
	v_pk_fma_f32 v[72:73], v[72:73], v[38:39], v[114:115]
	v_pk_fma_f32 v[76:77], v[76:77], v[38:39], v[116:117]
	v_pk_fma_f32 v[74:75], v[74:75], v[40:41], v[118:119]
	v_pk_fma_f32 v[78:79], v[78:79], v[40:41], v[120:121]
	s_waitcnt lgkmcnt(0)
	v_pk_mul_f32 v[106:107], v[72:73], v[84:85]
	v_pk_mul_f32 v[108:109], v[76:77], v[84:85]
	v_pk_mul_f32 v[122:123], v[72:73], v[42:43]
	v_pk_mul_f32 v[124:125], v[76:77], v[42:43]
	v_pk_fma_f32 v[106:107], v[74:75], v[86:87], v[106:107]
	v_pk_fma_f32 v[108:109], v[78:79], v[86:87], v[108:109]
	v_pk_fma_f32 v[122:123], v[74:75], v[44:45], v[122:123]
	v_pk_fma_f32 v[124:125], v[78:79], v[44:45], v[124:125]
	v_add_f32_e32 v110, v106, v107
	v_add_f32_e32 v112, v108, v109
	v_add_f32_e32 v126, v122, v123
	v_add_f32_e32 v127, v124, v125
	v_add_f32_dpp v110, v110, v110 quad_perm:[1,0,3,2] row_mask:0xf bank_mask:0xf bound_ctrl:1
	v_add_f32_dpp v112, v112, v112 quad_perm:[1,0,3,2] row_mask:0xf bank_mask:0xf bound_ctrl:1
	ds_write_b64 v187, v[126:127]
	ds_read_b128 v[30:33], v161 offset:8704
	v_add_f32_dpp v110, v110, v110 quad_perm:[2,3,0,1] row_mask:0xf bank_mask:0xf bound_ctrl:1
	v_add_f32_dpp v112, v112, v112 quad_perm:[2,3,0,1] row_mask:0xf bank_mask:0xf bound_ctrl:1
	ds_read_b128 v[34:37], v161 offset:16896
	ds_read_b128 v[46:49], v161 offset:25088
	v_add_f32_dpp v110, v110, v110 row_half_mirror row_mask:0xf bank_mask:0xf bound_ctrl:1
	v_add_f32_dpp v112, v112, v112 row_half_mirror row_mask:0xf bank_mask:0xf bound_ctrl:1
	ds_read_b64 v[80:81], v82 offset:41472
	ds_read_b128 v[38:41], v161 offset:512
	v_add_f32_dpp v110, v110, v110 row_ror:8 row_mask:0xf bank_mask:0xf bound_ctrl:1
	v_add_f32_dpp v112, v112, v112 row_ror:8 row_mask:0xf bank_mask:0xf bound_ctrl:1
	ds_read_b128 v[42:45], v161 offset:33280
	v_pk_mul_f32 v[114:115], v[88:89], v[110:111] op_sel_hi:[1,0]
	v_pk_mul_f32 v[116:117], v[88:89], v[112:113] op_sel_hi:[1,0]
	v_pk_mul_f32 v[118:119], v[90:91], v[110:111] op_sel_hi:[1,0]
	v_pk_mul_f32 v[120:121], v[90:91], v[112:113] op_sel_hi:[1,0]
	v_pk_fma_f32 v[114:115], v[100:101], v[104:105], v[114:115] op_sel_hi:[1,0,1]
	v_pk_fma_f32 v[116:117], v[100:101], v[104:105], v[116:117] op_sel:[0,1,0]
	v_pk_fma_f32 v[118:119], v[102:103], v[104:105], v[118:119] op_sel_hi:[1,0,1]
	v_pk_fma_f32 v[120:121], v[102:103], v[104:105], v[120:121] op_sel:[0,1,0]
	v_pk_fma_f32 v[72:73], v[72:73], v[92:93], v[114:115]
	v_pk_fma_f32 v[76:77], v[76:77], v[92:93], v[116:117]
	v_pk_fma_f32 v[74:75], v[74:75], v[94:95], v[118:119]
	v_pk_fma_f32 v[78:79], v[78:79], v[94:95], v[120:121]
	s_waitcnt lgkmcnt(0)
	v_pk_mul_f32 v[106:107], v[72:73], v[30:31]
	v_pk_mul_f32 v[108:109], v[76:77], v[30:31]
	v_pk_mul_f32 v[122:123], v[72:73], v[96:97]
	v_pk_mul_f32 v[124:125], v[76:77], v[96:97]
	v_pk_fma_f32 v[106:107], v[74:75], v[32:33], v[106:107]
	v_pk_fma_f32 v[108:109], v[78:79], v[32:33], v[108:109]
	v_pk_fma_f32 v[122:123], v[74:75], v[98:99], v[122:123]
	v_pk_fma_f32 v[124:125], v[78:79], v[98:99], v[124:125]
	v_add_f32_e32 v110, v106, v107
	v_add_f32_e32 v112, v108, v109
	v_add_f32_e32 v126, v122, v123
	v_add_f32_e32 v127, v124, v125
	v_add_f32_dpp v110, v110, v110 quad_perm:[1,0,3,2] row_mask:0xf bank_mask:0xf bound_ctrl:1
	v_add_f32_dpp v112, v112, v112 quad_perm:[1,0,3,2] row_mask:0xf bank_mask:0xf bound_ctrl:1
	ds_write_b64 v187, v[126:127] offset:2048
	ds_read_b128 v[84:87], v161 offset:8960
	v_add_f32_dpp v110, v110, v110 quad_perm:[2,3,0,1] row_mask:0xf bank_mask:0xf bound_ctrl:1
	v_add_f32_dpp v112, v112, v112 quad_perm:[2,3,0,1] row_mask:0xf bank_mask:0xf bound_ctrl:1
	ds_read_b128 v[88:91], v161 offset:17152
	ds_read_b128 v[100:103], v161 offset:25344
	v_add_f32_dpp v110, v110, v110 row_half_mirror row_mask:0xf bank_mask:0xf bound_ctrl:1
	v_add_f32_dpp v112, v112, v112 row_half_mirror row_mask:0xf bank_mask:0xf bound_ctrl:1
	ds_read_b64 v[104:105], v82 offset:41728
	ds_read_b128 v[92:95], v161 offset:768
	v_add_f32_dpp v110, v110, v110 row_ror:8 row_mask:0xf bank_mask:0xf bound_ctrl:1
	v_add_f32_dpp v112, v112, v112 row_ror:8 row_mask:0xf bank_mask:0xf bound_ctrl:1
	ds_read_b128 v[96:99], v161 offset:33536
	v_pk_mul_f32 v[114:115], v[34:35], v[110:111] op_sel_hi:[1,0]
	v_pk_mul_f32 v[116:117], v[34:35], v[112:113] op_sel_hi:[1,0]
	v_pk_mul_f32 v[118:119], v[36:37], v[110:111] op_sel_hi:[1,0]
	v_pk_mul_f32 v[120:121], v[36:37], v[112:113] op_sel_hi:[1,0]
	v_pk_fma_f32 v[114:115], v[46:47], v[80:81], v[114:115] op_sel_hi:[1,0,1]
	v_pk_fma_f32 v[116:117], v[46:47], v[80:81], v[116:117] op_sel:[0,1,0]
	v_pk_fma_f32 v[118:119], v[48:49], v[80:81], v[118:119] op_sel_hi:[1,0,1]
	v_pk_fma_f32 v[120:121], v[48:49], v[80:81], v[120:121] op_sel:[0,1,0]
	v_pk_fma_f32 v[72:73], v[72:73], v[38:39], v[114:115]
	v_pk_fma_f32 v[76:77], v[76:77], v[38:39], v[116:117]
	v_pk_fma_f32 v[74:75], v[74:75], v[40:41], v[118:119]
	v_pk_fma_f32 v[78:79], v[78:79], v[40:41], v[120:121]
	s_waitcnt lgkmcnt(0)
	v_pk_mul_f32 v[106:107], v[72:73], v[84:85]
	v_pk_mul_f32 v[108:109], v[76:77], v[84:85]
	v_pk_mul_f32 v[122:123], v[72:73], v[42:43]
	v_pk_mul_f32 v[124:125], v[76:77], v[42:43]
	v_pk_fma_f32 v[106:107], v[74:75], v[86:87], v[106:107]
	v_pk_fma_f32 v[108:109], v[78:79], v[86:87], v[108:109]
	v_pk_fma_f32 v[122:123], v[74:75], v[44:45], v[122:123]
	v_pk_fma_f32 v[124:125], v[78:79], v[44:45], v[124:125]
	v_add_f32_e32 v110, v106, v107
	v_add_f32_e32 v112, v108, v109
	v_add_f32_e32 v126, v122, v123
	v_add_f32_e32 v127, v124, v125
	v_add_f32_dpp v110, v110, v110 quad_perm:[1,0,3,2] row_mask:0xf bank_mask:0xf bound_ctrl:1
	v_add_f32_dpp v112, v112, v112 quad_perm:[1,0,3,2] row_mask:0xf bank_mask:0xf bound_ctrl:1
	ds_write_b64 v187, v[126:127] offset:4096
	ds_read_b128 v[30:33], v161 offset:9216
	v_add_f32_dpp v110, v110, v110 quad_perm:[2,3,0,1] row_mask:0xf bank_mask:0xf bound_ctrl:1
	v_add_f32_dpp v112, v112, v112 quad_perm:[2,3,0,1] row_mask:0xf bank_mask:0xf bound_ctrl:1
	ds_read_b128 v[34:37], v161 offset:17408
	ds_read_b128 v[46:49], v161 offset:25600
	v_add_f32_dpp v110, v110, v110 row_half_mirror row_mask:0xf bank_mask:0xf bound_ctrl:1
	v_add_f32_dpp v112, v112, v112 row_half_mirror row_mask:0xf bank_mask:0xf bound_ctrl:1
	ds_read_b64 v[80:81], v82 offset:41984
	ds_read_b128 v[38:41], v161 offset:1024
	v_add_f32_dpp v110, v110, v110 row_ror:8 row_mask:0xf bank_mask:0xf bound_ctrl:1
	v_add_f32_dpp v112, v112, v112 row_ror:8 row_mask:0xf bank_mask:0xf bound_ctrl:1
	ds_read_b128 v[42:45], v161 offset:33792
	v_pk_mul_f32 v[114:115], v[88:89], v[110:111] op_sel_hi:[1,0]
	v_pk_mul_f32 v[116:117], v[88:89], v[112:113] op_sel_hi:[1,0]
	v_pk_mul_f32 v[118:119], v[90:91], v[110:111] op_sel_hi:[1,0]
	v_pk_mul_f32 v[120:121], v[90:91], v[112:113] op_sel_hi:[1,0]
	v_pk_fma_f32 v[114:115], v[100:101], v[104:105], v[114:115] op_sel_hi:[1,0,1]
	v_pk_fma_f32 v[116:117], v[100:101], v[104:105], v[116:117] op_sel:[0,1,0]
	v_pk_fma_f32 v[118:119], v[102:103], v[104:105], v[118:119] op_sel_hi:[1,0,1]
	v_pk_fma_f32 v[120:121], v[102:103], v[104:105], v[120:121] op_sel:[0,1,0]
	v_pk_fma_f32 v[72:73], v[72:73], v[92:93], v[114:115]
	v_pk_fma_f32 v[76:77], v[76:77], v[92:93], v[116:117]
	v_pk_fma_f32 v[74:75], v[74:75], v[94:95], v[118:119]
	v_pk_fma_f32 v[78:79], v[78:79], v[94:95], v[120:121]
	s_waitcnt lgkmcnt(0)
	v_pk_mul_f32 v[106:107], v[72:73], v[30:31]
	v_pk_mul_f32 v[108:109], v[76:77], v[30:31]
	v_pk_mul_f32 v[122:123], v[72:73], v[96:97]
	v_pk_mul_f32 v[124:125], v[76:77], v[96:97]
	v_pk_fma_f32 v[106:107], v[74:75], v[32:33], v[106:107]
	v_pk_fma_f32 v[108:109], v[78:79], v[32:33], v[108:109]
	v_pk_fma_f32 v[122:123], v[74:75], v[98:99], v[122:123]
	v_pk_fma_f32 v[124:125], v[78:79], v[98:99], v[124:125]
	v_add_f32_e32 v110, v106, v107
	v_add_f32_e32 v112, v108, v109
	v_add_f32_e32 v126, v122, v123
	v_add_f32_e32 v127, v124, v125
	v_add_f32_dpp v110, v110, v110 quad_perm:[1,0,3,2] row_mask:0xf bank_mask:0xf bound_ctrl:1
	v_add_f32_dpp v112, v112, v112 quad_perm:[1,0,3,2] row_mask:0xf bank_mask:0xf bound_ctrl:1
	ds_write_b64 v187, v[126:127] offset:6144
	ds_read_b128 v[84:87], v161 offset:9472
	v_add_f32_dpp v110, v110, v110 quad_perm:[2,3,0,1] row_mask:0xf bank_mask:0xf bound_ctrl:1
	v_add_f32_dpp v112, v112, v112 quad_perm:[2,3,0,1] row_mask:0xf bank_mask:0xf bound_ctrl:1
	ds_read_b128 v[88:91], v161 offset:17664
	ds_read_b128 v[100:103], v161 offset:25856
	v_add_f32_dpp v110, v110, v110 row_half_mirror row_mask:0xf bank_mask:0xf bound_ctrl:1
	v_add_f32_dpp v112, v112, v112 row_half_mirror row_mask:0xf bank_mask:0xf bound_ctrl:1
	ds_read_b64 v[104:105], v82 offset:42240
	ds_read_b128 v[92:95], v161 offset:1280
	v_add_f32_dpp v110, v110, v110 row_ror:8 row_mask:0xf bank_mask:0xf bound_ctrl:1
	v_add_f32_dpp v112, v112, v112 row_ror:8 row_mask:0xf bank_mask:0xf bound_ctrl:1
	ds_read_b128 v[96:99], v161 offset:34048
	v_pk_mul_f32 v[114:115], v[34:35], v[110:111] op_sel_hi:[1,0]
	v_pk_mul_f32 v[116:117], v[34:35], v[112:113] op_sel_hi:[1,0]
	v_pk_mul_f32 v[118:119], v[36:37], v[110:111] op_sel_hi:[1,0]
	v_pk_mul_f32 v[120:121], v[36:37], v[112:113] op_sel_hi:[1,0]
	v_pk_fma_f32 v[114:115], v[46:47], v[80:81], v[114:115] op_sel_hi:[1,0,1]
	v_pk_fma_f32 v[116:117], v[46:47], v[80:81], v[116:117] op_sel:[0,1,0]
	v_pk_fma_f32 v[118:119], v[48:49], v[80:81], v[118:119] op_sel_hi:[1,0,1]
	v_pk_fma_f32 v[120:121], v[48:49], v[80:81], v[120:121] op_sel:[0,1,0]
	v_pk_fma_f32 v[72:73], v[72:73], v[38:39], v[114:115]
	v_pk_fma_f32 v[76:77], v[76:77], v[38:39], v[116:117]
	v_pk_fma_f32 v[74:75], v[74:75], v[40:41], v[118:119]
	v_pk_fma_f32 v[78:79], v[78:79], v[40:41], v[120:121]
	s_waitcnt lgkmcnt(0)
	v_pk_mul_f32 v[106:107], v[72:73], v[84:85]
	v_pk_mul_f32 v[108:109], v[76:77], v[84:85]
	v_pk_mul_f32 v[122:123], v[72:73], v[42:43]
	v_pk_mul_f32 v[124:125], v[76:77], v[42:43]
	v_pk_fma_f32 v[106:107], v[74:75], v[86:87], v[106:107]
	v_pk_fma_f32 v[108:109], v[78:79], v[86:87], v[108:109]
	v_pk_fma_f32 v[122:123], v[74:75], v[44:45], v[122:123]
	v_pk_fma_f32 v[124:125], v[78:79], v[44:45], v[124:125]
	v_add_f32_e32 v110, v106, v107
	v_add_f32_e32 v112, v108, v109
	v_add_f32_e32 v126, v122, v123
	v_add_f32_e32 v127, v124, v125
	v_add_f32_dpp v110, v110, v110 quad_perm:[1,0,3,2] row_mask:0xf bank_mask:0xf bound_ctrl:1
	v_add_f32_dpp v112, v112, v112 quad_perm:[1,0,3,2] row_mask:0xf bank_mask:0xf bound_ctrl:1
	ds_write_b64 v187, v[126:127] offset:8192
	ds_read_b128 v[30:33], v161 offset:9728
	v_add_f32_dpp v110, v110, v110 quad_perm:[2,3,0,1] row_mask:0xf bank_mask:0xf bound_ctrl:1
	v_add_f32_dpp v112, v112, v112 quad_perm:[2,3,0,1] row_mask:0xf bank_mask:0xf bound_ctrl:1
	ds_read_b128 v[34:37], v161 offset:17920
	ds_read_b128 v[46:49], v161 offset:26112
	v_add_f32_dpp v110, v110, v110 row_half_mirror row_mask:0xf bank_mask:0xf bound_ctrl:1
	v_add_f32_dpp v112, v112, v112 row_half_mirror row_mask:0xf bank_mask:0xf bound_ctrl:1
	ds_read_b64 v[80:81], v82 offset:42496
	ds_read_b128 v[38:41], v161 offset:1536
	v_add_f32_dpp v110, v110, v110 row_ror:8 row_mask:0xf bank_mask:0xf bound_ctrl:1
	v_add_f32_dpp v112, v112, v112 row_ror:8 row_mask:0xf bank_mask:0xf bound_ctrl:1
	ds_read_b128 v[42:45], v161 offset:34304
	v_pk_mul_f32 v[114:115], v[88:89], v[110:111] op_sel_hi:[1,0]
	v_pk_mul_f32 v[116:117], v[88:89], v[112:113] op_sel_hi:[1,0]
	v_pk_mul_f32 v[118:119], v[90:91], v[110:111] op_sel_hi:[1,0]
	v_pk_mul_f32 v[120:121], v[90:91], v[112:113] op_sel_hi:[1,0]
	v_pk_fma_f32 v[114:115], v[100:101], v[104:105], v[114:115] op_sel_hi:[1,0,1]
	v_pk_fma_f32 v[116:117], v[100:101], v[104:105], v[116:117] op_sel:[0,1,0]
	v_pk_fma_f32 v[118:119], v[102:103], v[104:105], v[118:119] op_sel_hi:[1,0,1]
	v_pk_fma_f32 v[120:121], v[102:103], v[104:105], v[120:121] op_sel:[0,1,0]
	v_pk_fma_f32 v[72:73], v[72:73], v[92:93], v[114:115]
	v_pk_fma_f32 v[76:77], v[76:77], v[92:93], v[116:117]
	v_pk_fma_f32 v[74:75], v[74:75], v[94:95], v[118:119]
	v_pk_fma_f32 v[78:79], v[78:79], v[94:95], v[120:121]
	s_waitcnt lgkmcnt(0)
	v_pk_mul_f32 v[106:107], v[72:73], v[30:31]
	v_pk_mul_f32 v[108:109], v[76:77], v[30:31]
	v_pk_mul_f32 v[122:123], v[72:73], v[96:97]
	v_pk_mul_f32 v[124:125], v[76:77], v[96:97]
	v_pk_fma_f32 v[106:107], v[74:75], v[32:33], v[106:107]
	v_pk_fma_f32 v[108:109], v[78:79], v[32:33], v[108:109]
	v_pk_fma_f32 v[122:123], v[74:75], v[98:99], v[122:123]
	v_pk_fma_f32 v[124:125], v[78:79], v[98:99], v[124:125]
	v_add_f32_e32 v110, v106, v107
	v_add_f32_e32 v112, v108, v109
	v_add_f32_e32 v126, v122, v123
	v_add_f32_e32 v127, v124, v125
	v_add_f32_dpp v110, v110, v110 quad_perm:[1,0,3,2] row_mask:0xf bank_mask:0xf bound_ctrl:1
	v_add_f32_dpp v112, v112, v112 quad_perm:[1,0,3,2] row_mask:0xf bank_mask:0xf bound_ctrl:1
	ds_write_b64 v187, v[126:127] offset:10240
	ds_read_b128 v[84:87], v161 offset:9984
	v_add_f32_dpp v110, v110, v110 quad_perm:[2,3,0,1] row_mask:0xf bank_mask:0xf bound_ctrl:1
	v_add_f32_dpp v112, v112, v112 quad_perm:[2,3,0,1] row_mask:0xf bank_mask:0xf bound_ctrl:1
	ds_read_b128 v[88:91], v161 offset:18176
	ds_read_b128 v[100:103], v161 offset:26368
	v_add_f32_dpp v110, v110, v110 row_half_mirror row_mask:0xf bank_mask:0xf bound_ctrl:1
	v_add_f32_dpp v112, v112, v112 row_half_mirror row_mask:0xf bank_mask:0xf bound_ctrl:1
	ds_read_b64 v[104:105], v82 offset:42752
	ds_read_b128 v[92:95], v161 offset:1792
	v_add_f32_dpp v110, v110, v110 row_ror:8 row_mask:0xf bank_mask:0xf bound_ctrl:1
	v_add_f32_dpp v112, v112, v112 row_ror:8 row_mask:0xf bank_mask:0xf bound_ctrl:1
	ds_read_b128 v[96:99], v161 offset:34560
	v_pk_mul_f32 v[114:115], v[34:35], v[110:111] op_sel_hi:[1,0]
	v_pk_mul_f32 v[116:117], v[34:35], v[112:113] op_sel_hi:[1,0]
	v_pk_mul_f32 v[118:119], v[36:37], v[110:111] op_sel_hi:[1,0]
	v_pk_mul_f32 v[120:121], v[36:37], v[112:113] op_sel_hi:[1,0]
	v_pk_fma_f32 v[114:115], v[46:47], v[80:81], v[114:115] op_sel_hi:[1,0,1]
	v_pk_fma_f32 v[116:117], v[46:47], v[80:81], v[116:117] op_sel:[0,1,0]
	v_pk_fma_f32 v[118:119], v[48:49], v[80:81], v[118:119] op_sel_hi:[1,0,1]
	v_pk_fma_f32 v[120:121], v[48:49], v[80:81], v[120:121] op_sel:[0,1,0]
	v_pk_fma_f32 v[72:73], v[72:73], v[38:39], v[114:115]
	v_pk_fma_f32 v[76:77], v[76:77], v[38:39], v[116:117]
	v_pk_fma_f32 v[74:75], v[74:75], v[40:41], v[118:119]
	v_pk_fma_f32 v[78:79], v[78:79], v[40:41], v[120:121]
	s_waitcnt lgkmcnt(0)
	v_pk_mul_f32 v[106:107], v[72:73], v[84:85]
	v_pk_mul_f32 v[108:109], v[76:77], v[84:85]
	v_pk_mul_f32 v[122:123], v[72:73], v[42:43]
	v_pk_mul_f32 v[124:125], v[76:77], v[42:43]
	v_pk_fma_f32 v[106:107], v[74:75], v[86:87], v[106:107]
	v_pk_fma_f32 v[108:109], v[78:79], v[86:87], v[108:109]
	v_pk_fma_f32 v[122:123], v[74:75], v[44:45], v[122:123]
	v_pk_fma_f32 v[124:125], v[78:79], v[44:45], v[124:125]
	v_add_f32_e32 v110, v106, v107
	v_add_f32_e32 v112, v108, v109
	v_add_f32_e32 v126, v122, v123
	v_add_f32_e32 v127, v124, v125
	v_add_f32_dpp v110, v110, v110 quad_perm:[1,0,3,2] row_mask:0xf bank_mask:0xf bound_ctrl:1
	v_add_f32_dpp v112, v112, v112 quad_perm:[1,0,3,2] row_mask:0xf bank_mask:0xf bound_ctrl:1
	ds_write_b64 v187, v[126:127] offset:12288
	ds_read_b128 v[30:33], v161 offset:10240
	v_add_f32_dpp v110, v110, v110 quad_perm:[2,3,0,1] row_mask:0xf bank_mask:0xf bound_ctrl:1
	v_add_f32_dpp v112, v112, v112 quad_perm:[2,3,0,1] row_mask:0xf bank_mask:0xf bound_ctrl:1
	ds_read_b128 v[34:37], v161 offset:18432
	ds_read_b128 v[46:49], v161 offset:26624
	v_add_f32_dpp v110, v110, v110 row_half_mirror row_mask:0xf bank_mask:0xf bound_ctrl:1
	v_add_f32_dpp v112, v112, v112 row_half_mirror row_mask:0xf bank_mask:0xf bound_ctrl:1
	ds_read_b64 v[80:81], v82 offset:43008
	ds_read_b128 v[38:41], v161 offset:2048
	v_add_f32_dpp v110, v110, v110 row_ror:8 row_mask:0xf bank_mask:0xf bound_ctrl:1
	v_add_f32_dpp v112, v112, v112 row_ror:8 row_mask:0xf bank_mask:0xf bound_ctrl:1
	ds_read_b128 v[42:45], v161 offset:34816
	v_pk_mul_f32 v[114:115], v[88:89], v[110:111] op_sel_hi:[1,0]
	v_pk_mul_f32 v[116:117], v[88:89], v[112:113] op_sel_hi:[1,0]
	v_pk_mul_f32 v[118:119], v[90:91], v[110:111] op_sel_hi:[1,0]
	v_pk_mul_f32 v[120:121], v[90:91], v[112:113] op_sel_hi:[1,0]
	v_pk_fma_f32 v[114:115], v[100:101], v[104:105], v[114:115] op_sel_hi:[1,0,1]
	v_pk_fma_f32 v[116:117], v[100:101], v[104:105], v[116:117] op_sel:[0,1,0]
	v_pk_fma_f32 v[118:119], v[102:103], v[104:105], v[118:119] op_sel_hi:[1,0,1]
	v_pk_fma_f32 v[120:121], v[102:103], v[104:105], v[120:121] op_sel:[0,1,0]
	v_pk_fma_f32 v[72:73], v[72:73], v[92:93], v[114:115]
	v_pk_fma_f32 v[76:77], v[76:77], v[92:93], v[116:117]
	v_pk_fma_f32 v[74:75], v[74:75], v[94:95], v[118:119]
	v_pk_fma_f32 v[78:79], v[78:79], v[94:95], v[120:121]
	s_waitcnt lgkmcnt(0)
	v_pk_mul_f32 v[106:107], v[72:73], v[30:31]
	v_pk_mul_f32 v[108:109], v[76:77], v[30:31]
	v_pk_mul_f32 v[122:123], v[72:73], v[96:97]
	v_pk_mul_f32 v[124:125], v[76:77], v[96:97]
	v_pk_fma_f32 v[106:107], v[74:75], v[32:33], v[106:107]
	v_pk_fma_f32 v[108:109], v[78:79], v[32:33], v[108:109]
	v_pk_fma_f32 v[122:123], v[74:75], v[98:99], v[122:123]
	v_pk_fma_f32 v[124:125], v[78:79], v[98:99], v[124:125]
	v_add_f32_e32 v110, v106, v107
	v_add_f32_e32 v112, v108, v109
	v_add_f32_e32 v126, v122, v123
	v_add_f32_e32 v127, v124, v125
	v_add_f32_dpp v110, v110, v110 quad_perm:[1,0,3,2] row_mask:0xf bank_mask:0xf bound_ctrl:1
	v_add_f32_dpp v112, v112, v112 quad_perm:[1,0,3,2] row_mask:0xf bank_mask:0xf bound_ctrl:1
	ds_write_b64 v187, v[126:127] offset:14336
	ds_read_b128 v[84:87], v161 offset:10496
	v_add_f32_dpp v110, v110, v110 quad_perm:[2,3,0,1] row_mask:0xf bank_mask:0xf bound_ctrl:1
	v_add_f32_dpp v112, v112, v112 quad_perm:[2,3,0,1] row_mask:0xf bank_mask:0xf bound_ctrl:1
	ds_read_b128 v[88:91], v161 offset:18688
	ds_read_b128 v[100:103], v161 offset:26880
	v_add_f32_dpp v110, v110, v110 row_half_mirror row_mask:0xf bank_mask:0xf bound_ctrl:1
	v_add_f32_dpp v112, v112, v112 row_half_mirror row_mask:0xf bank_mask:0xf bound_ctrl:1
	ds_read_b64 v[104:105], v82 offset:43264
	ds_read_b128 v[92:95], v161 offset:2304
	v_add_f32_dpp v110, v110, v110 row_ror:8 row_mask:0xf bank_mask:0xf bound_ctrl:1
	v_add_f32_dpp v112, v112, v112 row_ror:8 row_mask:0xf bank_mask:0xf bound_ctrl:1
	ds_read_b128 v[96:99], v161 offset:35072
	v_pk_mul_f32 v[114:115], v[34:35], v[110:111] op_sel_hi:[1,0]
	v_pk_mul_f32 v[116:117], v[34:35], v[112:113] op_sel_hi:[1,0]
	v_pk_mul_f32 v[118:119], v[36:37], v[110:111] op_sel_hi:[1,0]
	v_pk_mul_f32 v[120:121], v[36:37], v[112:113] op_sel_hi:[1,0]
	v_pk_fma_f32 v[114:115], v[46:47], v[80:81], v[114:115] op_sel_hi:[1,0,1]
	v_pk_fma_f32 v[116:117], v[46:47], v[80:81], v[116:117] op_sel:[0,1,0]
	v_pk_fma_f32 v[118:119], v[48:49], v[80:81], v[118:119] op_sel_hi:[1,0,1]
	v_pk_fma_f32 v[120:121], v[48:49], v[80:81], v[120:121] op_sel:[0,1,0]
	v_pk_fma_f32 v[72:73], v[72:73], v[38:39], v[114:115]
	v_pk_fma_f32 v[76:77], v[76:77], v[38:39], v[116:117]
	v_pk_fma_f32 v[74:75], v[74:75], v[40:41], v[118:119]
	v_pk_fma_f32 v[78:79], v[78:79], v[40:41], v[120:121]
	s_waitcnt lgkmcnt(0)
	v_pk_mul_f32 v[106:107], v[72:73], v[84:85]
	v_pk_mul_f32 v[108:109], v[76:77], v[84:85]
	v_pk_mul_f32 v[122:123], v[72:73], v[42:43]
	v_pk_mul_f32 v[124:125], v[76:77], v[42:43]
	v_pk_fma_f32 v[106:107], v[74:75], v[86:87], v[106:107]
	v_pk_fma_f32 v[108:109], v[78:79], v[86:87], v[108:109]
	v_pk_fma_f32 v[122:123], v[74:75], v[44:45], v[122:123]
	v_pk_fma_f32 v[124:125], v[78:79], v[44:45], v[124:125]
	v_add_f32_e32 v110, v106, v107
	v_add_f32_e32 v112, v108, v109
	v_add_f32_e32 v126, v122, v123
	v_add_f32_e32 v127, v124, v125
	v_add_f32_dpp v110, v110, v110 quad_perm:[1,0,3,2] row_mask:0xf bank_mask:0xf bound_ctrl:1
	v_add_f32_dpp v112, v112, v112 quad_perm:[1,0,3,2] row_mask:0xf bank_mask:0xf bound_ctrl:1
	ds_write_b64 v187, v[126:127] offset:16384
	ds_read_b128 v[30:33], v161 offset:10752
	v_add_f32_dpp v110, v110, v110 quad_perm:[2,3,0,1] row_mask:0xf bank_mask:0xf bound_ctrl:1
	v_add_f32_dpp v112, v112, v112 quad_perm:[2,3,0,1] row_mask:0xf bank_mask:0xf bound_ctrl:1
	ds_read_b128 v[34:37], v161 offset:18944
	ds_read_b128 v[46:49], v161 offset:27136
	v_add_f32_dpp v110, v110, v110 row_half_mirror row_mask:0xf bank_mask:0xf bound_ctrl:1
	v_add_f32_dpp v112, v112, v112 row_half_mirror row_mask:0xf bank_mask:0xf bound_ctrl:1
	ds_read_b64 v[80:81], v82 offset:43520
	ds_read_b128 v[38:41], v161 offset:2560
	v_add_f32_dpp v110, v110, v110 row_ror:8 row_mask:0xf bank_mask:0xf bound_ctrl:1
	v_add_f32_dpp v112, v112, v112 row_ror:8 row_mask:0xf bank_mask:0xf bound_ctrl:1
	ds_read_b128 v[42:45], v161 offset:35328
	v_pk_mul_f32 v[114:115], v[88:89], v[110:111] op_sel_hi:[1,0]
	v_pk_mul_f32 v[116:117], v[88:89], v[112:113] op_sel_hi:[1,0]
	v_pk_mul_f32 v[118:119], v[90:91], v[110:111] op_sel_hi:[1,0]
	v_pk_mul_f32 v[120:121], v[90:91], v[112:113] op_sel_hi:[1,0]
	v_pk_fma_f32 v[114:115], v[100:101], v[104:105], v[114:115] op_sel_hi:[1,0,1]
	v_pk_fma_f32 v[116:117], v[100:101], v[104:105], v[116:117] op_sel:[0,1,0]
	v_pk_fma_f32 v[118:119], v[102:103], v[104:105], v[118:119] op_sel_hi:[1,0,1]
	v_pk_fma_f32 v[120:121], v[102:103], v[104:105], v[120:121] op_sel:[0,1,0]
	v_pk_fma_f32 v[72:73], v[72:73], v[92:93], v[114:115]
	v_pk_fma_f32 v[76:77], v[76:77], v[92:93], v[116:117]
	v_pk_fma_f32 v[74:75], v[74:75], v[94:95], v[118:119]
	v_pk_fma_f32 v[78:79], v[78:79], v[94:95], v[120:121]
	s_waitcnt lgkmcnt(0)
	v_pk_mul_f32 v[106:107], v[72:73], v[30:31]
	v_pk_mul_f32 v[108:109], v[76:77], v[30:31]
	v_pk_mul_f32 v[122:123], v[72:73], v[96:97]
	v_pk_mul_f32 v[124:125], v[76:77], v[96:97]
	v_pk_fma_f32 v[106:107], v[74:75], v[32:33], v[106:107]
	v_pk_fma_f32 v[108:109], v[78:79], v[32:33], v[108:109]
	v_pk_fma_f32 v[122:123], v[74:75], v[98:99], v[122:123]
	v_pk_fma_f32 v[124:125], v[78:79], v[98:99], v[124:125]
	v_add_f32_e32 v110, v106, v107
	v_add_f32_e32 v112, v108, v109
	v_add_f32_e32 v126, v122, v123
	v_add_f32_e32 v127, v124, v125
	v_add_f32_dpp v110, v110, v110 quad_perm:[1,0,3,2] row_mask:0xf bank_mask:0xf bound_ctrl:1
	v_add_f32_dpp v112, v112, v112 quad_perm:[1,0,3,2] row_mask:0xf bank_mask:0xf bound_ctrl:1
	ds_write_b64 v187, v[126:127] offset:18432
	ds_read_b128 v[84:87], v161 offset:11008
	v_add_f32_dpp v110, v110, v110 quad_perm:[2,3,0,1] row_mask:0xf bank_mask:0xf bound_ctrl:1
	v_add_f32_dpp v112, v112, v112 quad_perm:[2,3,0,1] row_mask:0xf bank_mask:0xf bound_ctrl:1
	ds_read_b128 v[88:91], v161 offset:19200
	ds_read_b128 v[100:103], v161 offset:27392
	v_add_f32_dpp v110, v110, v110 row_half_mirror row_mask:0xf bank_mask:0xf bound_ctrl:1
	v_add_f32_dpp v112, v112, v112 row_half_mirror row_mask:0xf bank_mask:0xf bound_ctrl:1
	ds_read_b64 v[104:105], v82 offset:43776
	ds_read_b128 v[92:95], v161 offset:2816
	v_add_f32_dpp v110, v110, v110 row_ror:8 row_mask:0xf bank_mask:0xf bound_ctrl:1
	v_add_f32_dpp v112, v112, v112 row_ror:8 row_mask:0xf bank_mask:0xf bound_ctrl:1
	ds_read_b128 v[96:99], v161 offset:35584
	v_pk_mul_f32 v[114:115], v[34:35], v[110:111] op_sel_hi:[1,0]
	v_pk_mul_f32 v[116:117], v[34:35], v[112:113] op_sel_hi:[1,0]
	v_pk_mul_f32 v[118:119], v[36:37], v[110:111] op_sel_hi:[1,0]
	v_pk_mul_f32 v[120:121], v[36:37], v[112:113] op_sel_hi:[1,0]
	v_pk_fma_f32 v[114:115], v[46:47], v[80:81], v[114:115] op_sel_hi:[1,0,1]
	v_pk_fma_f32 v[116:117], v[46:47], v[80:81], v[116:117] op_sel:[0,1,0]
	v_pk_fma_f32 v[118:119], v[48:49], v[80:81], v[118:119] op_sel_hi:[1,0,1]
	v_pk_fma_f32 v[120:121], v[48:49], v[80:81], v[120:121] op_sel:[0,1,0]
	v_pk_fma_f32 v[72:73], v[72:73], v[38:39], v[114:115]
	v_pk_fma_f32 v[76:77], v[76:77], v[38:39], v[116:117]
	v_pk_fma_f32 v[74:75], v[74:75], v[40:41], v[118:119]
	v_pk_fma_f32 v[78:79], v[78:79], v[40:41], v[120:121]
	s_waitcnt lgkmcnt(0)
	v_pk_mul_f32 v[106:107], v[72:73], v[84:85]
	v_pk_mul_f32 v[108:109], v[76:77], v[84:85]
	v_pk_mul_f32 v[122:123], v[72:73], v[42:43]
	v_pk_mul_f32 v[124:125], v[76:77], v[42:43]
	v_pk_fma_f32 v[106:107], v[74:75], v[86:87], v[106:107]
	v_pk_fma_f32 v[108:109], v[78:79], v[86:87], v[108:109]
	v_pk_fma_f32 v[122:123], v[74:75], v[44:45], v[122:123]
	v_pk_fma_f32 v[124:125], v[78:79], v[44:45], v[124:125]
	v_add_f32_e32 v110, v106, v107
	v_add_f32_e32 v112, v108, v109
	v_add_f32_e32 v126, v122, v123
	v_add_f32_e32 v127, v124, v125
	v_add_f32_dpp v110, v110, v110 quad_perm:[1,0,3,2] row_mask:0xf bank_mask:0xf bound_ctrl:1
	v_add_f32_dpp v112, v112, v112 quad_perm:[1,0,3,2] row_mask:0xf bank_mask:0xf bound_ctrl:1
	ds_write_b64 v187, v[126:127] offset:20480
	ds_read_b128 v[30:33], v161 offset:11264
	v_add_f32_dpp v110, v110, v110 quad_perm:[2,3,0,1] row_mask:0xf bank_mask:0xf bound_ctrl:1
	v_add_f32_dpp v112, v112, v112 quad_perm:[2,3,0,1] row_mask:0xf bank_mask:0xf bound_ctrl:1
	ds_read_b128 v[34:37], v161 offset:19456
	ds_read_b128 v[46:49], v161 offset:27648
	v_add_f32_dpp v110, v110, v110 row_half_mirror row_mask:0xf bank_mask:0xf bound_ctrl:1
	v_add_f32_dpp v112, v112, v112 row_half_mirror row_mask:0xf bank_mask:0xf bound_ctrl:1
	ds_read_b64 v[80:81], v82 offset:44032
	ds_read_b128 v[38:41], v161 offset:3072
	v_add_f32_dpp v110, v110, v110 row_ror:8 row_mask:0xf bank_mask:0xf bound_ctrl:1
	v_add_f32_dpp v112, v112, v112 row_ror:8 row_mask:0xf bank_mask:0xf bound_ctrl:1
	ds_read_b128 v[42:45], v161 offset:35840
	v_pk_mul_f32 v[114:115], v[88:89], v[110:111] op_sel_hi:[1,0]
	v_pk_mul_f32 v[116:117], v[88:89], v[112:113] op_sel_hi:[1,0]
	v_pk_mul_f32 v[118:119], v[90:91], v[110:111] op_sel_hi:[1,0]
	v_pk_mul_f32 v[120:121], v[90:91], v[112:113] op_sel_hi:[1,0]
	v_pk_fma_f32 v[114:115], v[100:101], v[104:105], v[114:115] op_sel_hi:[1,0,1]
	v_pk_fma_f32 v[116:117], v[100:101], v[104:105], v[116:117] op_sel:[0,1,0]
	v_pk_fma_f32 v[118:119], v[102:103], v[104:105], v[118:119] op_sel_hi:[1,0,1]
	v_pk_fma_f32 v[120:121], v[102:103], v[104:105], v[120:121] op_sel:[0,1,0]
	v_pk_fma_f32 v[72:73], v[72:73], v[92:93], v[114:115]
	v_pk_fma_f32 v[76:77], v[76:77], v[92:93], v[116:117]
	v_pk_fma_f32 v[74:75], v[74:75], v[94:95], v[118:119]
	v_pk_fma_f32 v[78:79], v[78:79], v[94:95], v[120:121]
	s_waitcnt lgkmcnt(0)
	v_pk_mul_f32 v[106:107], v[72:73], v[30:31]
	v_pk_mul_f32 v[108:109], v[76:77], v[30:31]
	v_pk_mul_f32 v[122:123], v[72:73], v[96:97]
	v_pk_mul_f32 v[124:125], v[76:77], v[96:97]
	v_pk_fma_f32 v[106:107], v[74:75], v[32:33], v[106:107]
	v_pk_fma_f32 v[108:109], v[78:79], v[32:33], v[108:109]
	v_pk_fma_f32 v[122:123], v[74:75], v[98:99], v[122:123]
	v_pk_fma_f32 v[124:125], v[78:79], v[98:99], v[124:125]
	v_add_f32_e32 v110, v106, v107
	v_add_f32_e32 v112, v108, v109
	v_add_f32_e32 v126, v122, v123
	v_add_f32_e32 v127, v124, v125
	v_add_f32_dpp v110, v110, v110 quad_perm:[1,0,3,2] row_mask:0xf bank_mask:0xf bound_ctrl:1
	v_add_f32_dpp v112, v112, v112 quad_perm:[1,0,3,2] row_mask:0xf bank_mask:0xf bound_ctrl:1
	ds_write_b64 v187, v[126:127] offset:22528
	ds_read_b128 v[84:87], v161 offset:11520
	v_add_f32_dpp v110, v110, v110 quad_perm:[2,3,0,1] row_mask:0xf bank_mask:0xf bound_ctrl:1
	v_add_f32_dpp v112, v112, v112 quad_perm:[2,3,0,1] row_mask:0xf bank_mask:0xf bound_ctrl:1
	ds_read_b128 v[88:91], v161 offset:19712
	ds_read_b128 v[100:103], v161 offset:27904
	v_add_f32_dpp v110, v110, v110 row_half_mirror row_mask:0xf bank_mask:0xf bound_ctrl:1
	v_add_f32_dpp v112, v112, v112 row_half_mirror row_mask:0xf bank_mask:0xf bound_ctrl:1
	ds_read_b64 v[104:105], v82 offset:44288
	ds_read_b128 v[92:95], v161 offset:3328
	v_add_f32_dpp v110, v110, v110 row_ror:8 row_mask:0xf bank_mask:0xf bound_ctrl:1
	v_add_f32_dpp v112, v112, v112 row_ror:8 row_mask:0xf bank_mask:0xf bound_ctrl:1
	ds_read_b128 v[96:99], v161 offset:36096
	v_pk_mul_f32 v[114:115], v[34:35], v[110:111] op_sel_hi:[1,0]
	v_pk_mul_f32 v[116:117], v[34:35], v[112:113] op_sel_hi:[1,0]
	v_pk_mul_f32 v[118:119], v[36:37], v[110:111] op_sel_hi:[1,0]
	v_pk_mul_f32 v[120:121], v[36:37], v[112:113] op_sel_hi:[1,0]
	v_pk_fma_f32 v[114:115], v[46:47], v[80:81], v[114:115] op_sel_hi:[1,0,1]
	v_pk_fma_f32 v[116:117], v[46:47], v[80:81], v[116:117] op_sel:[0,1,0]
	v_pk_fma_f32 v[118:119], v[48:49], v[80:81], v[118:119] op_sel_hi:[1,0,1]
	v_pk_fma_f32 v[120:121], v[48:49], v[80:81], v[120:121] op_sel:[0,1,0]
	v_pk_fma_f32 v[72:73], v[72:73], v[38:39], v[114:115]
	v_pk_fma_f32 v[76:77], v[76:77], v[38:39], v[116:117]
	v_pk_fma_f32 v[74:75], v[74:75], v[40:41], v[118:119]
	v_pk_fma_f32 v[78:79], v[78:79], v[40:41], v[120:121]
	s_waitcnt lgkmcnt(0)
	v_pk_mul_f32 v[106:107], v[72:73], v[84:85]
	v_pk_mul_f32 v[108:109], v[76:77], v[84:85]
	v_pk_mul_f32 v[122:123], v[72:73], v[42:43]
	v_pk_mul_f32 v[124:125], v[76:77], v[42:43]
	v_pk_fma_f32 v[106:107], v[74:75], v[86:87], v[106:107]
	v_pk_fma_f32 v[108:109], v[78:79], v[86:87], v[108:109]
	v_pk_fma_f32 v[122:123], v[74:75], v[44:45], v[122:123]
	v_pk_fma_f32 v[124:125], v[78:79], v[44:45], v[124:125]
	v_add_f32_e32 v110, v106, v107
	v_add_f32_e32 v112, v108, v109
	v_add_f32_e32 v126, v122, v123
	v_add_f32_e32 v127, v124, v125
	v_add_f32_dpp v110, v110, v110 quad_perm:[1,0,3,2] row_mask:0xf bank_mask:0xf bound_ctrl:1
	v_add_f32_dpp v112, v112, v112 quad_perm:[1,0,3,2] row_mask:0xf bank_mask:0xf bound_ctrl:1
	ds_write_b64 v187, v[126:127] offset:24576
	ds_read_b128 v[30:33], v161 offset:11776
	v_add_f32_dpp v110, v110, v110 quad_perm:[2,3,0,1] row_mask:0xf bank_mask:0xf bound_ctrl:1
	v_add_f32_dpp v112, v112, v112 quad_perm:[2,3,0,1] row_mask:0xf bank_mask:0xf bound_ctrl:1
	ds_read_b128 v[34:37], v161 offset:19968
	ds_read_b128 v[46:49], v161 offset:28160
	v_add_f32_dpp v110, v110, v110 row_half_mirror row_mask:0xf bank_mask:0xf bound_ctrl:1
	v_add_f32_dpp v112, v112, v112 row_half_mirror row_mask:0xf bank_mask:0xf bound_ctrl:1
	ds_read_b64 v[80:81], v82 offset:44544
	ds_read_b128 v[38:41], v161 offset:3584
	v_add_f32_dpp v110, v110, v110 row_ror:8 row_mask:0xf bank_mask:0xf bound_ctrl:1
	v_add_f32_dpp v112, v112, v112 row_ror:8 row_mask:0xf bank_mask:0xf bound_ctrl:1
	ds_read_b128 v[42:45], v161 offset:36352
	v_pk_mul_f32 v[114:115], v[88:89], v[110:111] op_sel_hi:[1,0]
	v_pk_mul_f32 v[116:117], v[88:89], v[112:113] op_sel_hi:[1,0]
	v_pk_mul_f32 v[118:119], v[90:91], v[110:111] op_sel_hi:[1,0]
	v_pk_mul_f32 v[120:121], v[90:91], v[112:113] op_sel_hi:[1,0]
	v_pk_fma_f32 v[114:115], v[100:101], v[104:105], v[114:115] op_sel_hi:[1,0,1]
	v_pk_fma_f32 v[116:117], v[100:101], v[104:105], v[116:117] op_sel:[0,1,0]
	v_pk_fma_f32 v[118:119], v[102:103], v[104:105], v[118:119] op_sel_hi:[1,0,1]
	v_pk_fma_f32 v[120:121], v[102:103], v[104:105], v[120:121] op_sel:[0,1,0]
	v_pk_fma_f32 v[72:73], v[72:73], v[92:93], v[114:115]
	v_pk_fma_f32 v[76:77], v[76:77], v[92:93], v[116:117]
	v_pk_fma_f32 v[74:75], v[74:75], v[94:95], v[118:119]
	v_pk_fma_f32 v[78:79], v[78:79], v[94:95], v[120:121]
	s_waitcnt lgkmcnt(0)
	v_pk_mul_f32 v[106:107], v[72:73], v[30:31]
	v_pk_mul_f32 v[108:109], v[76:77], v[30:31]
	v_pk_mul_f32 v[122:123], v[72:73], v[96:97]
	v_pk_mul_f32 v[124:125], v[76:77], v[96:97]
	v_pk_fma_f32 v[106:107], v[74:75], v[32:33], v[106:107]
	v_pk_fma_f32 v[108:109], v[78:79], v[32:33], v[108:109]
	v_pk_fma_f32 v[122:123], v[74:75], v[98:99], v[122:123]
	v_pk_fma_f32 v[124:125], v[78:79], v[98:99], v[124:125]
	v_add_f32_e32 v110, v106, v107
	v_add_f32_e32 v112, v108, v109
	v_add_f32_e32 v126, v122, v123
	v_add_f32_e32 v127, v124, v125
	v_add_f32_dpp v110, v110, v110 quad_perm:[1,0,3,2] row_mask:0xf bank_mask:0xf bound_ctrl:1
	v_add_f32_dpp v112, v112, v112 quad_perm:[1,0,3,2] row_mask:0xf bank_mask:0xf bound_ctrl:1
	ds_write_b64 v187, v[126:127] offset:26624
	ds_read_b128 v[84:87], v161 offset:12032
	v_add_f32_dpp v110, v110, v110 quad_perm:[2,3,0,1] row_mask:0xf bank_mask:0xf bound_ctrl:1
	v_add_f32_dpp v112, v112, v112 quad_perm:[2,3,0,1] row_mask:0xf bank_mask:0xf bound_ctrl:1
	ds_read_b128 v[88:91], v161 offset:20224
	ds_read_b128 v[100:103], v161 offset:28416
	v_add_f32_dpp v110, v110, v110 row_half_mirror row_mask:0xf bank_mask:0xf bound_ctrl:1
	v_add_f32_dpp v112, v112, v112 row_half_mirror row_mask:0xf bank_mask:0xf bound_ctrl:1
	ds_read_b64 v[104:105], v82 offset:44800
	ds_read_b128 v[92:95], v161 offset:3840
	v_add_f32_dpp v110, v110, v110 row_ror:8 row_mask:0xf bank_mask:0xf bound_ctrl:1
	v_add_f32_dpp v112, v112, v112 row_ror:8 row_mask:0xf bank_mask:0xf bound_ctrl:1
	ds_read_b128 v[96:99], v161 offset:36608
	v_pk_mul_f32 v[114:115], v[34:35], v[110:111] op_sel_hi:[1,0]
	v_pk_mul_f32 v[116:117], v[34:35], v[112:113] op_sel_hi:[1,0]
	v_pk_mul_f32 v[118:119], v[36:37], v[110:111] op_sel_hi:[1,0]
	v_pk_mul_f32 v[120:121], v[36:37], v[112:113] op_sel_hi:[1,0]
	v_pk_fma_f32 v[114:115], v[46:47], v[80:81], v[114:115] op_sel_hi:[1,0,1]
	v_pk_fma_f32 v[116:117], v[46:47], v[80:81], v[116:117] op_sel:[0,1,0]
	v_pk_fma_f32 v[118:119], v[48:49], v[80:81], v[118:119] op_sel_hi:[1,0,1]
	v_pk_fma_f32 v[120:121], v[48:49], v[80:81], v[120:121] op_sel:[0,1,0]
	v_pk_fma_f32 v[72:73], v[72:73], v[38:39], v[114:115]
	v_pk_fma_f32 v[76:77], v[76:77], v[38:39], v[116:117]
	v_pk_fma_f32 v[74:75], v[74:75], v[40:41], v[118:119]
	v_pk_fma_f32 v[78:79], v[78:79], v[40:41], v[120:121]
	s_waitcnt lgkmcnt(0)
	v_pk_mul_f32 v[106:107], v[72:73], v[84:85]
	v_pk_mul_f32 v[108:109], v[76:77], v[84:85]
	v_pk_mul_f32 v[122:123], v[72:73], v[42:43]
	v_pk_mul_f32 v[124:125], v[76:77], v[42:43]
	v_pk_fma_f32 v[106:107], v[74:75], v[86:87], v[106:107]
	v_pk_fma_f32 v[108:109], v[78:79], v[86:87], v[108:109]
	v_pk_fma_f32 v[122:123], v[74:75], v[44:45], v[122:123]
	v_pk_fma_f32 v[124:125], v[78:79], v[44:45], v[124:125]
	v_add_f32_e32 v110, v106, v107
	v_add_f32_e32 v112, v108, v109
	v_add_f32_e32 v126, v122, v123
	v_add_f32_e32 v127, v124, v125
	v_add_f32_dpp v110, v110, v110 quad_perm:[1,0,3,2] row_mask:0xf bank_mask:0xf bound_ctrl:1
	v_add_f32_dpp v112, v112, v112 quad_perm:[1,0,3,2] row_mask:0xf bank_mask:0xf bound_ctrl:1
	ds_write_b64 v187, v[126:127] offset:28672
	ds_read_b128 v[30:33], v161 offset:12288
	v_add_f32_dpp v110, v110, v110 quad_perm:[2,3,0,1] row_mask:0xf bank_mask:0xf bound_ctrl:1
	v_add_f32_dpp v112, v112, v112 quad_perm:[2,3,0,1] row_mask:0xf bank_mask:0xf bound_ctrl:1
	ds_read_b128 v[34:37], v161 offset:20480
	ds_read_b128 v[46:49], v161 offset:28672
	v_add_f32_dpp v110, v110, v110 row_half_mirror row_mask:0xf bank_mask:0xf bound_ctrl:1
	v_add_f32_dpp v112, v112, v112 row_half_mirror row_mask:0xf bank_mask:0xf bound_ctrl:1
	ds_read_b64 v[80:81], v82 offset:45056
	ds_read_b128 v[38:41], v161 offset:4096
	v_add_f32_dpp v110, v110, v110 row_ror:8 row_mask:0xf bank_mask:0xf bound_ctrl:1
	v_add_f32_dpp v112, v112, v112 row_ror:8 row_mask:0xf bank_mask:0xf bound_ctrl:1
	ds_read_b128 v[42:45], v161 offset:36864
	v_pk_mul_f32 v[114:115], v[88:89], v[110:111] op_sel_hi:[1,0]
	v_pk_mul_f32 v[116:117], v[88:89], v[112:113] op_sel_hi:[1,0]
	v_pk_mul_f32 v[118:119], v[90:91], v[110:111] op_sel_hi:[1,0]
	v_pk_mul_f32 v[120:121], v[90:91], v[112:113] op_sel_hi:[1,0]
	v_pk_fma_f32 v[114:115], v[100:101], v[104:105], v[114:115] op_sel_hi:[1,0,1]
	v_pk_fma_f32 v[116:117], v[100:101], v[104:105], v[116:117] op_sel:[0,1,0]
	v_pk_fma_f32 v[118:119], v[102:103], v[104:105], v[118:119] op_sel_hi:[1,0,1]
	v_pk_fma_f32 v[120:121], v[102:103], v[104:105], v[120:121] op_sel:[0,1,0]
	v_pk_fma_f32 v[72:73], v[72:73], v[92:93], v[114:115]
	v_pk_fma_f32 v[76:77], v[76:77], v[92:93], v[116:117]
	v_pk_fma_f32 v[74:75], v[74:75], v[94:95], v[118:119]
	v_pk_fma_f32 v[78:79], v[78:79], v[94:95], v[120:121]
	s_waitcnt lgkmcnt(0)
	v_pk_mul_f32 v[106:107], v[72:73], v[30:31]
	v_pk_mul_f32 v[108:109], v[76:77], v[30:31]
	v_pk_mul_f32 v[122:123], v[72:73], v[96:97]
	v_pk_mul_f32 v[124:125], v[76:77], v[96:97]
	v_pk_fma_f32 v[106:107], v[74:75], v[32:33], v[106:107]
	v_pk_fma_f32 v[108:109], v[78:79], v[32:33], v[108:109]
	v_pk_fma_f32 v[122:123], v[74:75], v[98:99], v[122:123]
	v_pk_fma_f32 v[124:125], v[78:79], v[98:99], v[124:125]
	v_add_f32_e32 v110, v106, v107
	v_add_f32_e32 v112, v108, v109
	v_add_f32_e32 v126, v122, v123
	v_add_f32_e32 v127, v124, v125
	v_add_f32_dpp v110, v110, v110 quad_perm:[1,0,3,2] row_mask:0xf bank_mask:0xf bound_ctrl:1
	v_add_f32_dpp v112, v112, v112 quad_perm:[1,0,3,2] row_mask:0xf bank_mask:0xf bound_ctrl:1
	ds_write_b64 v187, v[126:127] offset:30720
	ds_read_b128 v[84:87], v161 offset:12544
	v_add_f32_dpp v110, v110, v110 quad_perm:[2,3,0,1] row_mask:0xf bank_mask:0xf bound_ctrl:1
	v_add_f32_dpp v112, v112, v112 quad_perm:[2,3,0,1] row_mask:0xf bank_mask:0xf bound_ctrl:1
	ds_read_b128 v[88:91], v161 offset:20736
	ds_read_b128 v[100:103], v161 offset:28928
	v_add_f32_dpp v110, v110, v110 row_half_mirror row_mask:0xf bank_mask:0xf bound_ctrl:1
	v_add_f32_dpp v112, v112, v112 row_half_mirror row_mask:0xf bank_mask:0xf bound_ctrl:1
	ds_read_b64 v[104:105], v82 offset:45312
	ds_read_b128 v[92:95], v161 offset:4352
	v_add_f32_dpp v110, v110, v110 row_ror:8 row_mask:0xf bank_mask:0xf bound_ctrl:1
	v_add_f32_dpp v112, v112, v112 row_ror:8 row_mask:0xf bank_mask:0xf bound_ctrl:1
	ds_read_b128 v[96:99], v161 offset:37120
	v_pk_mul_f32 v[114:115], v[34:35], v[110:111] op_sel_hi:[1,0]
	v_pk_mul_f32 v[116:117], v[34:35], v[112:113] op_sel_hi:[1,0]
	v_pk_mul_f32 v[118:119], v[36:37], v[110:111] op_sel_hi:[1,0]
	v_pk_mul_f32 v[120:121], v[36:37], v[112:113] op_sel_hi:[1,0]
	v_pk_fma_f32 v[114:115], v[46:47], v[80:81], v[114:115] op_sel_hi:[1,0,1]
	v_pk_fma_f32 v[116:117], v[46:47], v[80:81], v[116:117] op_sel:[0,1,0]
	v_pk_fma_f32 v[118:119], v[48:49], v[80:81], v[118:119] op_sel_hi:[1,0,1]
	v_pk_fma_f32 v[120:121], v[48:49], v[80:81], v[120:121] op_sel:[0,1,0]
	v_pk_fma_f32 v[72:73], v[72:73], v[38:39], v[114:115]
	v_pk_fma_f32 v[76:77], v[76:77], v[38:39], v[116:117]
	v_pk_fma_f32 v[74:75], v[74:75], v[40:41], v[118:119]
	v_pk_fma_f32 v[78:79], v[78:79], v[40:41], v[120:121]
	s_waitcnt lgkmcnt(0)
	v_pk_mul_f32 v[106:107], v[72:73], v[84:85]
	v_pk_mul_f32 v[108:109], v[76:77], v[84:85]
	v_pk_mul_f32 v[122:123], v[72:73], v[42:43]
	v_pk_mul_f32 v[124:125], v[76:77], v[42:43]
	v_pk_fma_f32 v[106:107], v[74:75], v[86:87], v[106:107]
	v_pk_fma_f32 v[108:109], v[78:79], v[86:87], v[108:109]
	v_pk_fma_f32 v[122:123], v[74:75], v[44:45], v[122:123]
	v_pk_fma_f32 v[124:125], v[78:79], v[44:45], v[124:125]
	v_add_f32_e32 v110, v106, v107
	v_add_f32_e32 v112, v108, v109
	v_add_f32_e32 v126, v122, v123
	v_add_f32_e32 v127, v124, v125
	v_add_f32_dpp v110, v110, v110 quad_perm:[1,0,3,2] row_mask:0xf bank_mask:0xf bound_ctrl:1
	v_add_f32_dpp v112, v112, v112 quad_perm:[1,0,3,2] row_mask:0xf bank_mask:0xf bound_ctrl:1
	ds_write_b64 v187, v[126:127] offset:32768
	ds_read_b128 v[30:33], v161 offset:12800
	v_add_f32_dpp v110, v110, v110 quad_perm:[2,3,0,1] row_mask:0xf bank_mask:0xf bound_ctrl:1
	v_add_f32_dpp v112, v112, v112 quad_perm:[2,3,0,1] row_mask:0xf bank_mask:0xf bound_ctrl:1
	ds_read_b128 v[34:37], v161 offset:20992
	ds_read_b128 v[46:49], v161 offset:29184
	v_add_f32_dpp v110, v110, v110 row_half_mirror row_mask:0xf bank_mask:0xf bound_ctrl:1
	v_add_f32_dpp v112, v112, v112 row_half_mirror row_mask:0xf bank_mask:0xf bound_ctrl:1
	ds_read_b64 v[80:81], v82 offset:45568
	ds_read_b128 v[38:41], v161 offset:4608
	v_add_f32_dpp v110, v110, v110 row_ror:8 row_mask:0xf bank_mask:0xf bound_ctrl:1
	v_add_f32_dpp v112, v112, v112 row_ror:8 row_mask:0xf bank_mask:0xf bound_ctrl:1
	ds_read_b128 v[42:45], v161 offset:37376
	v_pk_mul_f32 v[114:115], v[88:89], v[110:111] op_sel_hi:[1,0]
	v_pk_mul_f32 v[116:117], v[88:89], v[112:113] op_sel_hi:[1,0]
	v_pk_mul_f32 v[118:119], v[90:91], v[110:111] op_sel_hi:[1,0]
	v_pk_mul_f32 v[120:121], v[90:91], v[112:113] op_sel_hi:[1,0]
	v_pk_fma_f32 v[114:115], v[100:101], v[104:105], v[114:115] op_sel_hi:[1,0,1]
	v_pk_fma_f32 v[116:117], v[100:101], v[104:105], v[116:117] op_sel:[0,1,0]
	v_pk_fma_f32 v[118:119], v[102:103], v[104:105], v[118:119] op_sel_hi:[1,0,1]
	v_pk_fma_f32 v[120:121], v[102:103], v[104:105], v[120:121] op_sel:[0,1,0]
	v_pk_fma_f32 v[72:73], v[72:73], v[92:93], v[114:115]
	v_pk_fma_f32 v[76:77], v[76:77], v[92:93], v[116:117]
	v_pk_fma_f32 v[74:75], v[74:75], v[94:95], v[118:119]
	v_pk_fma_f32 v[78:79], v[78:79], v[94:95], v[120:121]
	s_waitcnt lgkmcnt(0)
	v_pk_mul_f32 v[106:107], v[72:73], v[30:31]
	v_pk_mul_f32 v[108:109], v[76:77], v[30:31]
	v_pk_mul_f32 v[122:123], v[72:73], v[96:97]
	v_pk_mul_f32 v[124:125], v[76:77], v[96:97]
	v_pk_fma_f32 v[106:107], v[74:75], v[32:33], v[106:107]
	v_pk_fma_f32 v[108:109], v[78:79], v[32:33], v[108:109]
	v_pk_fma_f32 v[122:123], v[74:75], v[98:99], v[122:123]
	v_pk_fma_f32 v[124:125], v[78:79], v[98:99], v[124:125]
	v_add_f32_e32 v110, v106, v107
	v_add_f32_e32 v112, v108, v109
	v_add_f32_e32 v126, v122, v123
	v_add_f32_e32 v127, v124, v125
	v_add_f32_dpp v110, v110, v110 quad_perm:[1,0,3,2] row_mask:0xf bank_mask:0xf bound_ctrl:1
	v_add_f32_dpp v112, v112, v112 quad_perm:[1,0,3,2] row_mask:0xf bank_mask:0xf bound_ctrl:1
	ds_write_b64 v187, v[126:127] offset:34816
	ds_read_b128 v[84:87], v161 offset:13056
	v_add_f32_dpp v110, v110, v110 quad_perm:[2,3,0,1] row_mask:0xf bank_mask:0xf bound_ctrl:1
	v_add_f32_dpp v112, v112, v112 quad_perm:[2,3,0,1] row_mask:0xf bank_mask:0xf bound_ctrl:1
	ds_read_b128 v[88:91], v161 offset:21248
	ds_read_b128 v[100:103], v161 offset:29440
	v_add_f32_dpp v110, v110, v110 row_half_mirror row_mask:0xf bank_mask:0xf bound_ctrl:1
	v_add_f32_dpp v112, v112, v112 row_half_mirror row_mask:0xf bank_mask:0xf bound_ctrl:1
	ds_read_b64 v[104:105], v82 offset:45824
	ds_read_b128 v[92:95], v161 offset:4864
	v_add_f32_dpp v110, v110, v110 row_ror:8 row_mask:0xf bank_mask:0xf bound_ctrl:1
	v_add_f32_dpp v112, v112, v112 row_ror:8 row_mask:0xf bank_mask:0xf bound_ctrl:1
	ds_read_b128 v[96:99], v161 offset:37632
	v_pk_mul_f32 v[114:115], v[34:35], v[110:111] op_sel_hi:[1,0]
	v_pk_mul_f32 v[116:117], v[34:35], v[112:113] op_sel_hi:[1,0]
	v_pk_mul_f32 v[118:119], v[36:37], v[110:111] op_sel_hi:[1,0]
	v_pk_mul_f32 v[120:121], v[36:37], v[112:113] op_sel_hi:[1,0]
	v_pk_fma_f32 v[114:115], v[46:47], v[80:81], v[114:115] op_sel_hi:[1,0,1]
	v_pk_fma_f32 v[116:117], v[46:47], v[80:81], v[116:117] op_sel:[0,1,0]
	v_pk_fma_f32 v[118:119], v[48:49], v[80:81], v[118:119] op_sel_hi:[1,0,1]
	v_pk_fma_f32 v[120:121], v[48:49], v[80:81], v[120:121] op_sel:[0,1,0]
	v_pk_fma_f32 v[72:73], v[72:73], v[38:39], v[114:115]
	v_pk_fma_f32 v[76:77], v[76:77], v[38:39], v[116:117]
	v_pk_fma_f32 v[74:75], v[74:75], v[40:41], v[118:119]
	v_pk_fma_f32 v[78:79], v[78:79], v[40:41], v[120:121]
	s_waitcnt lgkmcnt(0)
	v_pk_mul_f32 v[106:107], v[72:73], v[84:85]
	v_pk_mul_f32 v[108:109], v[76:77], v[84:85]
	v_pk_mul_f32 v[122:123], v[72:73], v[42:43]
	v_pk_mul_f32 v[124:125], v[76:77], v[42:43]
	v_pk_fma_f32 v[106:107], v[74:75], v[86:87], v[106:107]
	v_pk_fma_f32 v[108:109], v[78:79], v[86:87], v[108:109]
	v_pk_fma_f32 v[122:123], v[74:75], v[44:45], v[122:123]
	v_pk_fma_f32 v[124:125], v[78:79], v[44:45], v[124:125]
	v_add_f32_e32 v110, v106, v107
	v_add_f32_e32 v112, v108, v109
	v_add_f32_e32 v126, v122, v123
	v_add_f32_e32 v127, v124, v125
	v_add_f32_dpp v110, v110, v110 quad_perm:[1,0,3,2] row_mask:0xf bank_mask:0xf bound_ctrl:1
	v_add_f32_dpp v112, v112, v112 quad_perm:[1,0,3,2] row_mask:0xf bank_mask:0xf bound_ctrl:1
	ds_write_b64 v187, v[126:127] offset:36864
	ds_read_b128 v[30:33], v161 offset:13312
	v_add_f32_dpp v110, v110, v110 quad_perm:[2,3,0,1] row_mask:0xf bank_mask:0xf bound_ctrl:1
	v_add_f32_dpp v112, v112, v112 quad_perm:[2,3,0,1] row_mask:0xf bank_mask:0xf bound_ctrl:1
	ds_read_b128 v[34:37], v161 offset:21504
	ds_read_b128 v[46:49], v161 offset:29696
	v_add_f32_dpp v110, v110, v110 row_half_mirror row_mask:0xf bank_mask:0xf bound_ctrl:1
	v_add_f32_dpp v112, v112, v112 row_half_mirror row_mask:0xf bank_mask:0xf bound_ctrl:1
	ds_read_b64 v[80:81], v82 offset:46080
	ds_read_b128 v[38:41], v161 offset:5120
	v_add_f32_dpp v110, v110, v110 row_ror:8 row_mask:0xf bank_mask:0xf bound_ctrl:1
	v_add_f32_dpp v112, v112, v112 row_ror:8 row_mask:0xf bank_mask:0xf bound_ctrl:1
	ds_read_b128 v[42:45], v161 offset:37888
	v_pk_mul_f32 v[114:115], v[88:89], v[110:111] op_sel_hi:[1,0]
	v_pk_mul_f32 v[116:117], v[88:89], v[112:113] op_sel_hi:[1,0]
	v_pk_mul_f32 v[118:119], v[90:91], v[110:111] op_sel_hi:[1,0]
	v_pk_mul_f32 v[120:121], v[90:91], v[112:113] op_sel_hi:[1,0]
	v_pk_fma_f32 v[114:115], v[100:101], v[104:105], v[114:115] op_sel_hi:[1,0,1]
	v_pk_fma_f32 v[116:117], v[100:101], v[104:105], v[116:117] op_sel:[0,1,0]
	v_pk_fma_f32 v[118:119], v[102:103], v[104:105], v[118:119] op_sel_hi:[1,0,1]
	v_pk_fma_f32 v[120:121], v[102:103], v[104:105], v[120:121] op_sel:[0,1,0]
	v_pk_fma_f32 v[72:73], v[72:73], v[92:93], v[114:115]
	v_pk_fma_f32 v[76:77], v[76:77], v[92:93], v[116:117]
	v_pk_fma_f32 v[74:75], v[74:75], v[94:95], v[118:119]
	v_pk_fma_f32 v[78:79], v[78:79], v[94:95], v[120:121]
	s_waitcnt lgkmcnt(0)
	v_pk_mul_f32 v[106:107], v[72:73], v[30:31]
	v_pk_mul_f32 v[108:109], v[76:77], v[30:31]
	v_pk_mul_f32 v[122:123], v[72:73], v[96:97]
	v_pk_mul_f32 v[124:125], v[76:77], v[96:97]
	v_pk_fma_f32 v[106:107], v[74:75], v[32:33], v[106:107]
	v_pk_fma_f32 v[108:109], v[78:79], v[32:33], v[108:109]
	v_pk_fma_f32 v[122:123], v[74:75], v[98:99], v[122:123]
	v_pk_fma_f32 v[124:125], v[78:79], v[98:99], v[124:125]
	v_add_f32_e32 v110, v106, v107
	v_add_f32_e32 v112, v108, v109
	v_add_f32_e32 v126, v122, v123
	v_add_f32_e32 v127, v124, v125
	v_add_f32_dpp v110, v110, v110 quad_perm:[1,0,3,2] row_mask:0xf bank_mask:0xf bound_ctrl:1
	v_add_f32_dpp v112, v112, v112 quad_perm:[1,0,3,2] row_mask:0xf bank_mask:0xf bound_ctrl:1
	ds_write_b64 v187, v[126:127] offset:38912
	ds_read_b128 v[84:87], v161 offset:13568
	v_add_f32_dpp v110, v110, v110 quad_perm:[2,3,0,1] row_mask:0xf bank_mask:0xf bound_ctrl:1
	v_add_f32_dpp v112, v112, v112 quad_perm:[2,3,0,1] row_mask:0xf bank_mask:0xf bound_ctrl:1
	ds_read_b128 v[88:91], v161 offset:21760
	ds_read_b128 v[100:103], v161 offset:29952
	v_add_f32_dpp v110, v110, v110 row_half_mirror row_mask:0xf bank_mask:0xf bound_ctrl:1
	v_add_f32_dpp v112, v112, v112 row_half_mirror row_mask:0xf bank_mask:0xf bound_ctrl:1
	ds_read_b64 v[104:105], v82 offset:46336
	ds_read_b128 v[92:95], v161 offset:5376
	v_add_f32_dpp v110, v110, v110 row_ror:8 row_mask:0xf bank_mask:0xf bound_ctrl:1
	v_add_f32_dpp v112, v112, v112 row_ror:8 row_mask:0xf bank_mask:0xf bound_ctrl:1
	ds_read_b128 v[96:99], v161 offset:38144
	v_pk_mul_f32 v[114:115], v[34:35], v[110:111] op_sel_hi:[1,0]
	v_pk_mul_f32 v[116:117], v[34:35], v[112:113] op_sel_hi:[1,0]
	v_pk_mul_f32 v[118:119], v[36:37], v[110:111] op_sel_hi:[1,0]
	v_pk_mul_f32 v[120:121], v[36:37], v[112:113] op_sel_hi:[1,0]
	v_pk_fma_f32 v[114:115], v[46:47], v[80:81], v[114:115] op_sel_hi:[1,0,1]
	v_pk_fma_f32 v[116:117], v[46:47], v[80:81], v[116:117] op_sel:[0,1,0]
	v_pk_fma_f32 v[118:119], v[48:49], v[80:81], v[118:119] op_sel_hi:[1,0,1]
	v_pk_fma_f32 v[120:121], v[48:49], v[80:81], v[120:121] op_sel:[0,1,0]
	v_pk_fma_f32 v[72:73], v[72:73], v[38:39], v[114:115]
	v_pk_fma_f32 v[76:77], v[76:77], v[38:39], v[116:117]
	v_pk_fma_f32 v[74:75], v[74:75], v[40:41], v[118:119]
	v_pk_fma_f32 v[78:79], v[78:79], v[40:41], v[120:121]
	s_waitcnt lgkmcnt(0)
	v_pk_mul_f32 v[106:107], v[72:73], v[84:85]
	v_pk_mul_f32 v[108:109], v[76:77], v[84:85]
	v_pk_mul_f32 v[122:123], v[72:73], v[42:43]
	v_pk_mul_f32 v[124:125], v[76:77], v[42:43]
	v_pk_fma_f32 v[106:107], v[74:75], v[86:87], v[106:107]
	v_pk_fma_f32 v[108:109], v[78:79], v[86:87], v[108:109]
	v_pk_fma_f32 v[122:123], v[74:75], v[44:45], v[122:123]
	v_pk_fma_f32 v[124:125], v[78:79], v[44:45], v[124:125]
	v_add_f32_e32 v110, v106, v107
	v_add_f32_e32 v112, v108, v109
	v_add_f32_e32 v126, v122, v123
	v_add_f32_e32 v127, v124, v125
	v_add_f32_dpp v110, v110, v110 quad_perm:[1,0,3,2] row_mask:0xf bank_mask:0xf bound_ctrl:1
	v_add_f32_dpp v112, v112, v112 quad_perm:[1,0,3,2] row_mask:0xf bank_mask:0xf bound_ctrl:1
	ds_write_b64 v187, v[126:127] offset:40960
	ds_read_b128 v[30:33], v161 offset:13824
	v_add_f32_dpp v110, v110, v110 quad_perm:[2,3,0,1] row_mask:0xf bank_mask:0xf bound_ctrl:1
	v_add_f32_dpp v112, v112, v112 quad_perm:[2,3,0,1] row_mask:0xf bank_mask:0xf bound_ctrl:1
	ds_read_b128 v[34:37], v161 offset:22016
	ds_read_b128 v[46:49], v161 offset:30208
	v_add_f32_dpp v110, v110, v110 row_half_mirror row_mask:0xf bank_mask:0xf bound_ctrl:1
	v_add_f32_dpp v112, v112, v112 row_half_mirror row_mask:0xf bank_mask:0xf bound_ctrl:1
	ds_read_b64 v[80:81], v82 offset:46592
	ds_read_b128 v[38:41], v161 offset:5632
	v_add_f32_dpp v110, v110, v110 row_ror:8 row_mask:0xf bank_mask:0xf bound_ctrl:1
	v_add_f32_dpp v112, v112, v112 row_ror:8 row_mask:0xf bank_mask:0xf bound_ctrl:1
	ds_read_b128 v[42:45], v161 offset:38400
	v_pk_mul_f32 v[114:115], v[88:89], v[110:111] op_sel_hi:[1,0]
	v_pk_mul_f32 v[116:117], v[88:89], v[112:113] op_sel_hi:[1,0]
	v_pk_mul_f32 v[118:119], v[90:91], v[110:111] op_sel_hi:[1,0]
	v_pk_mul_f32 v[120:121], v[90:91], v[112:113] op_sel_hi:[1,0]
	v_pk_fma_f32 v[114:115], v[100:101], v[104:105], v[114:115] op_sel_hi:[1,0,1]
	v_pk_fma_f32 v[116:117], v[100:101], v[104:105], v[116:117] op_sel:[0,1,0]
	v_pk_fma_f32 v[118:119], v[102:103], v[104:105], v[118:119] op_sel_hi:[1,0,1]
	v_pk_fma_f32 v[120:121], v[102:103], v[104:105], v[120:121] op_sel:[0,1,0]
	v_pk_fma_f32 v[72:73], v[72:73], v[92:93], v[114:115]
	v_pk_fma_f32 v[76:77], v[76:77], v[92:93], v[116:117]
	v_pk_fma_f32 v[74:75], v[74:75], v[94:95], v[118:119]
	v_pk_fma_f32 v[78:79], v[78:79], v[94:95], v[120:121]
	s_waitcnt lgkmcnt(0)
	v_pk_mul_f32 v[106:107], v[72:73], v[30:31]
	v_pk_mul_f32 v[108:109], v[76:77], v[30:31]
	v_pk_mul_f32 v[122:123], v[72:73], v[96:97]
	v_pk_mul_f32 v[124:125], v[76:77], v[96:97]
	v_pk_fma_f32 v[106:107], v[74:75], v[32:33], v[106:107]
	v_pk_fma_f32 v[108:109], v[78:79], v[32:33], v[108:109]
	v_pk_fma_f32 v[122:123], v[74:75], v[98:99], v[122:123]
	v_pk_fma_f32 v[124:125], v[78:79], v[98:99], v[124:125]
	v_add_f32_e32 v110, v106, v107
	v_add_f32_e32 v112, v108, v109
	v_add_f32_e32 v126, v122, v123
	v_add_f32_e32 v127, v124, v125
	v_add_f32_dpp v110, v110, v110 quad_perm:[1,0,3,2] row_mask:0xf bank_mask:0xf bound_ctrl:1
	v_add_f32_dpp v112, v112, v112 quad_perm:[1,0,3,2] row_mask:0xf bank_mask:0xf bound_ctrl:1
	ds_write_b64 v187, v[126:127] offset:43008
	ds_read_b128 v[84:87], v161 offset:14080
	v_add_f32_dpp v110, v110, v110 quad_perm:[2,3,0,1] row_mask:0xf bank_mask:0xf bound_ctrl:1
	v_add_f32_dpp v112, v112, v112 quad_perm:[2,3,0,1] row_mask:0xf bank_mask:0xf bound_ctrl:1
	ds_read_b128 v[88:91], v161 offset:22272
	ds_read_b128 v[100:103], v161 offset:30464
	v_add_f32_dpp v110, v110, v110 row_half_mirror row_mask:0xf bank_mask:0xf bound_ctrl:1
	v_add_f32_dpp v112, v112, v112 row_half_mirror row_mask:0xf bank_mask:0xf bound_ctrl:1
	ds_read_b64 v[104:105], v82 offset:46848
	ds_read_b128 v[92:95], v161 offset:5888
	v_add_f32_dpp v110, v110, v110 row_ror:8 row_mask:0xf bank_mask:0xf bound_ctrl:1
	v_add_f32_dpp v112, v112, v112 row_ror:8 row_mask:0xf bank_mask:0xf bound_ctrl:1
	ds_read_b128 v[96:99], v161 offset:38656
	v_pk_mul_f32 v[114:115], v[34:35], v[110:111] op_sel_hi:[1,0]
	v_pk_mul_f32 v[116:117], v[34:35], v[112:113] op_sel_hi:[1,0]
	v_pk_mul_f32 v[118:119], v[36:37], v[110:111] op_sel_hi:[1,0]
	v_pk_mul_f32 v[120:121], v[36:37], v[112:113] op_sel_hi:[1,0]
	v_pk_fma_f32 v[114:115], v[46:47], v[80:81], v[114:115] op_sel_hi:[1,0,1]
	v_pk_fma_f32 v[116:117], v[46:47], v[80:81], v[116:117] op_sel:[0,1,0]
	v_pk_fma_f32 v[118:119], v[48:49], v[80:81], v[118:119] op_sel_hi:[1,0,1]
	v_pk_fma_f32 v[120:121], v[48:49], v[80:81], v[120:121] op_sel:[0,1,0]
	v_pk_fma_f32 v[72:73], v[72:73], v[38:39], v[114:115]
	v_pk_fma_f32 v[76:77], v[76:77], v[38:39], v[116:117]
	v_pk_fma_f32 v[74:75], v[74:75], v[40:41], v[118:119]
	v_pk_fma_f32 v[78:79], v[78:79], v[40:41], v[120:121]
	s_waitcnt lgkmcnt(0)
	v_pk_mul_f32 v[106:107], v[72:73], v[84:85]
	v_pk_mul_f32 v[108:109], v[76:77], v[84:85]
	v_pk_mul_f32 v[122:123], v[72:73], v[42:43]
	v_pk_mul_f32 v[124:125], v[76:77], v[42:43]
	v_pk_fma_f32 v[106:107], v[74:75], v[86:87], v[106:107]
	v_pk_fma_f32 v[108:109], v[78:79], v[86:87], v[108:109]
	v_pk_fma_f32 v[122:123], v[74:75], v[44:45], v[122:123]
	v_pk_fma_f32 v[124:125], v[78:79], v[44:45], v[124:125]
	v_add_f32_e32 v110, v106, v107
	v_add_f32_e32 v112, v108, v109
	v_add_f32_e32 v126, v122, v123
	v_add_f32_e32 v127, v124, v125
	v_add_f32_dpp v110, v110, v110 quad_perm:[1,0,3,2] row_mask:0xf bank_mask:0xf bound_ctrl:1
	v_add_f32_dpp v112, v112, v112 quad_perm:[1,0,3,2] row_mask:0xf bank_mask:0xf bound_ctrl:1
	ds_write_b64 v187, v[126:127] offset:45056
	ds_read_b128 v[30:33], v161 offset:14336
	v_add_f32_dpp v110, v110, v110 quad_perm:[2,3,0,1] row_mask:0xf bank_mask:0xf bound_ctrl:1
	v_add_f32_dpp v112, v112, v112 quad_perm:[2,3,0,1] row_mask:0xf bank_mask:0xf bound_ctrl:1
	ds_read_b128 v[34:37], v161 offset:22528
	ds_read_b128 v[46:49], v161 offset:30720
	v_add_f32_dpp v110, v110, v110 row_half_mirror row_mask:0xf bank_mask:0xf bound_ctrl:1
	v_add_f32_dpp v112, v112, v112 row_half_mirror row_mask:0xf bank_mask:0xf bound_ctrl:1
	ds_read_b64 v[80:81], v82 offset:47104
	ds_read_b128 v[38:41], v161 offset:6144
	v_add_f32_dpp v110, v110, v110 row_ror:8 row_mask:0xf bank_mask:0xf bound_ctrl:1
	v_add_f32_dpp v112, v112, v112 row_ror:8 row_mask:0xf bank_mask:0xf bound_ctrl:1
	ds_read_b128 v[42:45], v161 offset:38912
	v_pk_mul_f32 v[114:115], v[88:89], v[110:111] op_sel_hi:[1,0]
	v_pk_mul_f32 v[116:117], v[88:89], v[112:113] op_sel_hi:[1,0]
	v_pk_mul_f32 v[118:119], v[90:91], v[110:111] op_sel_hi:[1,0]
	v_pk_mul_f32 v[120:121], v[90:91], v[112:113] op_sel_hi:[1,0]
	v_pk_fma_f32 v[114:115], v[100:101], v[104:105], v[114:115] op_sel_hi:[1,0,1]
	v_pk_fma_f32 v[116:117], v[100:101], v[104:105], v[116:117] op_sel:[0,1,0]
	v_pk_fma_f32 v[118:119], v[102:103], v[104:105], v[118:119] op_sel_hi:[1,0,1]
	v_pk_fma_f32 v[120:121], v[102:103], v[104:105], v[120:121] op_sel:[0,1,0]
	v_pk_fma_f32 v[72:73], v[72:73], v[92:93], v[114:115]
	v_pk_fma_f32 v[76:77], v[76:77], v[92:93], v[116:117]
	v_pk_fma_f32 v[74:75], v[74:75], v[94:95], v[118:119]
	v_pk_fma_f32 v[78:79], v[78:79], v[94:95], v[120:121]
	s_waitcnt lgkmcnt(0)
	v_pk_mul_f32 v[106:107], v[72:73], v[30:31]
	v_pk_mul_f32 v[108:109], v[76:77], v[30:31]
	v_pk_mul_f32 v[122:123], v[72:73], v[96:97]
	v_pk_mul_f32 v[124:125], v[76:77], v[96:97]
	v_pk_fma_f32 v[106:107], v[74:75], v[32:33], v[106:107]
	v_pk_fma_f32 v[108:109], v[78:79], v[32:33], v[108:109]
	v_pk_fma_f32 v[122:123], v[74:75], v[98:99], v[122:123]
	v_pk_fma_f32 v[124:125], v[78:79], v[98:99], v[124:125]
	v_add_f32_e32 v110, v106, v107
	v_add_f32_e32 v112, v108, v109
	v_add_f32_e32 v126, v122, v123
	v_add_f32_e32 v127, v124, v125
	v_add_f32_dpp v110, v110, v110 quad_perm:[1,0,3,2] row_mask:0xf bank_mask:0xf bound_ctrl:1
	v_add_f32_dpp v112, v112, v112 quad_perm:[1,0,3,2] row_mask:0xf bank_mask:0xf bound_ctrl:1
	ds_write_b64 v187, v[126:127] offset:47104
	ds_read_b128 v[84:87], v161 offset:14592
	v_add_f32_dpp v110, v110, v110 quad_perm:[2,3,0,1] row_mask:0xf bank_mask:0xf bound_ctrl:1
	v_add_f32_dpp v112, v112, v112 quad_perm:[2,3,0,1] row_mask:0xf bank_mask:0xf bound_ctrl:1
	ds_read_b128 v[88:91], v161 offset:22784
	ds_read_b128 v[100:103], v161 offset:30976
	v_add_f32_dpp v110, v110, v110 row_half_mirror row_mask:0xf bank_mask:0xf bound_ctrl:1
	v_add_f32_dpp v112, v112, v112 row_half_mirror row_mask:0xf bank_mask:0xf bound_ctrl:1
	ds_read_b64 v[104:105], v82 offset:47360
	ds_read_b128 v[92:95], v161 offset:6400
	v_add_f32_dpp v110, v110, v110 row_ror:8 row_mask:0xf bank_mask:0xf bound_ctrl:1
	v_add_f32_dpp v112, v112, v112 row_ror:8 row_mask:0xf bank_mask:0xf bound_ctrl:1
	ds_read_b128 v[96:99], v161 offset:39168
	v_pk_mul_f32 v[114:115], v[34:35], v[110:111] op_sel_hi:[1,0]
	v_pk_mul_f32 v[116:117], v[34:35], v[112:113] op_sel_hi:[1,0]
	v_pk_mul_f32 v[118:119], v[36:37], v[110:111] op_sel_hi:[1,0]
	v_pk_mul_f32 v[120:121], v[36:37], v[112:113] op_sel_hi:[1,0]
	v_pk_fma_f32 v[114:115], v[46:47], v[80:81], v[114:115] op_sel_hi:[1,0,1]
	v_pk_fma_f32 v[116:117], v[46:47], v[80:81], v[116:117] op_sel:[0,1,0]
	v_pk_fma_f32 v[118:119], v[48:49], v[80:81], v[118:119] op_sel_hi:[1,0,1]
	v_pk_fma_f32 v[120:121], v[48:49], v[80:81], v[120:121] op_sel:[0,1,0]
	v_pk_fma_f32 v[72:73], v[72:73], v[38:39], v[114:115]
	v_pk_fma_f32 v[76:77], v[76:77], v[38:39], v[116:117]
	v_pk_fma_f32 v[74:75], v[74:75], v[40:41], v[118:119]
	v_pk_fma_f32 v[78:79], v[78:79], v[40:41], v[120:121]
	s_waitcnt lgkmcnt(0)
	v_pk_mul_f32 v[106:107], v[72:73], v[84:85]
	v_pk_mul_f32 v[108:109], v[76:77], v[84:85]
	v_pk_mul_f32 v[122:123], v[72:73], v[42:43]
	v_pk_mul_f32 v[124:125], v[76:77], v[42:43]
	v_pk_fma_f32 v[106:107], v[74:75], v[86:87], v[106:107]
	v_pk_fma_f32 v[108:109], v[78:79], v[86:87], v[108:109]
	v_pk_fma_f32 v[122:123], v[74:75], v[44:45], v[122:123]
	v_pk_fma_f32 v[124:125], v[78:79], v[44:45], v[124:125]
	v_add_f32_e32 v110, v106, v107
	v_add_f32_e32 v112, v108, v109
	v_add_f32_e32 v126, v122, v123
	v_add_f32_e32 v127, v124, v125
	v_add_f32_dpp v110, v110, v110 quad_perm:[1,0,3,2] row_mask:0xf bank_mask:0xf bound_ctrl:1
	v_add_f32_dpp v112, v112, v112 quad_perm:[1,0,3,2] row_mask:0xf bank_mask:0xf bound_ctrl:1
	ds_write_b64 v187, v[126:127] offset:49152
	ds_read_b128 v[30:33], v161 offset:14848
	v_add_f32_dpp v110, v110, v110 quad_perm:[2,3,0,1] row_mask:0xf bank_mask:0xf bound_ctrl:1
	v_add_f32_dpp v112, v112, v112 quad_perm:[2,3,0,1] row_mask:0xf bank_mask:0xf bound_ctrl:1
	ds_read_b128 v[34:37], v161 offset:23040
	ds_read_b128 v[46:49], v161 offset:31232
	v_add_f32_dpp v110, v110, v110 row_half_mirror row_mask:0xf bank_mask:0xf bound_ctrl:1
	v_add_f32_dpp v112, v112, v112 row_half_mirror row_mask:0xf bank_mask:0xf bound_ctrl:1
	ds_read_b64 v[80:81], v82 offset:47616
	ds_read_b128 v[38:41], v161 offset:6656
	v_add_f32_dpp v110, v110, v110 row_ror:8 row_mask:0xf bank_mask:0xf bound_ctrl:1
	v_add_f32_dpp v112, v112, v112 row_ror:8 row_mask:0xf bank_mask:0xf bound_ctrl:1
	ds_read_b128 v[42:45], v161 offset:39424
	v_pk_mul_f32 v[114:115], v[88:89], v[110:111] op_sel_hi:[1,0]
	v_pk_mul_f32 v[116:117], v[88:89], v[112:113] op_sel_hi:[1,0]
	v_pk_mul_f32 v[118:119], v[90:91], v[110:111] op_sel_hi:[1,0]
	v_pk_mul_f32 v[120:121], v[90:91], v[112:113] op_sel_hi:[1,0]
	v_pk_fma_f32 v[114:115], v[100:101], v[104:105], v[114:115] op_sel_hi:[1,0,1]
	v_pk_fma_f32 v[116:117], v[100:101], v[104:105], v[116:117] op_sel:[0,1,0]
	v_pk_fma_f32 v[118:119], v[102:103], v[104:105], v[118:119] op_sel_hi:[1,0,1]
	v_pk_fma_f32 v[120:121], v[102:103], v[104:105], v[120:121] op_sel:[0,1,0]
	v_pk_fma_f32 v[72:73], v[72:73], v[92:93], v[114:115]
	v_pk_fma_f32 v[76:77], v[76:77], v[92:93], v[116:117]
	v_pk_fma_f32 v[74:75], v[74:75], v[94:95], v[118:119]
	v_pk_fma_f32 v[78:79], v[78:79], v[94:95], v[120:121]
	s_waitcnt lgkmcnt(0)
	v_pk_mul_f32 v[106:107], v[72:73], v[30:31]
	v_pk_mul_f32 v[108:109], v[76:77], v[30:31]
	v_pk_mul_f32 v[122:123], v[72:73], v[96:97]
	v_pk_mul_f32 v[124:125], v[76:77], v[96:97]
	v_pk_fma_f32 v[106:107], v[74:75], v[32:33], v[106:107]
	v_pk_fma_f32 v[108:109], v[78:79], v[32:33], v[108:109]
	v_pk_fma_f32 v[122:123], v[74:75], v[98:99], v[122:123]
	v_pk_fma_f32 v[124:125], v[78:79], v[98:99], v[124:125]
	v_add_f32_e32 v110, v106, v107
	v_add_f32_e32 v112, v108, v109
	v_add_f32_e32 v126, v122, v123
	v_add_f32_e32 v127, v124, v125
	v_add_f32_dpp v110, v110, v110 quad_perm:[1,0,3,2] row_mask:0xf bank_mask:0xf bound_ctrl:1
	v_add_f32_dpp v112, v112, v112 quad_perm:[1,0,3,2] row_mask:0xf bank_mask:0xf bound_ctrl:1
	ds_write_b64 v187, v[126:127] offset:51200
	ds_read_b128 v[84:87], v161 offset:15104
	v_add_f32_dpp v110, v110, v110 quad_perm:[2,3,0,1] row_mask:0xf bank_mask:0xf bound_ctrl:1
	v_add_f32_dpp v112, v112, v112 quad_perm:[2,3,0,1] row_mask:0xf bank_mask:0xf bound_ctrl:1
	ds_read_b128 v[88:91], v161 offset:23296
	ds_read_b128 v[100:103], v161 offset:31488
	v_add_f32_dpp v110, v110, v110 row_half_mirror row_mask:0xf bank_mask:0xf bound_ctrl:1
	v_add_f32_dpp v112, v112, v112 row_half_mirror row_mask:0xf bank_mask:0xf bound_ctrl:1
	ds_read_b64 v[104:105], v82 offset:47872
	ds_read_b128 v[92:95], v161 offset:6912
	v_add_f32_dpp v110, v110, v110 row_ror:8 row_mask:0xf bank_mask:0xf bound_ctrl:1
	v_add_f32_dpp v112, v112, v112 row_ror:8 row_mask:0xf bank_mask:0xf bound_ctrl:1
	ds_read_b128 v[96:99], v161 offset:39680
	v_pk_mul_f32 v[114:115], v[34:35], v[110:111] op_sel_hi:[1,0]
	v_pk_mul_f32 v[116:117], v[34:35], v[112:113] op_sel_hi:[1,0]
	v_pk_mul_f32 v[118:119], v[36:37], v[110:111] op_sel_hi:[1,0]
	v_pk_mul_f32 v[120:121], v[36:37], v[112:113] op_sel_hi:[1,0]
	v_pk_fma_f32 v[114:115], v[46:47], v[80:81], v[114:115] op_sel_hi:[1,0,1]
	v_pk_fma_f32 v[116:117], v[46:47], v[80:81], v[116:117] op_sel:[0,1,0]
	v_pk_fma_f32 v[118:119], v[48:49], v[80:81], v[118:119] op_sel_hi:[1,0,1]
	v_pk_fma_f32 v[120:121], v[48:49], v[80:81], v[120:121] op_sel:[0,1,0]
	v_pk_fma_f32 v[72:73], v[72:73], v[38:39], v[114:115]
	v_pk_fma_f32 v[76:77], v[76:77], v[38:39], v[116:117]
	v_pk_fma_f32 v[74:75], v[74:75], v[40:41], v[118:119]
	v_pk_fma_f32 v[78:79], v[78:79], v[40:41], v[120:121]
	s_waitcnt lgkmcnt(0)
	v_pk_mul_f32 v[106:107], v[72:73], v[84:85]
	v_pk_mul_f32 v[108:109], v[76:77], v[84:85]
	v_pk_mul_f32 v[122:123], v[72:73], v[42:43]
	v_pk_mul_f32 v[124:125], v[76:77], v[42:43]
	v_pk_fma_f32 v[106:107], v[74:75], v[86:87], v[106:107]
	v_pk_fma_f32 v[108:109], v[78:79], v[86:87], v[108:109]
	v_pk_fma_f32 v[122:123], v[74:75], v[44:45], v[122:123]
	v_pk_fma_f32 v[124:125], v[78:79], v[44:45], v[124:125]
	v_add_f32_e32 v110, v106, v107
	v_add_f32_e32 v112, v108, v109
	v_add_f32_e32 v126, v122, v123
	v_add_f32_e32 v127, v124, v125
	v_add_f32_dpp v110, v110, v110 quad_perm:[1,0,3,2] row_mask:0xf bank_mask:0xf bound_ctrl:1
	v_add_f32_dpp v112, v112, v112 quad_perm:[1,0,3,2] row_mask:0xf bank_mask:0xf bound_ctrl:1
	ds_write_b64 v187, v[126:127] offset:53248
	ds_read_b128 v[30:33], v161 offset:15360
	v_add_f32_dpp v110, v110, v110 quad_perm:[2,3,0,1] row_mask:0xf bank_mask:0xf bound_ctrl:1
	v_add_f32_dpp v112, v112, v112 quad_perm:[2,3,0,1] row_mask:0xf bank_mask:0xf bound_ctrl:1
	ds_read_b128 v[34:37], v161 offset:23552
	ds_read_b128 v[46:49], v161 offset:31744
	v_add_f32_dpp v110, v110, v110 row_half_mirror row_mask:0xf bank_mask:0xf bound_ctrl:1
	v_add_f32_dpp v112, v112, v112 row_half_mirror row_mask:0xf bank_mask:0xf bound_ctrl:1
	ds_read_b64 v[80:81], v82 offset:48128
	ds_read_b128 v[38:41], v161 offset:7168
	v_add_f32_dpp v110, v110, v110 row_ror:8 row_mask:0xf bank_mask:0xf bound_ctrl:1
	v_add_f32_dpp v112, v112, v112 row_ror:8 row_mask:0xf bank_mask:0xf bound_ctrl:1
	ds_read_b128 v[42:45], v161 offset:39936
	v_pk_mul_f32 v[114:115], v[88:89], v[110:111] op_sel_hi:[1,0]
	v_pk_mul_f32 v[116:117], v[88:89], v[112:113] op_sel_hi:[1,0]
	v_pk_mul_f32 v[118:119], v[90:91], v[110:111] op_sel_hi:[1,0]
	v_pk_mul_f32 v[120:121], v[90:91], v[112:113] op_sel_hi:[1,0]
	v_pk_fma_f32 v[114:115], v[100:101], v[104:105], v[114:115] op_sel_hi:[1,0,1]
	v_pk_fma_f32 v[116:117], v[100:101], v[104:105], v[116:117] op_sel:[0,1,0]
	v_pk_fma_f32 v[118:119], v[102:103], v[104:105], v[118:119] op_sel_hi:[1,0,1]
	v_pk_fma_f32 v[120:121], v[102:103], v[104:105], v[120:121] op_sel:[0,1,0]
	v_pk_fma_f32 v[72:73], v[72:73], v[92:93], v[114:115]
	v_pk_fma_f32 v[76:77], v[76:77], v[92:93], v[116:117]
	v_pk_fma_f32 v[74:75], v[74:75], v[94:95], v[118:119]
	v_pk_fma_f32 v[78:79], v[78:79], v[94:95], v[120:121]
	s_waitcnt lgkmcnt(0)
	v_pk_mul_f32 v[106:107], v[72:73], v[30:31]
	v_pk_mul_f32 v[108:109], v[76:77], v[30:31]
	v_pk_mul_f32 v[122:123], v[72:73], v[96:97]
	v_pk_mul_f32 v[124:125], v[76:77], v[96:97]
	v_pk_fma_f32 v[106:107], v[74:75], v[32:33], v[106:107]
	v_pk_fma_f32 v[108:109], v[78:79], v[32:33], v[108:109]
	v_pk_fma_f32 v[122:123], v[74:75], v[98:99], v[122:123]
	v_pk_fma_f32 v[124:125], v[78:79], v[98:99], v[124:125]
	v_add_f32_e32 v110, v106, v107
	v_add_f32_e32 v112, v108, v109
	v_add_f32_e32 v126, v122, v123
	v_add_f32_e32 v127, v124, v125
	v_add_f32_dpp v110, v110, v110 quad_perm:[1,0,3,2] row_mask:0xf bank_mask:0xf bound_ctrl:1
	v_add_f32_dpp v112, v112, v112 quad_perm:[1,0,3,2] row_mask:0xf bank_mask:0xf bound_ctrl:1
	ds_write_b64 v187, v[126:127] offset:55296
	ds_read_b128 v[84:87], v161 offset:15616
	v_add_f32_dpp v110, v110, v110 quad_perm:[2,3,0,1] row_mask:0xf bank_mask:0xf bound_ctrl:1
	v_add_f32_dpp v112, v112, v112 quad_perm:[2,3,0,1] row_mask:0xf bank_mask:0xf bound_ctrl:1
	ds_read_b128 v[88:91], v161 offset:23808
	ds_read_b128 v[100:103], v161 offset:32000
	v_add_f32_dpp v110, v110, v110 row_half_mirror row_mask:0xf bank_mask:0xf bound_ctrl:1
	v_add_f32_dpp v112, v112, v112 row_half_mirror row_mask:0xf bank_mask:0xf bound_ctrl:1
	ds_read_b64 v[104:105], v82 offset:48384
	ds_read_b128 v[92:95], v161 offset:7424
	v_add_f32_dpp v110, v110, v110 row_ror:8 row_mask:0xf bank_mask:0xf bound_ctrl:1
	v_add_f32_dpp v112, v112, v112 row_ror:8 row_mask:0xf bank_mask:0xf bound_ctrl:1
	ds_read_b128 v[96:99], v161 offset:40192
	v_pk_mul_f32 v[114:115], v[34:35], v[110:111] op_sel_hi:[1,0]
	v_pk_mul_f32 v[116:117], v[34:35], v[112:113] op_sel_hi:[1,0]
	v_pk_mul_f32 v[118:119], v[36:37], v[110:111] op_sel_hi:[1,0]
	v_pk_mul_f32 v[120:121], v[36:37], v[112:113] op_sel_hi:[1,0]
	v_pk_fma_f32 v[114:115], v[46:47], v[80:81], v[114:115] op_sel_hi:[1,0,1]
	v_pk_fma_f32 v[116:117], v[46:47], v[80:81], v[116:117] op_sel:[0,1,0]
	v_pk_fma_f32 v[118:119], v[48:49], v[80:81], v[118:119] op_sel_hi:[1,0,1]
	v_pk_fma_f32 v[120:121], v[48:49], v[80:81], v[120:121] op_sel:[0,1,0]
	v_pk_fma_f32 v[72:73], v[72:73], v[38:39], v[114:115]
	v_pk_fma_f32 v[76:77], v[76:77], v[38:39], v[116:117]
	v_pk_fma_f32 v[74:75], v[74:75], v[40:41], v[118:119]
	v_pk_fma_f32 v[78:79], v[78:79], v[40:41], v[120:121]
	s_waitcnt lgkmcnt(0)
	v_pk_mul_f32 v[106:107], v[72:73], v[84:85]
	v_pk_mul_f32 v[108:109], v[76:77], v[84:85]
	v_pk_mul_f32 v[122:123], v[72:73], v[42:43]
	v_pk_mul_f32 v[124:125], v[76:77], v[42:43]
	v_pk_fma_f32 v[106:107], v[74:75], v[86:87], v[106:107]
	v_pk_fma_f32 v[108:109], v[78:79], v[86:87], v[108:109]
	v_pk_fma_f32 v[122:123], v[74:75], v[44:45], v[122:123]
	v_pk_fma_f32 v[124:125], v[78:79], v[44:45], v[124:125]
	v_add_f32_e32 v110, v106, v107
	v_add_f32_e32 v112, v108, v109
	v_add_f32_e32 v126, v122, v123
	v_add_f32_e32 v127, v124, v125
	v_add_f32_dpp v110, v110, v110 quad_perm:[1,0,3,2] row_mask:0xf bank_mask:0xf bound_ctrl:1
	v_add_f32_dpp v112, v112, v112 quad_perm:[1,0,3,2] row_mask:0xf bank_mask:0xf bound_ctrl:1
	ds_write_b64 v187, v[126:127] offset:57344
	ds_read_b128 v[30:33], v161 offset:15872
	v_add_f32_dpp v110, v110, v110 quad_perm:[2,3,0,1] row_mask:0xf bank_mask:0xf bound_ctrl:1
	v_add_f32_dpp v112, v112, v112 quad_perm:[2,3,0,1] row_mask:0xf bank_mask:0xf bound_ctrl:1
	ds_read_b128 v[34:37], v161 offset:24064
	ds_read_b128 v[46:49], v161 offset:32256
	v_add_f32_dpp v110, v110, v110 row_half_mirror row_mask:0xf bank_mask:0xf bound_ctrl:1
	v_add_f32_dpp v112, v112, v112 row_half_mirror row_mask:0xf bank_mask:0xf bound_ctrl:1
	ds_read_b64 v[80:81], v82 offset:48640
	ds_read_b128 v[38:41], v161 offset:7680
	v_add_f32_dpp v110, v110, v110 row_ror:8 row_mask:0xf bank_mask:0xf bound_ctrl:1
	v_add_f32_dpp v112, v112, v112 row_ror:8 row_mask:0xf bank_mask:0xf bound_ctrl:1
	ds_read_b128 v[42:45], v161 offset:40448
	v_pk_mul_f32 v[114:115], v[88:89], v[110:111] op_sel_hi:[1,0]
	v_pk_mul_f32 v[116:117], v[88:89], v[112:113] op_sel_hi:[1,0]
	v_pk_mul_f32 v[118:119], v[90:91], v[110:111] op_sel_hi:[1,0]
	v_pk_mul_f32 v[120:121], v[90:91], v[112:113] op_sel_hi:[1,0]
	v_pk_fma_f32 v[114:115], v[100:101], v[104:105], v[114:115] op_sel_hi:[1,0,1]
	v_pk_fma_f32 v[116:117], v[100:101], v[104:105], v[116:117] op_sel:[0,1,0]
	v_pk_fma_f32 v[118:119], v[102:103], v[104:105], v[118:119] op_sel_hi:[1,0,1]
	v_pk_fma_f32 v[120:121], v[102:103], v[104:105], v[120:121] op_sel:[0,1,0]
	v_pk_fma_f32 v[72:73], v[72:73], v[92:93], v[114:115]
	v_pk_fma_f32 v[76:77], v[76:77], v[92:93], v[116:117]
	v_pk_fma_f32 v[74:75], v[74:75], v[94:95], v[118:119]
	v_pk_fma_f32 v[78:79], v[78:79], v[94:95], v[120:121]
	s_waitcnt lgkmcnt(0)
	v_pk_mul_f32 v[106:107], v[72:73], v[30:31]
	v_pk_mul_f32 v[108:109], v[76:77], v[30:31]
	v_pk_mul_f32 v[122:123], v[72:73], v[96:97]
	v_pk_mul_f32 v[124:125], v[76:77], v[96:97]
	v_pk_fma_f32 v[106:107], v[74:75], v[32:33], v[106:107]
	v_pk_fma_f32 v[108:109], v[78:79], v[32:33], v[108:109]
	v_pk_fma_f32 v[122:123], v[74:75], v[98:99], v[122:123]
	v_pk_fma_f32 v[124:125], v[78:79], v[98:99], v[124:125]
	v_add_f32_e32 v110, v106, v107
	v_add_f32_e32 v112, v108, v109
	v_add_f32_e32 v126, v122, v123
	v_add_f32_e32 v127, v124, v125
	v_add_f32_dpp v110, v110, v110 quad_perm:[1,0,3,2] row_mask:0xf bank_mask:0xf bound_ctrl:1
	v_add_f32_dpp v112, v112, v112 quad_perm:[1,0,3,2] row_mask:0xf bank_mask:0xf bound_ctrl:1
	ds_write_b64 v187, v[126:127] offset:59392
	ds_read_b128 v[84:87], v161 offset:16128
	v_add_f32_dpp v110, v110, v110 quad_perm:[2,3,0,1] row_mask:0xf bank_mask:0xf bound_ctrl:1
	v_add_f32_dpp v112, v112, v112 quad_perm:[2,3,0,1] row_mask:0xf bank_mask:0xf bound_ctrl:1
	ds_read_b128 v[88:91], v161 offset:24320
	ds_read_b128 v[100:103], v161 offset:32512
	v_add_f32_dpp v110, v110, v110 row_half_mirror row_mask:0xf bank_mask:0xf bound_ctrl:1
	v_add_f32_dpp v112, v112, v112 row_half_mirror row_mask:0xf bank_mask:0xf bound_ctrl:1
	ds_read_b64 v[104:105], v82 offset:48896
	ds_read_b128 v[92:95], v161 offset:7936
	v_add_f32_dpp v110, v110, v110 row_ror:8 row_mask:0xf bank_mask:0xf bound_ctrl:1
	v_add_f32_dpp v112, v112, v112 row_ror:8 row_mask:0xf bank_mask:0xf bound_ctrl:1
	ds_read_b128 v[96:99], v161 offset:40704
	v_pk_mul_f32 v[114:115], v[34:35], v[110:111] op_sel_hi:[1,0]
	v_pk_mul_f32 v[116:117], v[34:35], v[112:113] op_sel_hi:[1,0]
	v_pk_mul_f32 v[118:119], v[36:37], v[110:111] op_sel_hi:[1,0]
	v_pk_mul_f32 v[120:121], v[36:37], v[112:113] op_sel_hi:[1,0]
	v_pk_fma_f32 v[114:115], v[46:47], v[80:81], v[114:115] op_sel_hi:[1,0,1]
	v_pk_fma_f32 v[116:117], v[46:47], v[80:81], v[116:117] op_sel:[0,1,0]
	v_pk_fma_f32 v[118:119], v[48:49], v[80:81], v[118:119] op_sel_hi:[1,0,1]
	v_pk_fma_f32 v[120:121], v[48:49], v[80:81], v[120:121] op_sel:[0,1,0]
	v_pk_fma_f32 v[72:73], v[72:73], v[38:39], v[114:115]
	v_pk_fma_f32 v[76:77], v[76:77], v[38:39], v[116:117]
	v_pk_fma_f32 v[74:75], v[74:75], v[40:41], v[118:119]
	v_pk_fma_f32 v[78:79], v[78:79], v[40:41], v[120:121]
	s_waitcnt lgkmcnt(0)
	v_pk_mul_f32 v[106:107], v[72:73], v[84:85]
	v_pk_mul_f32 v[108:109], v[76:77], v[84:85]
	v_pk_mul_f32 v[122:123], v[72:73], v[42:43]
	v_pk_mul_f32 v[124:125], v[76:77], v[42:43]
	v_pk_fma_f32 v[106:107], v[74:75], v[86:87], v[106:107]
	v_pk_fma_f32 v[108:109], v[78:79], v[86:87], v[108:109]
	v_pk_fma_f32 v[122:123], v[74:75], v[44:45], v[122:123]
	v_pk_fma_f32 v[124:125], v[78:79], v[44:45], v[124:125]
	v_add_f32_e32 v110, v106, v107
	v_add_f32_e32 v112, v108, v109
	v_add_f32_e32 v126, v122, v123
	v_add_f32_e32 v127, v124, v125
	v_add_f32_dpp v110, v110, v110 quad_perm:[1,0,3,2] row_mask:0xf bank_mask:0xf bound_ctrl:1
	v_add_f32_dpp v112, v112, v112 quad_perm:[1,0,3,2] row_mask:0xf bank_mask:0xf bound_ctrl:1
	ds_write_b64 v187, v[126:127] offset:61440
	v_add_f32_dpp v110, v110, v110 quad_perm:[2,3,0,1] row_mask:0xf bank_mask:0xf bound_ctrl:1
	v_add_f32_dpp v112, v112, v112 quad_perm:[2,3,0,1] row_mask:0xf bank_mask:0xf bound_ctrl:1
	s_nop 0
	v_add_f32_dpp v110, v110, v110 row_half_mirror row_mask:0xf bank_mask:0xf bound_ctrl:1
	v_add_f32_dpp v112, v112, v112 row_half_mirror row_mask:0xf bank_mask:0xf bound_ctrl:1
	s_nop 0
	v_add_f32_dpp v110, v110, v110 row_ror:8 row_mask:0xf bank_mask:0xf bound_ctrl:1
	v_add_f32_dpp v112, v112, v112 row_ror:8 row_mask:0xf bank_mask:0xf bound_ctrl:1
	v_pk_mul_f32 v[114:115], v[88:89], v[110:111] op_sel_hi:[1,0]
	v_pk_mul_f32 v[116:117], v[88:89], v[112:113] op_sel_hi:[1,0]
	v_pk_mul_f32 v[118:119], v[90:91], v[110:111] op_sel_hi:[1,0]
	v_pk_mul_f32 v[120:121], v[90:91], v[112:113] op_sel_hi:[1,0]
	v_pk_fma_f32 v[114:115], v[100:101], v[104:105], v[114:115] op_sel_hi:[1,0,1]
	v_pk_fma_f32 v[116:117], v[100:101], v[104:105], v[116:117] op_sel:[0,1,0]
	v_pk_fma_f32 v[118:119], v[102:103], v[104:105], v[118:119] op_sel_hi:[1,0,1]
	v_pk_fma_f32 v[120:121], v[102:103], v[104:105], v[120:121] op_sel:[0,1,0]
	v_pk_fma_f32 v[72:73], v[72:73], v[92:93], v[114:115]
	v_pk_fma_f32 v[76:77], v[76:77], v[92:93], v[116:117]
	v_pk_fma_f32 v[74:75], v[74:75], v[94:95], v[118:119]
	v_pk_fma_f32 v[78:79], v[78:79], v[94:95], v[120:121]
	v_pk_mul_f32 v[122:123], v[72:73], v[96:97]
	v_pk_mul_f32 v[124:125], v[76:77], v[96:97]
	v_pk_fma_f32 v[122:123], v[74:75], v[98:99], v[122:123]
	v_pk_fma_f32 v[124:125], v[78:79], v[98:99], v[124:125]
	v_add_f32_e32 v126, v122, v123
	v_add_f32_e32 v127, v124, v125
	ds_write_b64 v187, v[126:127] offset:63488
